# v30 plus duplicated s_waitcnt lgkmcnt(0) removed after the asm wait in each MFMA phase of the GEMM K-loops (90 sites)
# speedup vs baseline: 1.0094x; 1.0027x over previous
; #define PG8_STAGE(bufoff, gbase, voff) do { _Pragma("unroll") for (int _i = 0; _i < 2; ++_i) \
;         __builtin_amdgcn_global_load_lds((const unsigned*)((const char*)(gbase) + (voff)[_i]), (LAS unsigned*)(lds + (bufoff) + ldsw + _i * 8192), 16, 0, 0); } while (0)
; #define PG8_LDA(dst, b, h) do { _Pragma("unroll") for (int m = 0; m < 4; ++m) _Pragma("unroll") for (int k = 0; k < 2; ++k) dst[m][k] = *(const LAS bf16x8*)(lds + PG8_SA(b, h) + aoff + m * 2048 + k * 1024); } while (0)
; #define PG8_LDB(dst, b, h) do { _Pragma("unroll") for (int n = 0; n < 2; ++n) _Pragma("unroll") for (int k = 0; k < 2; ++k) dst[n][k] = *(const LAS bf16x8*)(lds + PG8_SB(b, h) + boff + n * 2048 + k * 1024); } while (0)
; #define PG8_MMA(ai, bj, At, Bt) do { __builtin_amdgcn_s_setprio(1); _Pragma("unroll") for (int m = 0; m < 4; ++m) _Pragma("unroll") for (int n = 0; n < 2; ++n) _Pragma("unroll") for (int k = 0; k < 2; ++k) \
;         acc[ai][bj][m][n] = __builtin_amdgcn_mfma_f32_16x16x32_bf16(Bt[n][k], At[m][k], acc[ai][bj][m][n], 0, 0, 0); __builtin_amdgcn_s_setprio(0); } while (0)
; #define PG8_WAIT_L(n) asm volatile("s_waitcnt lgkmcnt(" #n ")" ::: "memory")
; #define PG8_BAR __builtin_amdgcn_s_barrier()
; #define PG8_SCHED __builtin_amdgcn_sched_barrier(0)
; template <class Epi>
; DEVI void gemm_phase(LAS unsigned char* lds, const bf16_t* gA, const bf16_t* gBt, const int lda, const int ldb, const int K, const StaticOrder S_, const Epi E) {
;     ...
;             const bool last = (t == nt - 2);
;             const char* a1 = cA + (size_t)(t + 1) * kstep;
;             const char* a2 = last ? nA : cA + (size_t)(t + 2) * kstep; const char* b2 = last ? nB : cB + (size_t)(t + 2) * kstep;
;             const char* a3 = a2 + kstep; const char* b3 = b2 + kstep;
;             PG8_LDB(B0, 0, 0); PG8_SCHED; PG8_LDA(At, 0, 0); PG8_STAGE(PG8_SA(1, 1), a1 + hstepA, voffA);
;             PG8_WAIT_L(8); PG8_BAR; PG8_WAIT_L(0); PG8_MMA(0, 0, At, B0); PG8_BAR; PG8_SCHED;
;             PG8_LDB(B1, 0, 1); PG8_STAGE(PG8_SB(0, 0), b2, voffB);
;             PG8_BAR; PG8_WAIT_L(0); PG8_MMA(0, 1, At, B1); PG8_BAR;
;             PG8_LDA(At, 0, 1); PG8_STAGE(PG8_SA(0, 0), a2, voffA);
;             PG8_BAR; PG8_WAIT_L(0); PG8_MMA(1, 0, At, B0); PG8_BAR; PG8_SCHED;
.LBB0_259:
	ds_read_b128 v[158:161], v151
	ds_read_b128 v[162:165], v151 offset:1024
	ds_read_b128 v[166:169], v151 offset:2048
	ds_read_b128 v[170:173], v151 offset:3072
	s_add_i32 s79, s26, 2
	s_add_u32 s28, s24, 0x80
	s_addc_u32 s27, s25, 0
	s_cmp_eq_u32 s96, s26
	s_cselect_b32 s26, s4, s28
	s_cselect_b32 s27, s5, s27
	s_cselect_b32 s29, s23, s78
	s_cselect_b32 s28, s22, s77
	v_lshl_add_u64 v[144:145], s[24:25], 0, v[138:139]
	s_add_i32 m0, s37, 0xc000
	ds_read_b128 v[174:177], v152
	ds_read_b128 v[178:181], v152 offset:1024
	ds_read_b128 v[182:185], v152 offset:2048
	ds_read_b128 v[186:189], v152 offset:3072
	ds_read_b128 v[190:193], v152 offset:4096
	ds_read_b128 v[198:201], v152 offset:5120
	ds_read_b128 v[202:205], v152 offset:6144
	ds_read_b128 v[206:209], v152 offset:7168
	global_load_lds_dwordx4 v[144:145], off
	v_lshl_add_u64 v[144:145], s[24:25], 0, v[140:141]
	s_add_i32 m0, s37, 0xe000
	s_nop 0
	global_load_lds_dwordx4 v[144:145], off
	s_waitcnt lgkmcnt(8)
	s_barrier
	s_waitcnt lgkmcnt(0)
	v_mfma_f32_16x16x32_bf16 v[120:123], v[158:161], v[174:177], v[120:123]
	v_mfma_f32_16x16x32_bf16 v[116:119], v[166:169], v[174:177], v[116:119]
	v_mfma_f32_16x16x32_bf16 v[108:111], v[158:161], v[182:185], v[108:111]
	v_mfma_f32_16x16x32_bf16 v[100:103], v[166:169], v[182:185], v[100:103]
	v_mfma_f32_16x16x32_bf16 v[92:95], v[158:161], v[190:193], v[92:95]
	v_mfma_f32_16x16x32_bf16 v[84:87], v[166:169], v[190:193], v[84:87]
	v_mfma_f32_16x16x32_bf16 v[76:79], v[158:161], v[202:205], v[76:79]
	v_mfma_f32_16x16x32_bf16 v[68:71], v[166:169], v[202:205], v[68:71]
	v_mfma_f32_16x16x32_bf16 v[120:123], v[162:165], v[178:181], v[120:123]
	v_mfma_f32_16x16x32_bf16 v[116:119], v[170:173], v[178:181], v[116:119]
	v_mfma_f32_16x16x32_bf16 v[108:111], v[162:165], v[186:189], v[108:111]
	v_mfma_f32_16x16x32_bf16 v[100:103], v[170:173], v[186:189], v[100:103]
	v_mfma_f32_16x16x32_bf16 v[92:95], v[162:165], v[198:201], v[92:95]
	v_mfma_f32_16x16x32_bf16 v[84:87], v[170:173], v[198:201], v[84:87]
	v_mfma_f32_16x16x32_bf16 v[76:79], v[162:165], v[206:209], v[76:79]
	v_mfma_f32_16x16x32_bf16 v[68:71], v[170:173], v[206:209], v[68:71]
	s_barrier
	s_add_i32 vcc_lo, s41, s36
	v_lshl_add_u64 v[144:145], s[28:29], 0, v[130:131]
	s_mov_b32 m0, vcc_lo
	ds_read_b128 v[210:213], v153
	ds_read_b128 v[214:217], v153 offset:1024
	ds_read_b128 v[218:221], v153 offset:2048
	ds_read_b128 v[222:225], v153 offset:3072
	global_load_lds_dwordx4 v[144:145], off
	v_lshl_add_u64 v[194:195], s[28:29], 0, v[134:135]
	s_add_i32 m0, vcc_lo, 0x2000
	s_nop 0
	global_load_lds_dwordx4 v[194:195], off
	s_barrier
	s_waitcnt lgkmcnt(0)
	v_mfma_f32_16x16x32_bf16 v[124:127], v[210:213], v[174:177], v[124:127]
	v_mfma_f32_16x16x32_bf16 v[112:115], v[218:221], v[174:177], v[112:115]
	v_mfma_f32_16x16x32_bf16 v[104:107], v[210:213], v[182:185], v[104:107]
	v_mfma_f32_16x16x32_bf16 v[96:99], v[218:221], v[182:185], v[96:99]
	v_mfma_f32_16x16x32_bf16 v[88:91], v[210:213], v[190:193], v[88:91]
	v_mfma_f32_16x16x32_bf16 v[80:83], v[218:221], v[190:193], v[80:83]
	v_mfma_f32_16x16x32_bf16 v[72:75], v[210:213], v[202:205], v[72:75]
	v_mfma_f32_16x16x32_bf16 v[64:67], v[218:221], v[202:205], v[64:67]
	v_mfma_f32_16x16x32_bf16 v[124:127], v[214:217], v[178:181], v[124:127]
	v_mfma_f32_16x16x32_bf16 v[112:115], v[222:225], v[178:181], v[112:115]
	v_mfma_f32_16x16x32_bf16 v[104:107], v[214:217], v[186:189], v[104:107]
	v_mfma_f32_16x16x32_bf16 v[96:99], v[222:225], v[186:189], v[96:99]
	v_mfma_f32_16x16x32_bf16 v[88:91], v[214:217], v[198:201], v[88:91]
	v_mfma_f32_16x16x32_bf16 v[80:83], v[222:225], v[198:201], v[80:83]
	v_mfma_f32_16x16x32_bf16 v[72:75], v[214:217], v[206:209], v[72:75]
	v_mfma_f32_16x16x32_bf16 v[64:67], v[222:225], v[206:209], v[64:67]
	s_mov_b32 m0, s37
	v_lshl_add_u64 v[226:227], s[26:27], 0, v[128:129]
	s_barrier
	ds_read_b128 v[174:177], v152 offset:16384
	ds_read_b128 v[178:181], v152 offset:17408
	ds_read_b128 v[182:185], v152 offset:18432
	ds_read_b128 v[186:189], v152 offset:19456
	ds_read_b128 v[190:193], v152 offset:20480
	ds_read_b128 v[198:201], v152 offset:21504
	ds_read_b128 v[202:205], v152 offset:22528
	ds_read_b128 v[206:209], v152 offset:23552
	global_load_lds_dwordx4 v[226:227], off
	v_lshl_add_u64 v[228:229], s[26:27], 0, v[132:133]
	s_mov_b32 m0, s48
	s_nop 0
	global_load_lds_dwordx4 v[228:229], off
	s_barrier
	s_waitcnt lgkmcnt(0)
	v_mfma_f32_16x16x32_bf16 v[60:63], v[158:161], v[174:177], v[60:63]
	v_mfma_f32_16x16x32_bf16 v[56:59], v[166:169], v[174:177], v[56:59]
	v_mfma_f32_16x16x32_bf16 v[44:47], v[158:161], v[182:185], v[44:47]
	v_mfma_f32_16x16x32_bf16 v[40:43], v[166:169], v[182:185], v[40:43]
	v_mfma_f32_16x16x32_bf16 v[28:31], v[158:161], v[190:193], v[28:31]
	v_mfma_f32_16x16x32_bf16 v[24:27], v[166:169], v[190:193], v[24:27]
	v_mfma_f32_16x16x32_bf16 v[12:15], v[158:161], v[202:205], v[12:15]
	v_mfma_f32_16x16x32_bf16 v[8:11], v[166:169], v[202:205], v[8:11]
	v_mfma_f32_16x16x32_bf16 v[60:63], v[162:165], v[178:181], v[60:63]
	v_mfma_f32_16x16x32_bf16 v[56:59], v[170:173], v[178:181], v[56:59]
	v_mfma_f32_16x16x32_bf16 v[44:47], v[162:165], v[186:189], v[44:47]
	v_mfma_f32_16x16x32_bf16 v[40:43], v[170:173], v[186:189], v[40:43]
	v_mfma_f32_16x16x32_bf16 v[28:31], v[162:165], v[198:201], v[28:31]
	v_mfma_f32_16x16x32_bf16 v[24:27], v[170:173], v[198:201], v[24:27]
	v_mfma_f32_16x16x32_bf16 v[12:15], v[162:165], v[206:209], v[12:15]
	v_mfma_f32_16x16x32_bf16 v[8:11], v[170:173], v[206:209], v[8:11]
	s_barrier
; #define PG8_STAGE(bufoff, gbase, voff) do { _Pragma("unroll") for (int _i = 0; _i < 2; ++_i) \
;         __builtin_amdgcn_global_load_lds((const unsigned*)((const char*)(gbase) + (voff)[_i]), (LAS unsigned*)(lds + (bufoff) + ldsw + _i * 8192), 16, 0, 0); } while (0)
; #define PG8_LDA(dst, b, h) do { _Pragma("unroll") for (int m = 0; m < 4; ++m) _Pragma("unroll") for (int k = 0; k < 2; ++k) dst[m][k] = *(const LAS bf16x8*)(lds + PG8_SA(b, h) + aoff + m * 2048 + k * 1024); } while (0)
; #define PG8_LDB(dst, b, h) do { _Pragma("unroll") for (int n = 0; n < 2; ++n) _Pragma("unroll") for (int k = 0; k < 2; ++k) dst[n][k] = *(const LAS bf16x8*)(lds + PG8_SB(b, h) + boff + n * 2048 + k * 1024); } while (0)
; #define PG8_MMA(ai, bj, At, Bt) do { __builtin_amdgcn_s_setprio(1); _Pragma("unroll") for (int m = 0; m < 4; ++m) _Pragma("unroll") for (int n = 0; n < 2; ++n) _Pragma("unroll") for (int k = 0; k < 2; ++k) \
;         acc[ai][bj][m][n] = __builtin_amdgcn_mfma_f32_16x16x32_bf16(Bt[n][k], At[m][k], acc[ai][bj][m][n], 0, 0, 0); __builtin_amdgcn_s_setprio(0); } while (0)
; #define PG8_WAIT_V(n) asm volatile("s_waitcnt vmcnt(" #n ")" ::: "memory")
; #define PG8_WAIT_L(n) asm volatile("s_waitcnt lgkmcnt(" #n ")" ::: "memory")
; #define PG8_BAR __builtin_amdgcn_s_barrier()
; #define PG8_SCHED __builtin_amdgcn_sched_barrier(0)
; template <class Epi>
; DEVI void gemm_phase(LAS unsigned char* lds, const bf16_t* gA, const bf16_t* gBt, const int lda, const int ldb, const int K, const StaticOrder S_, const Epi E) {
;     ...
;             PG8_STAGE(PG8_SB(0, 1), b2 + hstepB, voffB);
;             PG8_WAIT_V(6); PG8_BAR; PG8_MMA(1, 1, At, B1); PG8_BAR;
;             PG8_LDB(B0, 1, 0); PG8_SCHED; PG8_LDA(At, 1, 0); PG8_STAGE(PG8_SA(0, 1), a2 + hstepA, voffA);
;             PG8_WAIT_L(8); PG8_BAR; PG8_WAIT_L(0); PG8_MMA(0, 0, At, B0); PG8_BAR; PG8_SCHED;
;             PG8_LDB(B1, 1, 1); PG8_STAGE(PG8_SB(1, 0), b3, voffB);
	s_add_u32 s28, s28, s8
	s_addc_u32 s29, s29, s9
	s_add_i32 vcc_lo, s0, s36
	v_lshl_add_u64 v[230:231], s[28:29], 0, v[130:131]
	s_mov_b32 m0, vcc_lo
	v_lshl_add_u64 v[232:233], s[28:29], 0, v[134:135]
	global_load_lds_dwordx4 v[230:231], off
	s_add_i32 m0, vcc_lo, 0x2000
	s_nop 0
	global_load_lds_dwordx4 v[232:233], off
	s_waitcnt vmcnt(6)
	s_barrier
	v_mfma_f32_16x16x32_bf16 v[52:55], v[210:213], v[174:177], v[52:55]
	v_mfma_f32_16x16x32_bf16 v[48:51], v[218:221], v[174:177], v[48:51]
	v_mfma_f32_16x16x32_bf16 v[36:39], v[210:213], v[182:185], v[36:39]
	v_mfma_f32_16x16x32_bf16 v[32:35], v[218:221], v[182:185], v[32:35]
	v_mfma_f32_16x16x32_bf16 v[20:23], v[210:213], v[190:193], v[20:23]
	v_mfma_f32_16x16x32_bf16 v[16:19], v[218:221], v[190:193], v[16:19]
	v_mfma_f32_16x16x32_bf16 v[4:7], v[210:213], v[202:205], v[4:7]
	v_mfma_f32_16x16x32_bf16 v[0:3], v[218:221], v[202:205], v[0:3]
	v_mfma_f32_16x16x32_bf16 v[52:55], v[214:217], v[178:181], v[52:55]
	v_mfma_f32_16x16x32_bf16 v[48:51], v[222:225], v[178:181], v[48:51]
	v_mfma_f32_16x16x32_bf16 v[36:39], v[214:217], v[186:189], v[36:39]
	v_mfma_f32_16x16x32_bf16 v[32:35], v[222:225], v[186:189], v[32:35]
	v_mfma_f32_16x16x32_bf16 v[20:23], v[214:217], v[198:201], v[20:23]
	v_mfma_f32_16x16x32_bf16 v[16:19], v[222:225], v[198:201], v[16:19]
	v_mfma_f32_16x16x32_bf16 v[4:7], v[214:217], v[206:209], v[4:7]
	v_mfma_f32_16x16x32_bf16 v[0:3], v[222:225], v[206:209], v[0:3]
	s_barrier
	ds_read_b128 v[158:161], v154
	ds_read_b128 v[162:165], v154 offset:1024
	ds_read_b128 v[166:169], v154 offset:2048
	ds_read_b128 v[170:173], v154 offset:3072
	s_add_u32 s26, s26, s2
	s_addc_u32 s27, s27, s3
	s_mov_b32 m0, s49
	v_lshl_add_u64 v[210:211], s[26:27], 0, v[128:129]
	ds_read_b128 v[174:177], v152 offset:32768
	ds_read_b128 v[178:181], v152 offset:33792
	ds_read_b128 v[182:185], v152 offset:34816
	ds_read_b128 v[186:189], v152 offset:35840
	ds_read_b128 v[190:193], v152 offset:36864
	ds_read_b128 v[198:201], v152 offset:37888
	ds_read_b128 v[202:205], v152 offset:38912
	ds_read_b128 v[206:209], v152 offset:39936
	global_load_lds_dwordx4 v[210:211], off
	v_lshl_add_u64 v[210:211], s[26:27], 0, v[132:133]
	s_mov_b32 m0, s51
	s_nop 0
	global_load_lds_dwordx4 v[210:211], off
	s_waitcnt lgkmcnt(8)
	s_barrier
	s_waitcnt lgkmcnt(0)
	v_mfma_f32_16x16x32_bf16 v[120:123], v[158:161], v[174:177], v[120:123]
	v_mfma_f32_16x16x32_bf16 v[116:119], v[166:169], v[174:177], v[116:119]
	v_mfma_f32_16x16x32_bf16 v[108:111], v[158:161], v[182:185], v[108:111]
	v_mfma_f32_16x16x32_bf16 v[100:103], v[166:169], v[182:185], v[100:103]
	v_mfma_f32_16x16x32_bf16 v[92:95], v[158:161], v[190:193], v[92:95]
	v_mfma_f32_16x16x32_bf16 v[84:87], v[166:169], v[190:193], v[84:87]
	v_mfma_f32_16x16x32_bf16 v[76:79], v[158:161], v[202:205], v[76:79]
	v_mfma_f32_16x16x32_bf16 v[68:71], v[166:169], v[202:205], v[68:71]
	v_mfma_f32_16x16x32_bf16 v[120:123], v[162:165], v[178:181], v[120:123]
	v_mfma_f32_16x16x32_bf16 v[116:119], v[170:173], v[178:181], v[116:119]
	v_mfma_f32_16x16x32_bf16 v[108:111], v[162:165], v[186:189], v[108:111]
	v_mfma_f32_16x16x32_bf16 v[100:103], v[170:173], v[186:189], v[100:103]
	v_mfma_f32_16x16x32_bf16 v[92:95], v[162:165], v[198:201], v[92:95]
	v_mfma_f32_16x16x32_bf16 v[84:87], v[170:173], v[198:201], v[84:87]
	v_mfma_f32_16x16x32_bf16 v[76:79], v[162:165], v[206:209], v[76:79]
	v_mfma_f32_16x16x32_bf16 v[68:71], v[170:173], v[206:209], v[68:71]
	s_barrier
	s_add_i32 s26, s1, s36
	v_lshl_add_u64 v[144:145], v[144:145], 0, s[20:21]
	s_mov_b32 m0, s26
	ds_read_b128 v[210:213], v155
	ds_read_b128 v[214:217], v155 offset:1024
	ds_read_b128 v[218:221], v155 offset:2048
	ds_read_b128 v[222:225], v155 offset:3072
	global_load_lds_dwordx4 v[144:145], off
	v_lshl_add_u64 v[144:145], v[194:195], 0, s[20:21]
	s_add_i32 m0, s26, 0x2000
	s_nop 0
	global_load_lds_dwordx4 v[144:145], off
	s_barrier
; #define PG8_STAGE(bufoff, gbase, voff) do { _Pragma("unroll") for (int _i = 0; _i < 2; ++_i) \
;         __builtin_amdgcn_global_load_lds((const unsigned*)((const char*)(gbase) + (voff)[_i]), (LAS unsigned*)(lds + (bufoff) + ldsw + _i * 8192), 16, 0, 0); } while (0)
; #define PG8_LDA(dst, b, h) do { _Pragma("unroll") for (int m = 0; m < 4; ++m) _Pragma("unroll") for (int k = 0; k < 2; ++k) dst[m][k] = *(const LAS bf16x8*)(lds + PG8_SA(b, h) + aoff + m * 2048 + k * 1024); } while (0)
; #define PG8_MMA(ai, bj, At, Bt) do { __builtin_amdgcn_s_setprio(1); _Pragma("unroll") for (int m = 0; m < 4; ++m) _Pragma("unroll") for (int n = 0; n < 2; ++n) _Pragma("unroll") for (int k = 0; k < 2; ++k) \
;         acc[ai][bj][m][n] = __builtin_amdgcn_mfma_f32_16x16x32_bf16(Bt[n][k], At[m][k], acc[ai][bj][m][n], 0, 0, 0); __builtin_amdgcn_s_setprio(0); } while (0)
; #define PG8_WAIT_V(n) asm volatile("s_waitcnt vmcnt(" #n ")" ::: "memory")
; #define PG8_WAIT_L(n) asm volatile("s_waitcnt lgkmcnt(" #n ")" ::: "memory")
; #define PG8_BAR __builtin_amdgcn_s_barrier()
; #define PG8_SCHED __builtin_amdgcn_sched_barrier(0)
; template <class Epi>
; DEVI void gemm_phase(LAS unsigned char* lds, const bf16_t* gA, const bf16_t* gBt, const int lda, const int ldb, const int K, const StaticOrder S_, const Epi E) {
;     ...
;             PG8_BAR; PG8_WAIT_L(0); PG8_MMA(0, 1, At, B1); PG8_BAR;
;             PG8_LDA(At, 1, 1); PG8_STAGE(PG8_SA(1, 0), a3, voffA);
;             PG8_BAR; PG8_WAIT_L(0); PG8_MMA(1, 0, At, B0); PG8_BAR; PG8_SCHED;
;             PG8_STAGE(PG8_SB(1, 1), b3 + hstepB, voffB);
;             PG8_WAIT_V(6); PG8_BAR; PG8_MMA(1, 1, At, B1); PG8_BAR;
	s_waitcnt lgkmcnt(0)
	v_mfma_f32_16x16x32_bf16 v[124:127], v[210:213], v[174:177], v[124:127]
	v_mfma_f32_16x16x32_bf16 v[112:115], v[218:221], v[174:177], v[112:115]
	v_mfma_f32_16x16x32_bf16 v[104:107], v[210:213], v[182:185], v[104:107]
	v_mfma_f32_16x16x32_bf16 v[96:99], v[218:221], v[182:185], v[96:99]
	v_mfma_f32_16x16x32_bf16 v[88:91], v[210:213], v[190:193], v[88:91]
	v_mfma_f32_16x16x32_bf16 v[80:83], v[218:221], v[190:193], v[80:83]
	v_mfma_f32_16x16x32_bf16 v[72:75], v[210:213], v[202:205], v[72:75]
	v_mfma_f32_16x16x32_bf16 v[64:67], v[218:221], v[202:205], v[64:67]
	v_mfma_f32_16x16x32_bf16 v[124:127], v[214:217], v[178:181], v[124:127]
	v_mfma_f32_16x16x32_bf16 v[112:115], v[222:225], v[178:181], v[112:115]
	v_mfma_f32_16x16x32_bf16 v[104:107], v[214:217], v[186:189], v[104:107]
	v_mfma_f32_16x16x32_bf16 v[96:99], v[222:225], v[186:189], v[96:99]
	v_mfma_f32_16x16x32_bf16 v[88:91], v[214:217], v[198:201], v[88:91]
	v_mfma_f32_16x16x32_bf16 v[80:83], v[222:225], v[198:201], v[80:83]
	v_mfma_f32_16x16x32_bf16 v[72:75], v[214:217], v[206:209], v[72:75]
	v_mfma_f32_16x16x32_bf16 v[64:67], v[222:225], v[206:209], v[64:67]
	s_mov_b32 m0, s50
	v_lshl_add_u64 v[144:145], v[226:227], 0, s[20:21]
	s_barrier
	ds_read_b128 v[174:177], v152 offset:49152
	ds_read_b128 v[178:181], v152 offset:50176
	ds_read_b128 v[182:185], v152 offset:51200
	ds_read_b128 v[186:189], v152 offset:52224
	ds_read_b128 v[190:193], v152 offset:53248
	ds_read_b128 v[198:201], v152 offset:54272
	ds_read_b128 v[202:205], v152 offset:55296
	ds_read_b128 v[206:209], v152 offset:56320
	global_load_lds_dwordx4 v[144:145], off
	v_lshl_add_u64 v[144:145], v[228:229], 0, s[20:21]
	s_mov_b32 m0, s60
	s_nop 0
	global_load_lds_dwordx4 v[144:145], off
	s_barrier
	s_waitcnt lgkmcnt(0)
	v_mfma_f32_16x16x32_bf16 v[60:63], v[158:161], v[174:177], v[60:63]
	v_mfma_f32_16x16x32_bf16 v[56:59], v[166:169], v[174:177], v[56:59]
	v_mfma_f32_16x16x32_bf16 v[44:47], v[158:161], v[182:185], v[44:47]
	v_mfma_f32_16x16x32_bf16 v[40:43], v[166:169], v[182:185], v[40:43]
	v_mfma_f32_16x16x32_bf16 v[28:31], v[158:161], v[190:193], v[28:31]
	v_mfma_f32_16x16x32_bf16 v[24:27], v[166:169], v[190:193], v[24:27]
	v_mfma_f32_16x16x32_bf16 v[12:15], v[158:161], v[202:205], v[12:15]
	v_mfma_f32_16x16x32_bf16 v[8:11], v[166:169], v[202:205], v[8:11]
	v_mfma_f32_16x16x32_bf16 v[60:63], v[162:165], v[178:181], v[60:63]
	v_mfma_f32_16x16x32_bf16 v[56:59], v[170:173], v[178:181], v[56:59]
	v_mfma_f32_16x16x32_bf16 v[44:47], v[162:165], v[186:189], v[44:47]
	v_mfma_f32_16x16x32_bf16 v[40:43], v[170:173], v[186:189], v[40:43]
	v_mfma_f32_16x16x32_bf16 v[28:31], v[162:165], v[198:201], v[28:31]
	v_mfma_f32_16x16x32_bf16 v[24:27], v[170:173], v[198:201], v[24:27]
	v_mfma_f32_16x16x32_bf16 v[12:15], v[162:165], v[206:209], v[12:15]
	v_mfma_f32_16x16x32_bf16 v[8:11], v[170:173], v[206:209], v[8:11]
	s_barrier
	s_add_i32 s26, s31, s36
	v_lshl_add_u64 v[144:145], v[230:231], 0, s[20:21]
	s_mov_b32 m0, s26
	s_nop 0
	global_load_lds_dwordx4 v[144:145], off
	v_lshl_add_u64 v[144:145], v[232:233], 0, s[20:21]
	s_add_i32 m0, s26, 0x2000
	s_nop 0
	global_load_lds_dwordx4 v[144:145], off
	s_waitcnt vmcnt(6)
	s_barrier
	v_mfma_f32_16x16x32_bf16 v[52:55], v[210:213], v[174:177], v[52:55]
	v_mfma_f32_16x16x32_bf16 v[48:51], v[218:221], v[174:177], v[48:51]
	v_mfma_f32_16x16x32_bf16 v[36:39], v[210:213], v[182:185], v[36:39]
	v_mfma_f32_16x16x32_bf16 v[32:35], v[218:221], v[182:185], v[32:35]
	v_mfma_f32_16x16x32_bf16 v[20:23], v[210:213], v[190:193], v[20:23]
	v_mfma_f32_16x16x32_bf16 v[16:19], v[218:221], v[190:193], v[16:19]
	v_mfma_f32_16x16x32_bf16 v[4:7], v[210:213], v[202:205], v[4:7]
	v_mfma_f32_16x16x32_bf16 v[0:3], v[218:221], v[202:205], v[0:3]
	v_mfma_f32_16x16x32_bf16 v[52:55], v[214:217], v[178:181], v[52:55]
	v_mfma_f32_16x16x32_bf16 v[48:51], v[222:225], v[178:181], v[48:51]
	v_mfma_f32_16x16x32_bf16 v[36:39], v[214:217], v[186:189], v[36:39]
	v_mfma_f32_16x16x32_bf16 v[32:35], v[222:225], v[186:189], v[32:35]
	v_mfma_f32_16x16x32_bf16 v[20:23], v[214:217], v[198:201], v[20:23]
	v_mfma_f32_16x16x32_bf16 v[16:19], v[222:225], v[198:201], v[16:19]
	v_mfma_f32_16x16x32_bf16 v[4:7], v[214:217], v[206:209], v[4:7]
	v_mfma_f32_16x16x32_bf16 v[0:3], v[222:225], v[206:209], v[0:3]
	s_add_u32 s24, s24, 0x100
	s_addc_u32 s25, s25, 0
	s_add_u32 s77, s77, 0x100
	s_addc_u32 s78, s78, 0
	s_cmp_ge_i32 s79, s61
	s_mov_b32 s26, s79
	s_barrier
	s_cbranch_scc0 .LBB0_259

; #define PG8_STAGE(bufoff, gbase, voff) do { _Pragma("unroll") for (int _i = 0; _i < 2; ++_i) \
;         __builtin_amdgcn_global_load_lds((const unsigned*)((const char*)(gbase) + (voff)[_i]), (LAS unsigned*)(lds + (bufoff) + ldsw + _i * 8192), 16, 0, 0); } while (0)
; #define PG8_LDA(dst, b, h) do { _Pragma("unroll") for (int m = 0; m < 4; ++m) _Pragma("unroll") for (int k = 0; k < 2; ++k) dst[m][k] = *(const LAS bf16x8*)(lds + PG8_SA(b, h) + aoff + m * 2048 + k * 1024); } while (0)
; #define PG8_LDB(dst, b, h) do { _Pragma("unroll") for (int n = 0; n < 2; ++n) _Pragma("unroll") for (int k = 0; k < 2; ++k) dst[n][k] = *(const LAS bf16x8*)(lds + PG8_SB(b, h) + boff + n * 2048 + k * 1024); } while (0)
; #define PG8_MMA(ai, bj, At, Bt) do { __builtin_amdgcn_s_setprio(1); _Pragma("unroll") for (int m = 0; m < 4; ++m) _Pragma("unroll") for (int n = 0; n < 2; ++n) _Pragma("unroll") for (int k = 0; k < 2; ++k) \
;         acc[ai][bj][m][n] = __builtin_amdgcn_mfma_f32_16x16x32_bf16(Bt[n][k], At[m][k], acc[ai][bj][m][n], 0, 0, 0); __builtin_amdgcn_s_setprio(0); } while (0)
; #define PG8_WAIT_L(n) asm volatile("s_waitcnt lgkmcnt(" #n ")" ::: "memory")
; #define PG8_BAR __builtin_amdgcn_s_barrier()
; #define PG8_SCHED __builtin_amdgcn_sched_barrier(0)
; template <class Epi>
; DEVI void gemm_phase(LAS unsigned char* lds, const bf16_t* gA, const bf16_t* gBt, const int lda, const int ldb, const int K, const StaticOrder S_, const Epi E) {
;     ...
;             const bool last = (t == nt - 2);
;             const char* a1 = cA + (size_t)(t + 1) * kstep;
;             const char* a2 = last ? nA : cA + (size_t)(t + 2) * kstep; const char* b2 = last ? nB : cB + (size_t)(t + 2) * kstep;
;             const char* a3 = a2 + kstep; const char* b3 = b2 + kstep;
;             PG8_LDB(B0, 0, 0); PG8_SCHED; PG8_LDA(At, 0, 0); PG8_STAGE(PG8_SA(1, 1), a1 + hstepA, voffA);
;             PG8_WAIT_L(8); PG8_BAR; PG8_WAIT_L(0); PG8_MMA(0, 0, At, B0); PG8_BAR; PG8_SCHED;
;             PG8_LDB(B1, 0, 1); PG8_STAGE(PG8_SB(0, 0), b2, voffB);
;             PG8_BAR; PG8_WAIT_L(0); PG8_MMA(0, 1, At, B1); PG8_BAR;
;             PG8_LDA(At, 0, 1); PG8_STAGE(PG8_SA(0, 0), a2, voffA);
;             PG8_BAR; PG8_WAIT_L(0); PG8_MMA(1, 0, At, B0); PG8_BAR; PG8_SCHED;
.LBB0_388:
	ds_read_b128 v[128:131], v201
	ds_read_b128 v[132:135], v201 offset:1024
	ds_read_b128 v[136:139], v201 offset:2048
	ds_read_b128 v[140:143], v201 offset:3072
	s_add_i32 s74, s16, 2
	s_add_u32 s40, s14, 0x80
	s_addc_u32 s17, s15, 0
	s_cmp_eq_u32 s29, s16
	s_cselect_b32 s16, s12, s40
	s_cselect_b32 s17, s13, s17
	s_cselect_b32 s41, s43, s73
	s_cselect_b32 s40, s42, s72
	v_lshl_add_u64 v[164:165], s[14:15], 0, v[174:175]
	s_add_i32 m0, s24, 0xc000
	ds_read_b128 v[144:147], v202
	ds_read_b128 v[148:151], v202 offset:1024
	ds_read_b128 v[152:155], v202 offset:2048
	ds_read_b128 v[156:159], v202 offset:3072
	ds_read_b128 v[160:163], v202 offset:4096
	ds_read_b128 v[180:183], v202 offset:5120
	ds_read_b128 v[184:187], v202 offset:6144
	ds_read_b128 v[188:191], v202 offset:7168
	global_load_lds_dwordx4 v[164:165], off
	v_lshl_add_u64 v[164:165], s[14:15], 0, v[176:177]
	s_add_i32 m0, s24, 0xe000
	s_nop 0
	global_load_lds_dwordx4 v[164:165], off
	s_waitcnt lgkmcnt(8)
	s_barrier
	s_waitcnt lgkmcnt(0)
	v_mfma_f32_16x16x32_bf16 v[124:127], v[128:131], v[144:147], v[124:127]
	v_mfma_f32_16x16x32_bf16 v[120:123], v[136:139], v[144:147], v[120:123]
	v_mfma_f32_16x16x32_bf16 v[108:111], v[128:131], v[152:155], v[108:111]
	v_mfma_f32_16x16x32_bf16 v[104:107], v[136:139], v[152:155], v[104:107]
	v_mfma_f32_16x16x32_bf16 v[92:95], v[128:131], v[160:163], v[92:95]
	v_mfma_f32_16x16x32_bf16 v[88:91], v[136:139], v[160:163], v[88:91]
	v_mfma_f32_16x16x32_bf16 v[76:79], v[128:131], v[184:187], v[76:79]
	v_mfma_f32_16x16x32_bf16 v[72:75], v[136:139], v[184:187], v[72:75]
	v_mfma_f32_16x16x32_bf16 v[124:127], v[132:135], v[148:151], v[124:127]
	v_mfma_f32_16x16x32_bf16 v[120:123], v[140:143], v[148:151], v[120:123]
	v_mfma_f32_16x16x32_bf16 v[108:111], v[132:135], v[156:159], v[108:111]
	v_mfma_f32_16x16x32_bf16 v[104:107], v[140:143], v[156:159], v[104:107]
	v_mfma_f32_16x16x32_bf16 v[92:95], v[132:135], v[180:183], v[92:95]
	v_mfma_f32_16x16x32_bf16 v[88:91], v[140:143], v[180:183], v[88:91]
	v_mfma_f32_16x16x32_bf16 v[76:79], v[132:135], v[188:191], v[76:79]
	v_mfma_f32_16x16x32_bf16 v[72:75], v[140:143], v[188:191], v[72:75]
	s_barrier
	s_add_i32 s75, s97, s22
	v_lshl_add_u64 v[164:165], s[40:41], 0, v[168:169]
	s_mov_b32 m0, s75
	ds_read_b128 v[192:195], v203
	ds_read_b128 v[206:209], v203 offset:1024
	ds_read_b128 v[210:213], v203 offset:2048
	ds_read_b128 v[214:217], v203 offset:3072
	global_load_lds_dwordx4 v[164:165], off
	v_lshl_add_u64 v[218:219], s[40:41], 0, v[172:173]
	s_add_i32 m0, s75, 0x2000
	s_nop 0
	global_load_lds_dwordx4 v[218:219], off
	s_barrier
	s_waitcnt lgkmcnt(0)
	v_mfma_f32_16x16x32_bf16 v[116:119], v[192:195], v[144:147], v[116:119]
	v_mfma_f32_16x16x32_bf16 v[112:115], v[210:213], v[144:147], v[112:115]
	v_mfma_f32_16x16x32_bf16 v[100:103], v[192:195], v[152:155], v[100:103]
	v_mfma_f32_16x16x32_bf16 v[96:99], v[210:213], v[152:155], v[96:99]
	v_mfma_f32_16x16x32_bf16 v[84:87], v[192:195], v[160:163], v[84:87]
	v_mfma_f32_16x16x32_bf16 v[80:83], v[210:213], v[160:163], v[80:83]
	v_mfma_f32_16x16x32_bf16 v[68:71], v[192:195], v[184:187], v[68:71]
	v_mfma_f32_16x16x32_bf16 v[64:67], v[210:213], v[184:187], v[64:67]
	v_mfma_f32_16x16x32_bf16 v[116:119], v[206:209], v[148:151], v[116:119]
	v_mfma_f32_16x16x32_bf16 v[112:115], v[214:217], v[148:151], v[112:115]
	v_mfma_f32_16x16x32_bf16 v[100:103], v[206:209], v[156:159], v[100:103]
	v_mfma_f32_16x16x32_bf16 v[96:99], v[214:217], v[156:159], v[96:99]
	v_mfma_f32_16x16x32_bf16 v[84:87], v[206:209], v[180:183], v[84:87]
	v_mfma_f32_16x16x32_bf16 v[80:83], v[214:217], v[180:183], v[80:83]
	v_mfma_f32_16x16x32_bf16 v[68:71], v[206:209], v[188:191], v[68:71]
	v_mfma_f32_16x16x32_bf16 v[64:67], v[214:217], v[188:191], v[64:67]
	s_mov_b32 m0, s24
	v_lshl_add_u64 v[220:221], s[16:17], 0, v[166:167]
	s_barrier
	ds_read_b128 v[144:147], v202 offset:16384
	ds_read_b128 v[148:151], v202 offset:17408
	ds_read_b128 v[152:155], v202 offset:18432
	ds_read_b128 v[156:159], v202 offset:19456
	ds_read_b128 v[160:163], v202 offset:20480
	ds_read_b128 v[180:183], v202 offset:21504
	ds_read_b128 v[184:187], v202 offset:22528
	ds_read_b128 v[188:191], v202 offset:23552
	global_load_lds_dwordx4 v[220:221], off
	v_lshl_add_u64 v[222:223], s[16:17], 0, v[170:171]
	s_mov_b32 m0, s25
	s_nop 0
	global_load_lds_dwordx4 v[222:223], off
	s_barrier
	s_waitcnt lgkmcnt(0)
	v_mfma_f32_16x16x32_bf16 v[60:63], v[128:131], v[144:147], v[60:63]
	v_mfma_f32_16x16x32_bf16 v[56:59], v[136:139], v[144:147], v[56:59]
	v_mfma_f32_16x16x32_bf16 v[44:47], v[128:131], v[152:155], v[44:47]
	v_mfma_f32_16x16x32_bf16 v[40:43], v[136:139], v[152:155], v[40:43]
	v_mfma_f32_16x16x32_bf16 v[28:31], v[128:131], v[160:163], v[28:31]
	v_mfma_f32_16x16x32_bf16 v[24:27], v[136:139], v[160:163], v[24:27]
	v_mfma_f32_16x16x32_bf16 v[12:15], v[128:131], v[184:187], v[12:15]
	v_mfma_f32_16x16x32_bf16 v[8:11], v[136:139], v[184:187], v[8:11]
	v_mfma_f32_16x16x32_bf16 v[60:63], v[132:135], v[148:151], v[60:63]
	v_mfma_f32_16x16x32_bf16 v[56:59], v[140:143], v[148:151], v[56:59]
	v_mfma_f32_16x16x32_bf16 v[44:47], v[132:135], v[156:159], v[44:47]
	v_mfma_f32_16x16x32_bf16 v[40:43], v[140:143], v[156:159], v[40:43]
	v_mfma_f32_16x16x32_bf16 v[28:31], v[132:135], v[180:183], v[28:31]
	v_mfma_f32_16x16x32_bf16 v[24:27], v[140:143], v[180:183], v[24:27]
	v_mfma_f32_16x16x32_bf16 v[12:15], v[132:135], v[188:191], v[12:15]
	v_mfma_f32_16x16x32_bf16 v[8:11], v[140:143], v[188:191], v[8:11]
	s_barrier
; #define PG8_STAGE(bufoff, gbase, voff) do { _Pragma("unroll") for (int _i = 0; _i < 2; ++_i) \
;         __builtin_amdgcn_global_load_lds((const unsigned*)((const char*)(gbase) + (voff)[_i]), (LAS unsigned*)(lds + (bufoff) + ldsw + _i * 8192), 16, 0, 0); } while (0)
; #define PG8_LDA(dst, b, h) do { _Pragma("unroll") for (int m = 0; m < 4; ++m) _Pragma("unroll") for (int k = 0; k < 2; ++k) dst[m][k] = *(const LAS bf16x8*)(lds + PG8_SA(b, h) + aoff + m * 2048 + k * 1024); } while (0)
; #define PG8_LDB(dst, b, h) do { _Pragma("unroll") for (int n = 0; n < 2; ++n) _Pragma("unroll") for (int k = 0; k < 2; ++k) dst[n][k] = *(const LAS bf16x8*)(lds + PG8_SB(b, h) + boff + n * 2048 + k * 1024); } while (0)
; #define PG8_MMA(ai, bj, At, Bt) do { __builtin_amdgcn_s_setprio(1); _Pragma("unroll") for (int m = 0; m < 4; ++m) _Pragma("unroll") for (int n = 0; n < 2; ++n) _Pragma("unroll") for (int k = 0; k < 2; ++k) \
;         acc[ai][bj][m][n] = __builtin_amdgcn_mfma_f32_16x16x32_bf16(Bt[n][k], At[m][k], acc[ai][bj][m][n], 0, 0, 0); __builtin_amdgcn_s_setprio(0); } while (0)
; #define PG8_WAIT_V(n) asm volatile("s_waitcnt vmcnt(" #n ")" ::: "memory")
; #define PG8_WAIT_L(n) asm volatile("s_waitcnt lgkmcnt(" #n ")" ::: "memory")
; #define PG8_BAR __builtin_amdgcn_s_barrier()
; #define PG8_SCHED __builtin_amdgcn_sched_barrier(0)
; template <class Epi>
; DEVI void gemm_phase(LAS unsigned char* lds, const bf16_t* gA, const bf16_t* gBt, const int lda, const int ldb, const int K, const StaticOrder S_, const Epi E) {
;     ...
;             PG8_STAGE(PG8_SB(0, 1), b2 + hstepB, voffB);
;             PG8_WAIT_V(6); PG8_BAR; PG8_MMA(1, 1, At, B1); PG8_BAR;
;             PG8_LDB(B0, 1, 0); PG8_SCHED; PG8_LDA(At, 1, 0); PG8_STAGE(PG8_SA(0, 1), a2 + hstepA, voffA);
;             PG8_WAIT_L(8); PG8_BAR; PG8_WAIT_L(0); PG8_MMA(0, 0, At, B0); PG8_BAR; PG8_SCHED;
;             PG8_LDB(B1, 1, 1); PG8_STAGE(PG8_SB(1, 0), b3, voffB);
;             PG8_BAR; PG8_WAIT_L(0); PG8_MMA(0, 1, At, B1); PG8_BAR;
	s_add_u32 s40, s40, s0
	s_addc_u32 s41, s41, s1
	s_add_i32 s75, s50, s22
	v_lshl_add_u64 v[224:225], s[40:41], 0, v[168:169]
	s_mov_b32 m0, s75
	v_lshl_add_u64 v[226:227], s[40:41], 0, v[172:173]
	global_load_lds_dwordx4 v[224:225], off
	s_add_i32 m0, s75, 0x2000
	s_nop 0
	global_load_lds_dwordx4 v[226:227], off
	s_waitcnt vmcnt(6)
	s_barrier
	v_mfma_f32_16x16x32_bf16 v[52:55], v[192:195], v[144:147], v[52:55]
	v_mfma_f32_16x16x32_bf16 v[48:51], v[210:213], v[144:147], v[48:51]
	v_mfma_f32_16x16x32_bf16 v[36:39], v[192:195], v[152:155], v[36:39]
	v_mfma_f32_16x16x32_bf16 v[32:35], v[210:213], v[152:155], v[32:35]
	v_mfma_f32_16x16x32_bf16 v[20:23], v[192:195], v[160:163], v[20:23]
	v_mfma_f32_16x16x32_bf16 v[16:19], v[210:213], v[160:163], v[16:19]
	v_mfma_f32_16x16x32_bf16 v[4:7], v[192:195], v[184:187], v[4:7]
	v_mfma_f32_16x16x32_bf16 v[0:3], v[210:213], v[184:187], v[0:3]
	v_mfma_f32_16x16x32_bf16 v[52:55], v[206:209], v[148:151], v[52:55]
	v_mfma_f32_16x16x32_bf16 v[48:51], v[214:217], v[148:151], v[48:51]
	v_mfma_f32_16x16x32_bf16 v[36:39], v[206:209], v[156:159], v[36:39]
	v_mfma_f32_16x16x32_bf16 v[32:35], v[214:217], v[156:159], v[32:35]
	v_mfma_f32_16x16x32_bf16 v[20:23], v[206:209], v[180:183], v[20:23]
	v_mfma_f32_16x16x32_bf16 v[16:19], v[214:217], v[180:183], v[16:19]
	v_mfma_f32_16x16x32_bf16 v[4:7], v[206:209], v[188:191], v[4:7]
	v_mfma_f32_16x16x32_bf16 v[0:3], v[214:217], v[188:191], v[0:3]
	s_add_i32 s40, 0, 0x18000
	v_add_u32_e32 v140, s40, v199
	s_barrier
	ds_read_b128 v[128:131], v140
	ds_read_b128 v[132:135], v140 offset:1024
	ds_read_b128 v[136:139], v140 offset:2048
	ds_read_b128 v[140:143], v140 offset:3072
	s_add_u32 s16, s16, s48
	s_addc_u32 s17, s17, s49
	s_mov_b32 m0, s26
	v_lshl_add_u64 v[192:193], s[16:17], 0, v[166:167]
	ds_read_b128 v[144:147], v202 offset:32768
	ds_read_b128 v[148:151], v202 offset:33792
	ds_read_b128 v[152:155], v202 offset:34816
	ds_read_b128 v[156:159], v202 offset:35840
	ds_read_b128 v[160:163], v202 offset:36864
	ds_read_b128 v[180:183], v202 offset:37888
	ds_read_b128 v[184:187], v202 offset:38912
	ds_read_b128 v[188:191], v202 offset:39936
	global_load_lds_dwordx4 v[192:193], off
	v_lshl_add_u64 v[192:193], s[16:17], 0, v[170:171]
	s_mov_b32 m0, s27
	s_nop 0
	global_load_lds_dwordx4 v[192:193], off
	s_waitcnt lgkmcnt(8)
	s_barrier
	s_waitcnt lgkmcnt(0)
	v_mfma_f32_16x16x32_bf16 v[124:127], v[128:131], v[144:147], v[124:127]
	v_mfma_f32_16x16x32_bf16 v[120:123], v[136:139], v[144:147], v[120:123]
	v_mfma_f32_16x16x32_bf16 v[108:111], v[128:131], v[152:155], v[108:111]
	v_mfma_f32_16x16x32_bf16 v[104:107], v[136:139], v[152:155], v[104:107]
	v_mfma_f32_16x16x32_bf16 v[92:95], v[128:131], v[160:163], v[92:95]
	v_mfma_f32_16x16x32_bf16 v[88:91], v[136:139], v[160:163], v[88:91]
	v_mfma_f32_16x16x32_bf16 v[76:79], v[128:131], v[184:187], v[76:79]
	v_mfma_f32_16x16x32_bf16 v[72:75], v[136:139], v[184:187], v[72:75]
	v_mfma_f32_16x16x32_bf16 v[124:127], v[132:135], v[148:151], v[124:127]
	v_mfma_f32_16x16x32_bf16 v[120:123], v[140:143], v[148:151], v[120:123]
	v_mfma_f32_16x16x32_bf16 v[108:111], v[132:135], v[156:159], v[108:111]
	v_mfma_f32_16x16x32_bf16 v[104:107], v[140:143], v[156:159], v[104:107]
	v_mfma_f32_16x16x32_bf16 v[92:95], v[132:135], v[180:183], v[92:95]
	v_mfma_f32_16x16x32_bf16 v[88:91], v[140:143], v[180:183], v[88:91]
	v_mfma_f32_16x16x32_bf16 v[76:79], v[132:135], v[188:191], v[76:79]
	v_mfma_f32_16x16x32_bf16 v[72:75], v[140:143], v[188:191], v[72:75]
	s_barrier
	s_add_i32 s16, 0, 0x1c000
	s_add_i32 s17, s40, s22
	v_add_u32_e32 v214, s16, v199
	v_lshl_add_u64 v[164:165], v[164:165], 0, s[10:11]
	s_mov_b32 m0, s17
	ds_read_b128 v[192:195], v214
	ds_read_b128 v[206:209], v214 offset:1024
	ds_read_b128 v[210:213], v214 offset:2048
	ds_read_b128 v[214:217], v214 offset:3072
	global_load_lds_dwordx4 v[164:165], off
	v_lshl_add_u64 v[164:165], v[218:219], 0, s[10:11]
	s_add_i32 m0, s17, 0x2000
	s_nop 0
	global_load_lds_dwordx4 v[164:165], off
	s_barrier
; #define PG8_STAGE(bufoff, gbase, voff) do { _Pragma("unroll") for (int _i = 0; _i < 2; ++_i) \
;         __builtin_amdgcn_global_load_lds((const unsigned*)((const char*)(gbase) + (voff)[_i]), (LAS unsigned*)(lds + (bufoff) + ldsw + _i * 8192), 16, 0, 0); } while (0)
; #define PG8_LDA(dst, b, h) do { _Pragma("unroll") for (int m = 0; m < 4; ++m) _Pragma("unroll") for (int k = 0; k < 2; ++k) dst[m][k] = *(const LAS bf16x8*)(lds + PG8_SA(b, h) + aoff + m * 2048 + k * 1024); } while (0)
; #define PG8_MMA(ai, bj, At, Bt) do { __builtin_amdgcn_s_setprio(1); _Pragma("unroll") for (int m = 0; m < 4; ++m) _Pragma("unroll") for (int n = 0; n < 2; ++n) _Pragma("unroll") for (int k = 0; k < 2; ++k) \
;         acc[ai][bj][m][n] = __builtin_amdgcn_mfma_f32_16x16x32_bf16(Bt[n][k], At[m][k], acc[ai][bj][m][n], 0, 0, 0); __builtin_amdgcn_s_setprio(0); } while (0)
; #define PG8_WAIT_V(n) asm volatile("s_waitcnt vmcnt(" #n ")" ::: "memory")
; #define PG8_WAIT_L(n) asm volatile("s_waitcnt lgkmcnt(" #n ")" ::: "memory")
; #define PG8_BAR __builtin_amdgcn_s_barrier()
; #define PG8_SCHED __builtin_amdgcn_sched_barrier(0)
; template <class Epi>
; DEVI void gemm_phase(LAS unsigned char* lds, const bf16_t* gA, const bf16_t* gBt, const int lda, const int ldb, const int K, const StaticOrder S_, const Epi E) {
;     ...
;             PG8_BAR; PG8_WAIT_L(0); PG8_MMA(0, 1, At, B1); PG8_BAR;
;             PG8_LDA(At, 1, 1); PG8_STAGE(PG8_SA(1, 0), a3, voffA);
;             PG8_BAR; PG8_WAIT_L(0); PG8_MMA(1, 0, At, B0); PG8_BAR; PG8_SCHED;
;             PG8_STAGE(PG8_SB(1, 1), b3 + hstepB, voffB);
;             PG8_WAIT_V(6); PG8_BAR; PG8_MMA(1, 1, At, B1); PG8_BAR;
	s_waitcnt lgkmcnt(0)
	v_mfma_f32_16x16x32_bf16 v[116:119], v[192:195], v[144:147], v[116:119]
	v_mfma_f32_16x16x32_bf16 v[112:115], v[210:213], v[144:147], v[112:115]
	v_mfma_f32_16x16x32_bf16 v[100:103], v[192:195], v[152:155], v[100:103]
	v_mfma_f32_16x16x32_bf16 v[96:99], v[210:213], v[152:155], v[96:99]
	v_mfma_f32_16x16x32_bf16 v[84:87], v[192:195], v[160:163], v[84:87]
	v_mfma_f32_16x16x32_bf16 v[80:83], v[210:213], v[160:163], v[80:83]
	v_mfma_f32_16x16x32_bf16 v[68:71], v[192:195], v[184:187], v[68:71]
	v_mfma_f32_16x16x32_bf16 v[64:67], v[210:213], v[184:187], v[64:67]
	v_mfma_f32_16x16x32_bf16 v[116:119], v[206:209], v[148:151], v[116:119]
	v_mfma_f32_16x16x32_bf16 v[112:115], v[214:217], v[148:151], v[112:115]
	v_mfma_f32_16x16x32_bf16 v[100:103], v[206:209], v[156:159], v[100:103]
	v_mfma_f32_16x16x32_bf16 v[96:99], v[214:217], v[156:159], v[96:99]
	v_mfma_f32_16x16x32_bf16 v[84:87], v[206:209], v[180:183], v[84:87]
	v_mfma_f32_16x16x32_bf16 v[80:83], v[214:217], v[180:183], v[80:83]
	v_mfma_f32_16x16x32_bf16 v[68:71], v[206:209], v[188:191], v[68:71]
	v_mfma_f32_16x16x32_bf16 v[64:67], v[214:217], v[188:191], v[64:67]
	s_mov_b32 m0, s18
	v_lshl_add_u64 v[164:165], v[220:221], 0, s[10:11]
	s_barrier
	ds_read_b128 v[144:147], v202 offset:49152
	ds_read_b128 v[148:151], v202 offset:50176
	ds_read_b128 v[152:155], v202 offset:51200
	ds_read_b128 v[156:159], v202 offset:52224
	ds_read_b128 v[160:163], v202 offset:53248
	ds_read_b128 v[180:183], v202 offset:54272
	ds_read_b128 v[184:187], v202 offset:55296
	ds_read_b128 v[188:191], v202 offset:56320
	global_load_lds_dwordx4 v[164:165], off
	v_lshl_add_u64 v[164:165], v[222:223], 0, s[10:11]
	s_mov_b32 m0, s19
	s_nop 0
	global_load_lds_dwordx4 v[164:165], off
	s_barrier
	s_waitcnt lgkmcnt(0)
	v_mfma_f32_16x16x32_bf16 v[60:63], v[128:131], v[144:147], v[60:63]
	v_mfma_f32_16x16x32_bf16 v[56:59], v[136:139], v[144:147], v[56:59]
	v_mfma_f32_16x16x32_bf16 v[44:47], v[128:131], v[152:155], v[44:47]
	v_mfma_f32_16x16x32_bf16 v[40:43], v[136:139], v[152:155], v[40:43]
	v_mfma_f32_16x16x32_bf16 v[28:31], v[128:131], v[160:163], v[28:31]
	v_mfma_f32_16x16x32_bf16 v[24:27], v[136:139], v[160:163], v[24:27]
	v_mfma_f32_16x16x32_bf16 v[12:15], v[128:131], v[184:187], v[12:15]
	v_mfma_f32_16x16x32_bf16 v[8:11], v[136:139], v[184:187], v[8:11]
	v_mfma_f32_16x16x32_bf16 v[60:63], v[132:135], v[148:151], v[60:63]
	v_mfma_f32_16x16x32_bf16 v[56:59], v[140:143], v[148:151], v[56:59]
	v_mfma_f32_16x16x32_bf16 v[44:47], v[132:135], v[156:159], v[44:47]
	v_mfma_f32_16x16x32_bf16 v[40:43], v[140:143], v[156:159], v[40:43]
	v_mfma_f32_16x16x32_bf16 v[28:31], v[132:135], v[180:183], v[28:31]
	v_mfma_f32_16x16x32_bf16 v[24:27], v[140:143], v[180:183], v[24:27]
	v_mfma_f32_16x16x32_bf16 v[12:15], v[132:135], v[188:191], v[12:15]
	v_mfma_f32_16x16x32_bf16 v[8:11], v[140:143], v[188:191], v[8:11]
	s_barrier
	s_add_i32 s16, s16, s22
	v_lshl_add_u64 v[128:129], v[224:225], 0, s[10:11]
	s_mov_b32 m0, s16
	s_nop 0
	global_load_lds_dwordx4 v[128:129], off
	v_lshl_add_u64 v[128:129], v[226:227], 0, s[10:11]
	s_add_i32 m0, s16, 0x2000
	s_nop 0
	global_load_lds_dwordx4 v[128:129], off
	s_waitcnt vmcnt(6)
	s_barrier
	v_mfma_f32_16x16x32_bf16 v[52:55], v[192:195], v[144:147], v[52:55]
	v_mfma_f32_16x16x32_bf16 v[48:51], v[210:213], v[144:147], v[48:51]
	v_mfma_f32_16x16x32_bf16 v[36:39], v[192:195], v[152:155], v[36:39]
	v_mfma_f32_16x16x32_bf16 v[32:35], v[210:213], v[152:155], v[32:35]
	v_mfma_f32_16x16x32_bf16 v[20:23], v[192:195], v[160:163], v[20:23]
	v_mfma_f32_16x16x32_bf16 v[16:19], v[210:213], v[160:163], v[16:19]
	v_mfma_f32_16x16x32_bf16 v[4:7], v[192:195], v[184:187], v[4:7]
	v_mfma_f32_16x16x32_bf16 v[0:3], v[210:213], v[184:187], v[0:3]
	v_mfma_f32_16x16x32_bf16 v[52:55], v[206:209], v[148:151], v[52:55]
	v_mfma_f32_16x16x32_bf16 v[48:51], v[214:217], v[148:151], v[48:51]
	v_mfma_f32_16x16x32_bf16 v[36:39], v[206:209], v[156:159], v[36:39]
	v_mfma_f32_16x16x32_bf16 v[32:35], v[214:217], v[156:159], v[32:35]
	v_mfma_f32_16x16x32_bf16 v[20:23], v[206:209], v[180:183], v[20:23]
	v_mfma_f32_16x16x32_bf16 v[16:19], v[214:217], v[180:183], v[16:19]
	v_mfma_f32_16x16x32_bf16 v[4:7], v[206:209], v[188:191], v[4:7]
	v_mfma_f32_16x16x32_bf16 v[0:3], v[214:217], v[188:191], v[0:3]
	s_add_u32 s14, s14, 0x100
	s_addc_u32 s15, s15, 0
	s_add_u32 s72, s72, 0x100
	s_addc_u32 s73, s73, 0
	s_cmp_ge_i32 s74, s28
	s_mov_b32 s16, s74
	s_barrier
	s_cbranch_scc0 .LBB0_388

; #define PG8_STAGE(bufoff, gbase, voff) do { _Pragma("unroll") for (int _i = 0; _i < 2; ++_i) \
;         __builtin_amdgcn_global_load_lds((const unsigned*)((const char*)(gbase) + (voff)[_i]), (LAS unsigned*)(lds + (bufoff) + ldsw + _i * 8192), 16, 0, 0); } while (0)
; #define PG8_LDA(dst, b, h) do { _Pragma("unroll") for (int m = 0; m < 4; ++m) _Pragma("unroll") for (int k = 0; k < 2; ++k) dst[m][k] = *(const LAS bf16x8*)(lds + PG8_SA(b, h) + aoff + m * 2048 + k * 1024); } while (0)
; #define PG8_LDB(dst, b, h) do { _Pragma("unroll") for (int n = 0; n < 2; ++n) _Pragma("unroll") for (int k = 0; k < 2; ++k) dst[n][k] = *(const LAS bf16x8*)(lds + PG8_SB(b, h) + boff + n * 2048 + k * 1024); } while (0)
; #define PG8_MMA(ai, bj, At, Bt) do { __builtin_amdgcn_s_setprio(1); _Pragma("unroll") for (int m = 0; m < 4; ++m) _Pragma("unroll") for (int n = 0; n < 2; ++n) _Pragma("unroll") for (int k = 0; k < 2; ++k) \
;         acc[ai][bj][m][n] = __builtin_amdgcn_mfma_f32_16x16x32_bf16(Bt[n][k], At[m][k], acc[ai][bj][m][n], 0, 0, 0); __builtin_amdgcn_s_setprio(0); } while (0)
; #define PG8_WAIT_L(n) asm volatile("s_waitcnt lgkmcnt(" #n ")" ::: "memory")
; #define PG8_BAR __builtin_amdgcn_s_barrier()
; #define PG8_SCHED __builtin_amdgcn_sched_barrier(0)
; template <class Epi>
; DEVI void gemm_phase(LAS unsigned char* lds, const bf16_t* gA, const bf16_t* gBt, const int lda, const int ldb, const int K, const StaticOrder S_, const Epi E) {
;     ...
;             const bool last = (t == nt - 2);
;             const char* a1 = cA + (size_t)(t + 1) * kstep;
;             const char* a2 = last ? nA : cA + (size_t)(t + 2) * kstep; const char* b2 = last ? nB : cB + (size_t)(t + 2) * kstep;
;             const char* a3 = a2 + kstep; const char* b3 = b2 + kstep;
;             PG8_LDB(B0, 0, 0); PG8_SCHED; PG8_LDA(At, 0, 0); PG8_STAGE(PG8_SA(1, 1), a1 + hstepA, voffA);
;             PG8_WAIT_L(8); PG8_BAR; PG8_WAIT_L(0); PG8_MMA(0, 0, At, B0); PG8_BAR; PG8_SCHED;
;             PG8_LDB(B1, 0, 1); PG8_STAGE(PG8_SB(0, 0), b2, voffB);
;             PG8_BAR; PG8_WAIT_L(0); PG8_MMA(0, 1, At, B1); PG8_BAR;
;             PG8_LDA(At, 0, 1); PG8_STAGE(PG8_SA(0, 0), a2, voffA);
;             PG8_BAR; PG8_WAIT_L(0); PG8_MMA(1, 0, At, B0); PG8_BAR; PG8_SCHED;
.LBB0_519:
	ds_read_b128 v[160:163], v153
	ds_read_b128 v[164:167], v153 offset:1024
	ds_read_b128 v[168:171], v153 offset:2048
	ds_read_b128 v[172:175], v153 offset:3072
	s_add_i32 s77, s16, 2
	s_add_u32 s40, s14, 0x80
	s_addc_u32 s17, s15, 0
	s_cmp_eq_u32 s26, s16
	s_cselect_b32 s16, s48, s40
	s_cselect_b32 s17, s49, s17
	s_cselect_b32 s41, s61, s69
	s_cselect_b32 s40, s60, s68
	v_lshl_add_u64 v[144:145], s[14:15], 0, v[138:139]
	s_add_i32 m0, s19, 0xc000
	ds_read_b128 v[176:179], v154
	ds_read_b128 v[180:183], v154 offset:1024
	ds_read_b128 v[184:187], v154 offset:2048
	ds_read_b128 v[188:191], v154 offset:3072
	ds_read_b128 v[192:195], v154 offset:4096
	ds_read_b128 v[198:201], v154 offset:5120
	ds_read_b128 v[202:205], v154 offset:6144
	ds_read_b128 v[206:209], v154 offset:7168
	global_load_lds_dwordx4 v[144:145], off
	v_lshl_add_u64 v[144:145], s[14:15], 0, v[140:141]
	s_add_i32 m0, s19, 0xe000
	s_nop 0
	global_load_lds_dwordx4 v[144:145], off
	s_waitcnt lgkmcnt(8)
	s_barrier
	s_waitcnt lgkmcnt(0)
	v_mfma_f32_16x16x32_bf16 v[124:127], v[160:163], v[176:179], v[124:127]
	v_mfma_f32_16x16x32_bf16 v[120:123], v[168:171], v[176:179], v[120:123]
	v_mfma_f32_16x16x32_bf16 v[108:111], v[160:163], v[184:187], v[108:111]
	v_mfma_f32_16x16x32_bf16 v[104:107], v[168:171], v[184:187], v[104:107]
	v_mfma_f32_16x16x32_bf16 v[92:95], v[160:163], v[192:195], v[92:95]
	v_mfma_f32_16x16x32_bf16 v[88:91], v[168:171], v[192:195], v[88:91]
	v_mfma_f32_16x16x32_bf16 v[76:79], v[160:163], v[202:205], v[76:79]
	v_mfma_f32_16x16x32_bf16 v[72:75], v[168:171], v[202:205], v[72:75]
	v_mfma_f32_16x16x32_bf16 v[124:127], v[164:167], v[180:183], v[124:127]
	v_mfma_f32_16x16x32_bf16 v[120:123], v[172:175], v[180:183], v[120:123]
	v_mfma_f32_16x16x32_bf16 v[108:111], v[164:167], v[188:191], v[108:111]
	v_mfma_f32_16x16x32_bf16 v[104:107], v[172:175], v[188:191], v[104:107]
	v_mfma_f32_16x16x32_bf16 v[92:95], v[164:167], v[198:201], v[92:95]
	v_mfma_f32_16x16x32_bf16 v[88:91], v[172:175], v[198:201], v[88:91]
	v_mfma_f32_16x16x32_bf16 v[76:79], v[164:167], v[206:209], v[76:79]
	v_mfma_f32_16x16x32_bf16 v[72:75], v[172:175], v[206:209], v[72:75]
	s_barrier
	s_add_i32 s78, s31, s18
	v_lshl_add_u64 v[144:145], s[40:41], 0, v[130:131]
	s_mov_b32 m0, s78
	ds_read_b128 v[210:213], v155
	ds_read_b128 v[214:217], v155 offset:1024
	ds_read_b128 v[218:221], v155 offset:2048
	ds_read_b128 v[222:225], v155 offset:3072
	global_load_lds_dwordx4 v[144:145], off
	v_lshl_add_u64 v[226:227], s[40:41], 0, v[134:135]
	s_add_i32 m0, s78, 0x2000
	s_nop 0
	global_load_lds_dwordx4 v[226:227], off
	s_barrier
	s_waitcnt lgkmcnt(0)
	v_mfma_f32_16x16x32_bf16 v[116:119], v[210:213], v[176:179], v[116:119]
	v_mfma_f32_16x16x32_bf16 v[112:115], v[218:221], v[176:179], v[112:115]
	v_mfma_f32_16x16x32_bf16 v[100:103], v[210:213], v[184:187], v[100:103]
	v_mfma_f32_16x16x32_bf16 v[96:99], v[218:221], v[184:187], v[96:99]
	v_mfma_f32_16x16x32_bf16 v[84:87], v[210:213], v[192:195], v[84:87]
	v_mfma_f32_16x16x32_bf16 v[80:83], v[218:221], v[192:195], v[80:83]
	v_mfma_f32_16x16x32_bf16 v[68:71], v[210:213], v[202:205], v[68:71]
	v_mfma_f32_16x16x32_bf16 v[64:67], v[218:221], v[202:205], v[64:67]
	v_mfma_f32_16x16x32_bf16 v[116:119], v[214:217], v[180:183], v[116:119]
	v_mfma_f32_16x16x32_bf16 v[112:115], v[222:225], v[180:183], v[112:115]
	v_mfma_f32_16x16x32_bf16 v[100:103], v[214:217], v[188:191], v[100:103]
	v_mfma_f32_16x16x32_bf16 v[96:99], v[222:225], v[188:191], v[96:99]
	v_mfma_f32_16x16x32_bf16 v[84:87], v[214:217], v[198:201], v[84:87]
	v_mfma_f32_16x16x32_bf16 v[80:83], v[222:225], v[198:201], v[80:83]
	v_mfma_f32_16x16x32_bf16 v[68:71], v[214:217], v[206:209], v[68:71]
	v_mfma_f32_16x16x32_bf16 v[64:67], v[222:225], v[206:209], v[64:67]
	s_mov_b32 m0, s19
	v_lshl_add_u64 v[228:229], s[16:17], 0, v[128:129]
	s_barrier
	ds_read_b128 v[176:179], v154 offset:16384
	ds_read_b128 v[180:183], v154 offset:17408
	ds_read_b128 v[184:187], v154 offset:18432
	ds_read_b128 v[188:191], v154 offset:19456
	ds_read_b128 v[192:195], v154 offset:20480
	ds_read_b128 v[198:201], v154 offset:21504
	ds_read_b128 v[202:205], v154 offset:22528
	ds_read_b128 v[206:209], v154 offset:23552
	global_load_lds_dwordx4 v[228:229], off
	v_lshl_add_u64 v[230:231], s[16:17], 0, v[132:133]
	s_mov_b32 m0, s20
	s_nop 0
	global_load_lds_dwordx4 v[230:231], off
	s_barrier
	s_waitcnt lgkmcnt(0)
	v_mfma_f32_16x16x32_bf16 v[60:63], v[160:163], v[176:179], v[60:63]
	v_mfma_f32_16x16x32_bf16 v[56:59], v[168:171], v[176:179], v[56:59]
	v_mfma_f32_16x16x32_bf16 v[44:47], v[160:163], v[184:187], v[44:47]
	v_mfma_f32_16x16x32_bf16 v[40:43], v[168:171], v[184:187], v[40:43]
	v_mfma_f32_16x16x32_bf16 v[28:31], v[160:163], v[192:195], v[28:31]
	v_mfma_f32_16x16x32_bf16 v[24:27], v[168:171], v[192:195], v[24:27]
	v_mfma_f32_16x16x32_bf16 v[12:15], v[160:163], v[202:205], v[12:15]
	v_mfma_f32_16x16x32_bf16 v[8:11], v[168:171], v[202:205], v[8:11]
	v_mfma_f32_16x16x32_bf16 v[60:63], v[164:167], v[180:183], v[60:63]
	v_mfma_f32_16x16x32_bf16 v[56:59], v[172:175], v[180:183], v[56:59]
	v_mfma_f32_16x16x32_bf16 v[44:47], v[164:167], v[188:191], v[44:47]
	v_mfma_f32_16x16x32_bf16 v[40:43], v[172:175], v[188:191], v[40:43]
	v_mfma_f32_16x16x32_bf16 v[28:31], v[164:167], v[198:201], v[28:31]
	v_mfma_f32_16x16x32_bf16 v[24:27], v[172:175], v[198:201], v[24:27]
	v_mfma_f32_16x16x32_bf16 v[12:15], v[164:167], v[206:209], v[12:15]
	v_mfma_f32_16x16x32_bf16 v[8:11], v[172:175], v[206:209], v[8:11]
	s_barrier
; #define PG8_STAGE(bufoff, gbase, voff) do { _Pragma("unroll") for (int _i = 0; _i < 2; ++_i) \
;         __builtin_amdgcn_global_load_lds((const unsigned*)((const char*)(gbase) + (voff)[_i]), (LAS unsigned*)(lds + (bufoff) + ldsw + _i * 8192), 16, 0, 0); } while (0)
; #define PG8_LDA(dst, b, h) do { _Pragma("unroll") for (int m = 0; m < 4; ++m) _Pragma("unroll") for (int k = 0; k < 2; ++k) dst[m][k] = *(const LAS bf16x8*)(lds + PG8_SA(b, h) + aoff + m * 2048 + k * 1024); } while (0)
; #define PG8_LDB(dst, b, h) do { _Pragma("unroll") for (int n = 0; n < 2; ++n) _Pragma("unroll") for (int k = 0; k < 2; ++k) dst[n][k] = *(const LAS bf16x8*)(lds + PG8_SB(b, h) + boff + n * 2048 + k * 1024); } while (0)
; #define PG8_MMA(ai, bj, At, Bt) do { __builtin_amdgcn_s_setprio(1); _Pragma("unroll") for (int m = 0; m < 4; ++m) _Pragma("unroll") for (int n = 0; n < 2; ++n) _Pragma("unroll") for (int k = 0; k < 2; ++k) \
;         acc[ai][bj][m][n] = __builtin_amdgcn_mfma_f32_16x16x32_bf16(Bt[n][k], At[m][k], acc[ai][bj][m][n], 0, 0, 0); __builtin_amdgcn_s_setprio(0); } while (0)
; #define PG8_WAIT_V(n) asm volatile("s_waitcnt vmcnt(" #n ")" ::: "memory")
; #define PG8_WAIT_L(n) asm volatile("s_waitcnt lgkmcnt(" #n ")" ::: "memory")
; #define PG8_BAR __builtin_amdgcn_s_barrier()
; #define PG8_SCHED __builtin_amdgcn_sched_barrier(0)
; template <class Epi>
; DEVI void gemm_phase(LAS unsigned char* lds, const bf16_t* gA, const bf16_t* gBt, const int lda, const int ldb, const int K, const StaticOrder S_, const Epi E) {
;     ...
;             PG8_STAGE(PG8_SB(0, 1), b2 + hstepB, voffB);
;             PG8_WAIT_V(6); PG8_BAR; PG8_MMA(1, 1, At, B1); PG8_BAR;
;             PG8_LDB(B0, 1, 0); PG8_SCHED; PG8_LDA(At, 1, 0); PG8_STAGE(PG8_SA(0, 1), a2 + hstepA, voffA);
;             PG8_WAIT_L(8); PG8_BAR; PG8_WAIT_L(0); PG8_MMA(0, 0, At, B0); PG8_BAR; PG8_SCHED;
;             PG8_LDB(B1, 1, 1); PG8_STAGE(PG8_SB(1, 0), b3, voffB);
	s_add_u32 s40, s40, s2
	s_addc_u32 s41, s41, s3
	s_add_i32 s78, s34, s18
	v_lshl_add_u64 v[232:233], s[40:41], 0, v[130:131]
	s_mov_b32 m0, s78
	v_lshl_add_u64 v[234:235], s[40:41], 0, v[134:135]
	global_load_lds_dwordx4 v[232:233], off
	s_add_i32 m0, s78, 0x2000
	s_nop 0
	global_load_lds_dwordx4 v[234:235], off
	s_waitcnt vmcnt(6)
	s_barrier
	v_mfma_f32_16x16x32_bf16 v[52:55], v[210:213], v[176:179], v[52:55]
	v_mfma_f32_16x16x32_bf16 v[48:51], v[218:221], v[176:179], v[48:51]
	v_mfma_f32_16x16x32_bf16 v[36:39], v[210:213], v[184:187], v[36:39]
	v_mfma_f32_16x16x32_bf16 v[32:35], v[218:221], v[184:187], v[32:35]
	v_mfma_f32_16x16x32_bf16 v[20:23], v[210:213], v[192:195], v[20:23]
	v_mfma_f32_16x16x32_bf16 v[16:19], v[218:221], v[192:195], v[16:19]
	v_mfma_f32_16x16x32_bf16 v[4:7], v[210:213], v[202:205], v[4:7]
	v_mfma_f32_16x16x32_bf16 v[0:3], v[218:221], v[202:205], v[0:3]
	v_mfma_f32_16x16x32_bf16 v[52:55], v[214:217], v[180:183], v[52:55]
	v_mfma_f32_16x16x32_bf16 v[48:51], v[222:225], v[180:183], v[48:51]
	v_mfma_f32_16x16x32_bf16 v[36:39], v[214:217], v[188:191], v[36:39]
	v_mfma_f32_16x16x32_bf16 v[32:35], v[222:225], v[188:191], v[32:35]
	v_mfma_f32_16x16x32_bf16 v[20:23], v[214:217], v[198:201], v[20:23]
	v_mfma_f32_16x16x32_bf16 v[16:19], v[222:225], v[198:201], v[16:19]
	v_mfma_f32_16x16x32_bf16 v[4:7], v[214:217], v[206:209], v[4:7]
	v_mfma_f32_16x16x32_bf16 v[0:3], v[222:225], v[206:209], v[0:3]
	s_barrier
	ds_read_b128 v[160:163], v156
	ds_read_b128 v[164:167], v156 offset:1024
	ds_read_b128 v[168:171], v156 offset:2048
	ds_read_b128 v[172:175], v156 offset:3072
	s_add_u32 s16, s16, s0
	s_addc_u32 s17, s17, s1
	s_mov_b32 m0, s21
	v_lshl_add_u64 v[210:211], s[16:17], 0, v[128:129]
	ds_read_b128 v[176:179], v154 offset:32768
	ds_read_b128 v[180:183], v154 offset:33792
	ds_read_b128 v[184:187], v154 offset:34816
	ds_read_b128 v[188:191], v154 offset:35840
	ds_read_b128 v[192:195], v154 offset:36864
	ds_read_b128 v[198:201], v154 offset:37888
	ds_read_b128 v[202:205], v154 offset:38912
	ds_read_b128 v[206:209], v154 offset:39936
	global_load_lds_dwordx4 v[210:211], off
	v_lshl_add_u64 v[210:211], s[16:17], 0, v[132:133]
	s_mov_b32 m0, s22
	s_nop 0
	global_load_lds_dwordx4 v[210:211], off
	s_waitcnt lgkmcnt(8)
	s_barrier
	s_waitcnt lgkmcnt(0)
	v_mfma_f32_16x16x32_bf16 v[124:127], v[160:163], v[176:179], v[124:127]
	v_mfma_f32_16x16x32_bf16 v[120:123], v[168:171], v[176:179], v[120:123]
	v_mfma_f32_16x16x32_bf16 v[108:111], v[160:163], v[184:187], v[108:111]
	v_mfma_f32_16x16x32_bf16 v[104:107], v[168:171], v[184:187], v[104:107]
	v_mfma_f32_16x16x32_bf16 v[92:95], v[160:163], v[192:195], v[92:95]
	v_mfma_f32_16x16x32_bf16 v[88:91], v[168:171], v[192:195], v[88:91]
	v_mfma_f32_16x16x32_bf16 v[76:79], v[160:163], v[202:205], v[76:79]
	v_mfma_f32_16x16x32_bf16 v[72:75], v[168:171], v[202:205], v[72:75]
	v_mfma_f32_16x16x32_bf16 v[124:127], v[164:167], v[180:183], v[124:127]
	v_mfma_f32_16x16x32_bf16 v[120:123], v[172:175], v[180:183], v[120:123]
	v_mfma_f32_16x16x32_bf16 v[108:111], v[164:167], v[188:191], v[108:111]
	v_mfma_f32_16x16x32_bf16 v[104:107], v[172:175], v[188:191], v[104:107]
	v_mfma_f32_16x16x32_bf16 v[92:95], v[164:167], v[198:201], v[92:95]
	v_mfma_f32_16x16x32_bf16 v[88:91], v[172:175], v[198:201], v[88:91]
	v_mfma_f32_16x16x32_bf16 v[76:79], v[164:167], v[206:209], v[76:79]
	v_mfma_f32_16x16x32_bf16 v[72:75], v[172:175], v[206:209], v[72:75]
	s_barrier
	s_add_i32 s16, s35, s18
	v_lshl_add_u64 v[144:145], v[144:145], 0, s[46:47]
	s_mov_b32 m0, s16
	ds_read_b128 v[210:213], v157
	ds_read_b128 v[214:217], v157 offset:1024
	ds_read_b128 v[218:221], v157 offset:2048
	ds_read_b128 v[222:225], v157 offset:3072
	global_load_lds_dwordx4 v[144:145], off
	v_lshl_add_u64 v[144:145], v[226:227], 0, s[46:47]
	s_add_i32 m0, s16, 0x2000
	s_nop 0
	global_load_lds_dwordx4 v[144:145], off
	s_barrier
; #define LAS __attribute__((address_space(3)))
; #define PG8_STAGE(bufoff, gbase, voff) do { _Pragma("unroll") for (int _i = 0; _i < 2; ++_i) \
;         __builtin_amdgcn_global_load_lds((const unsigned*)((const char*)(gbase) + (voff)[_i]), (LAS unsigned*)(lds + (bufoff) + ldsw + _i * 8192), 16, 0, 0); } while (0)
; #define PG8_LDA(dst, b, h) do { _Pragma("unroll") for (int m = 0; m < 4; ++m) _Pragma("unroll") for (int k = 0; k < 2; ++k) dst[m][k] = *(const LAS bf16x8*)(lds + PG8_SA(b, h) + aoff + m * 2048 + k * 1024); } while (0)
; #define PG8_MMA(ai, bj, At, Bt) do { __builtin_amdgcn_s_setprio(1); _Pragma("unroll") for (int m = 0; m < 4; ++m) _Pragma("unroll") for (int n = 0; n < 2; ++n) _Pragma("unroll") for (int k = 0; k < 2; ++k) \
;         acc[ai][bj][m][n] = __builtin_amdgcn_mfma_f32_16x16x32_bf16(Bt[n][k], At[m][k], acc[ai][bj][m][n], 0, 0, 0); __builtin_amdgcn_s_setprio(0); } while (0)
; #define PG8_WAIT_V(n) asm volatile("s_waitcnt vmcnt(" #n ")" ::: "memory")
; #define PG8_WAIT_L(n) asm volatile("s_waitcnt lgkmcnt(" #n ")" ::: "memory")
; #define PG8_BAR __builtin_amdgcn_s_barrier()
; #define PG8_SCHED __builtin_amdgcn_sched_barrier(0)
; template <class Epi>
; DEVI void gemm_phase(LAS unsigned char* lds, const bf16_t* gA, const bf16_t* gBt, const int lda, const int ldb, const int K, const StaticOrder S_, const Epi E) {
;     ...
;             PG8_BAR; PG8_WAIT_L(0); PG8_MMA(0, 1, At, B1); PG8_BAR;
;             PG8_LDA(At, 1, 1); PG8_STAGE(PG8_SA(1, 0), a3, voffA);
;             PG8_BAR; PG8_WAIT_L(0); PG8_MMA(1, 0, At, B0); PG8_BAR; PG8_SCHED;
;             PG8_STAGE(PG8_SB(1, 1), b3 + hstepB, voffB);
;             PG8_WAIT_V(6); PG8_BAR; PG8_MMA(1, 1, At, B1); PG8_BAR;
;         }
;         E(acc, cur, wr, wc, fr, fq, (const LAS float*)(lds + STAGE_BYTES + (ui & 1) * 2048));
	s_waitcnt lgkmcnt(0)
	v_mfma_f32_16x16x32_bf16 v[116:119], v[210:213], v[176:179], v[116:119]
	v_mfma_f32_16x16x32_bf16 v[112:115], v[218:221], v[176:179], v[112:115]
	v_mfma_f32_16x16x32_bf16 v[100:103], v[210:213], v[184:187], v[100:103]
	v_mfma_f32_16x16x32_bf16 v[96:99], v[218:221], v[184:187], v[96:99]
	v_mfma_f32_16x16x32_bf16 v[84:87], v[210:213], v[192:195], v[84:87]
	v_mfma_f32_16x16x32_bf16 v[80:83], v[218:221], v[192:195], v[80:83]
	v_mfma_f32_16x16x32_bf16 v[68:71], v[210:213], v[202:205], v[68:71]
	v_mfma_f32_16x16x32_bf16 v[64:67], v[218:221], v[202:205], v[64:67]
	v_mfma_f32_16x16x32_bf16 v[116:119], v[214:217], v[180:183], v[116:119]
	v_mfma_f32_16x16x32_bf16 v[112:115], v[222:225], v[180:183], v[112:115]
	v_mfma_f32_16x16x32_bf16 v[100:103], v[214:217], v[188:191], v[100:103]
	v_mfma_f32_16x16x32_bf16 v[96:99], v[222:225], v[188:191], v[96:99]
	v_mfma_f32_16x16x32_bf16 v[84:87], v[214:217], v[198:201], v[84:87]
	v_mfma_f32_16x16x32_bf16 v[80:83], v[222:225], v[198:201], v[80:83]
	v_mfma_f32_16x16x32_bf16 v[68:71], v[214:217], v[206:209], v[68:71]
	v_mfma_f32_16x16x32_bf16 v[64:67], v[222:225], v[206:209], v[64:67]
	s_mov_b32 m0, s23
	v_lshl_add_u64 v[144:145], v[228:229], 0, s[46:47]
	s_barrier
	ds_read_b128 v[176:179], v154 offset:49152
	ds_read_b128 v[180:183], v154 offset:50176
	ds_read_b128 v[184:187], v154 offset:51200
	ds_read_b128 v[188:191], v154 offset:52224
	ds_read_b128 v[192:195], v154 offset:53248
	ds_read_b128 v[198:201], v154 offset:54272
	ds_read_b128 v[202:205], v154 offset:55296
	ds_read_b128 v[206:209], v154 offset:56320
	global_load_lds_dwordx4 v[144:145], off
	v_lshl_add_u64 v[144:145], v[230:231], 0, s[46:47]
	s_mov_b32 m0, s24
	s_nop 0
	global_load_lds_dwordx4 v[144:145], off
	s_barrier
	s_waitcnt lgkmcnt(0)
	v_mfma_f32_16x16x32_bf16 v[60:63], v[160:163], v[176:179], v[60:63]
	v_mfma_f32_16x16x32_bf16 v[56:59], v[168:171], v[176:179], v[56:59]
	v_mfma_f32_16x16x32_bf16 v[44:47], v[160:163], v[184:187], v[44:47]
	v_mfma_f32_16x16x32_bf16 v[40:43], v[168:171], v[184:187], v[40:43]
	v_mfma_f32_16x16x32_bf16 v[28:31], v[160:163], v[192:195], v[28:31]
	v_mfma_f32_16x16x32_bf16 v[24:27], v[168:171], v[192:195], v[24:27]
	v_mfma_f32_16x16x32_bf16 v[12:15], v[160:163], v[202:205], v[12:15]
	v_mfma_f32_16x16x32_bf16 v[8:11], v[168:171], v[202:205], v[8:11]
	v_mfma_f32_16x16x32_bf16 v[60:63], v[164:167], v[180:183], v[60:63]
	v_mfma_f32_16x16x32_bf16 v[56:59], v[172:175], v[180:183], v[56:59]
	v_mfma_f32_16x16x32_bf16 v[44:47], v[164:167], v[188:191], v[44:47]
	v_mfma_f32_16x16x32_bf16 v[40:43], v[172:175], v[188:191], v[40:43]
	v_mfma_f32_16x16x32_bf16 v[28:31], v[164:167], v[198:201], v[28:31]
	v_mfma_f32_16x16x32_bf16 v[24:27], v[172:175], v[198:201], v[24:27]
	v_mfma_f32_16x16x32_bf16 v[12:15], v[164:167], v[206:209], v[12:15]
	v_mfma_f32_16x16x32_bf16 v[8:11], v[172:175], v[206:209], v[8:11]
	s_barrier
	s_add_i32 s16, s50, s18
	v_lshl_add_u64 v[144:145], v[232:233], 0, s[46:47]
	s_mov_b32 m0, s16
	s_nop 0
	global_load_lds_dwordx4 v[144:145], off
	v_lshl_add_u64 v[144:145], v[234:235], 0, s[46:47]
	s_add_i32 m0, s16, 0x2000
	s_nop 0
	global_load_lds_dwordx4 v[144:145], off
	s_waitcnt vmcnt(6)
	s_barrier
	v_mfma_f32_16x16x32_bf16 v[52:55], v[210:213], v[176:179], v[52:55]
	v_mfma_f32_16x16x32_bf16 v[48:51], v[218:221], v[176:179], v[48:51]
	v_mfma_f32_16x16x32_bf16 v[36:39], v[210:213], v[184:187], v[36:39]
	v_mfma_f32_16x16x32_bf16 v[32:35], v[218:221], v[184:187], v[32:35]
	v_mfma_f32_16x16x32_bf16 v[20:23], v[210:213], v[192:195], v[20:23]
	v_mfma_f32_16x16x32_bf16 v[16:19], v[218:221], v[192:195], v[16:19]
	v_mfma_f32_16x16x32_bf16 v[4:7], v[210:213], v[202:205], v[4:7]
	v_mfma_f32_16x16x32_bf16 v[0:3], v[218:221], v[202:205], v[0:3]
	v_mfma_f32_16x16x32_bf16 v[52:55], v[214:217], v[180:183], v[52:55]
	v_mfma_f32_16x16x32_bf16 v[48:51], v[222:225], v[180:183], v[48:51]
	v_mfma_f32_16x16x32_bf16 v[36:39], v[214:217], v[188:191], v[36:39]
	v_mfma_f32_16x16x32_bf16 v[32:35], v[222:225], v[188:191], v[32:35]
	v_mfma_f32_16x16x32_bf16 v[20:23], v[214:217], v[198:201], v[20:23]
	v_mfma_f32_16x16x32_bf16 v[16:19], v[222:225], v[198:201], v[16:19]
	v_mfma_f32_16x16x32_bf16 v[4:7], v[214:217], v[206:209], v[4:7]
	v_mfma_f32_16x16x32_bf16 v[0:3], v[222:225], v[206:209], v[0:3]
	s_add_u32 s14, s14, 0x100
	s_addc_u32 s15, s15, 0
	s_add_u32 s68, s68, 0x100
	s_addc_u32 s69, s69, 0
	s_cmp_ge_i32 s77, s25
	s_mov_b32 s16, s77
	s_barrier
	s_cbranch_scc0 .LBB0_519
	v_readlane_b32 s78, v240, 54
	v_readlane_b32 s79, v240, 55

; #define PG8_STAGE(bufoff, gbase, voff) do { _Pragma("unroll") for (int _i = 0; _i < 2; ++_i) \
;         __builtin_amdgcn_global_load_lds((const unsigned*)((const char*)(gbase) + (voff)[_i]), (LAS unsigned*)(lds + (bufoff) + ldsw + _i * 8192), 16, 0, 0); } while (0)
; #define PG8_LDA(dst, b, h) do { _Pragma("unroll") for (int m = 0; m < 4; ++m) _Pragma("unroll") for (int k = 0; k < 2; ++k) dst[m][k] = *(const LAS bf16x8*)(lds + PG8_SA(b, h) + aoff + m * 2048 + k * 1024); } while (0)
; #define PG8_LDB(dst, b, h) do { _Pragma("unroll") for (int n = 0; n < 2; ++n) _Pragma("unroll") for (int k = 0; k < 2; ++k) dst[n][k] = *(const LAS bf16x8*)(lds + PG8_SB(b, h) + boff + n * 2048 + k * 1024); } while (0)
; #define PG8_MMA(ai, bj, At, Bt) do { __builtin_amdgcn_s_setprio(1); _Pragma("unroll") for (int m = 0; m < 4; ++m) _Pragma("unroll") for (int n = 0; n < 2; ++n) _Pragma("unroll") for (int k = 0; k < 2; ++k) \
;         acc[ai][bj][m][n] = __builtin_amdgcn_mfma_f32_16x16x32_bf16(Bt[n][k], At[m][k], acc[ai][bj][m][n], 0, 0, 0); __builtin_amdgcn_s_setprio(0); } while (0)
; #define PG8_WAIT_L(n) asm volatile("s_waitcnt lgkmcnt(" #n ")" ::: "memory")
; #define PG8_BAR __builtin_amdgcn_s_barrier()
; #define PG8_SCHED __builtin_amdgcn_sched_barrier(0)
; template <class Epi>
; DEVI void gemm_phase(LAS unsigned char* lds, const bf16_t* gA, const bf16_t* gBt, const int lda, const int ldb, const int K, const StaticOrder S_, const Epi E) {
;     ...
;             const bool last = (t == nt - 2);
;             const char* a1 = cA + (size_t)(t + 1) * kstep;
;             const char* a2 = last ? nA : cA + (size_t)(t + 2) * kstep; const char* b2 = last ? nB : cB + (size_t)(t + 2) * kstep;
;             const char* a3 = a2 + kstep; const char* b3 = b2 + kstep;
;             PG8_LDB(B0, 0, 0); PG8_SCHED; PG8_LDA(At, 0, 0); PG8_STAGE(PG8_SA(1, 1), a1 + hstepA, voffA);
;             PG8_WAIT_L(8); PG8_BAR; PG8_WAIT_L(0); PG8_MMA(0, 0, At, B0); PG8_BAR; PG8_SCHED;
;             PG8_LDB(B1, 0, 1); PG8_STAGE(PG8_SB(0, 0), b2, voffB);
;             PG8_BAR; PG8_WAIT_L(0); PG8_MMA(0, 1, At, B1); PG8_BAR;
;             PG8_LDA(At, 0, 1); PG8_STAGE(PG8_SA(0, 0), a2, voffA);
;             PG8_BAR; PG8_WAIT_L(0); PG8_MMA(1, 0, At, B0); PG8_BAR; PG8_SCHED;
.LBB0_744:
	ds_read_b128 v[160:163], v153
	ds_read_b128 v[164:167], v153 offset:1024
	ds_read_b128 v[168:171], v153 offset:2048
	ds_read_b128 v[172:175], v153 offset:3072
	s_add_i32 s77, s16, 2
	s_add_u32 s40, s14, 0x80
	s_addc_u32 s17, s15, 0
	s_cmp_eq_u32 s26, s16
	s_cselect_b32 s16, s48, s40
	s_cselect_b32 s17, s49, s17
	s_cselect_b32 s41, s61, s65
	s_cselect_b32 s40, s60, s64
	v_lshl_add_u64 v[144:145], s[14:15], 0, v[138:139]
	s_add_i32 m0, s19, 0xc000
	ds_read_b128 v[176:179], v154
	ds_read_b128 v[180:183], v154 offset:1024
	ds_read_b128 v[184:187], v154 offset:2048
	ds_read_b128 v[188:191], v154 offset:3072
	ds_read_b128 v[192:195], v154 offset:4096
	ds_read_b128 v[198:201], v154 offset:5120
	ds_read_b128 v[202:205], v154 offset:6144
	ds_read_b128 v[206:209], v154 offset:7168
	global_load_lds_dwordx4 v[144:145], off
	v_lshl_add_u64 v[144:145], s[14:15], 0, v[140:141]
	s_add_i32 m0, s19, 0xe000
	s_nop 0
	global_load_lds_dwordx4 v[144:145], off
	s_waitcnt lgkmcnt(8)
	s_barrier
	s_waitcnt lgkmcnt(0)
	v_mfma_f32_16x16x32_bf16 v[124:127], v[160:163], v[176:179], v[124:127]
	v_mfma_f32_16x16x32_bf16 v[120:123], v[168:171], v[176:179], v[120:123]
	v_mfma_f32_16x16x32_bf16 v[108:111], v[160:163], v[184:187], v[108:111]
	v_mfma_f32_16x16x32_bf16 v[104:107], v[168:171], v[184:187], v[104:107]
	v_mfma_f32_16x16x32_bf16 v[92:95], v[160:163], v[192:195], v[92:95]
	v_mfma_f32_16x16x32_bf16 v[88:91], v[168:171], v[192:195], v[88:91]
	v_mfma_f32_16x16x32_bf16 v[76:79], v[160:163], v[202:205], v[76:79]
	v_mfma_f32_16x16x32_bf16 v[72:75], v[168:171], v[202:205], v[72:75]
	v_mfma_f32_16x16x32_bf16 v[124:127], v[164:167], v[180:183], v[124:127]
	v_mfma_f32_16x16x32_bf16 v[120:123], v[172:175], v[180:183], v[120:123]
	v_mfma_f32_16x16x32_bf16 v[108:111], v[164:167], v[188:191], v[108:111]
	v_mfma_f32_16x16x32_bf16 v[104:107], v[172:175], v[188:191], v[104:107]
	v_mfma_f32_16x16x32_bf16 v[92:95], v[164:167], v[198:201], v[92:95]
	v_mfma_f32_16x16x32_bf16 v[88:91], v[172:175], v[198:201], v[88:91]
	v_mfma_f32_16x16x32_bf16 v[76:79], v[164:167], v[206:209], v[76:79]
	v_mfma_f32_16x16x32_bf16 v[72:75], v[172:175], v[206:209], v[72:75]
	s_barrier
	s_add_i32 s78, s31, s18
	v_lshl_add_u64 v[144:145], s[40:41], 0, v[130:131]
	s_mov_b32 m0, s78
	ds_read_b128 v[210:213], v155
	ds_read_b128 v[214:217], v155 offset:1024
	ds_read_b128 v[218:221], v155 offset:2048
	ds_read_b128 v[222:225], v155 offset:3072
	global_load_lds_dwordx4 v[144:145], off
	v_lshl_add_u64 v[226:227], s[40:41], 0, v[134:135]
	s_add_i32 m0, s78, 0x2000
	s_nop 0
	global_load_lds_dwordx4 v[226:227], off
	s_barrier
	s_waitcnt lgkmcnt(0)
	v_mfma_f32_16x16x32_bf16 v[116:119], v[210:213], v[176:179], v[116:119]
	v_mfma_f32_16x16x32_bf16 v[112:115], v[218:221], v[176:179], v[112:115]
	v_mfma_f32_16x16x32_bf16 v[100:103], v[210:213], v[184:187], v[100:103]
	v_mfma_f32_16x16x32_bf16 v[96:99], v[218:221], v[184:187], v[96:99]
	v_mfma_f32_16x16x32_bf16 v[84:87], v[210:213], v[192:195], v[84:87]
	v_mfma_f32_16x16x32_bf16 v[80:83], v[218:221], v[192:195], v[80:83]
	v_mfma_f32_16x16x32_bf16 v[68:71], v[210:213], v[202:205], v[68:71]
	v_mfma_f32_16x16x32_bf16 v[64:67], v[218:221], v[202:205], v[64:67]
	v_mfma_f32_16x16x32_bf16 v[116:119], v[214:217], v[180:183], v[116:119]
	v_mfma_f32_16x16x32_bf16 v[112:115], v[222:225], v[180:183], v[112:115]
	v_mfma_f32_16x16x32_bf16 v[100:103], v[214:217], v[188:191], v[100:103]
	v_mfma_f32_16x16x32_bf16 v[96:99], v[222:225], v[188:191], v[96:99]
	v_mfma_f32_16x16x32_bf16 v[84:87], v[214:217], v[198:201], v[84:87]
	v_mfma_f32_16x16x32_bf16 v[80:83], v[222:225], v[198:201], v[80:83]
	v_mfma_f32_16x16x32_bf16 v[68:71], v[214:217], v[206:209], v[68:71]
	v_mfma_f32_16x16x32_bf16 v[64:67], v[222:225], v[206:209], v[64:67]
	s_mov_b32 m0, s19
	v_lshl_add_u64 v[228:229], s[16:17], 0, v[128:129]
	s_barrier
	ds_read_b128 v[176:179], v154 offset:16384
	ds_read_b128 v[180:183], v154 offset:17408
	ds_read_b128 v[184:187], v154 offset:18432
	ds_read_b128 v[188:191], v154 offset:19456
	ds_read_b128 v[192:195], v154 offset:20480
	ds_read_b128 v[198:201], v154 offset:21504
	ds_read_b128 v[202:205], v154 offset:22528
	ds_read_b128 v[206:209], v154 offset:23552
	global_load_lds_dwordx4 v[228:229], off
	v_lshl_add_u64 v[230:231], s[16:17], 0, v[132:133]
	s_mov_b32 m0, s20
	s_nop 0
	global_load_lds_dwordx4 v[230:231], off
	s_barrier
	s_waitcnt lgkmcnt(0)
	v_mfma_f32_16x16x32_bf16 v[60:63], v[160:163], v[176:179], v[60:63]
	v_mfma_f32_16x16x32_bf16 v[56:59], v[168:171], v[176:179], v[56:59]
	v_mfma_f32_16x16x32_bf16 v[44:47], v[160:163], v[184:187], v[44:47]
	v_mfma_f32_16x16x32_bf16 v[40:43], v[168:171], v[184:187], v[40:43]
	v_mfma_f32_16x16x32_bf16 v[28:31], v[160:163], v[192:195], v[28:31]
	v_mfma_f32_16x16x32_bf16 v[24:27], v[168:171], v[192:195], v[24:27]
	v_mfma_f32_16x16x32_bf16 v[12:15], v[160:163], v[202:205], v[12:15]
	v_mfma_f32_16x16x32_bf16 v[8:11], v[168:171], v[202:205], v[8:11]
	v_mfma_f32_16x16x32_bf16 v[60:63], v[164:167], v[180:183], v[60:63]
	v_mfma_f32_16x16x32_bf16 v[56:59], v[172:175], v[180:183], v[56:59]
	v_mfma_f32_16x16x32_bf16 v[44:47], v[164:167], v[188:191], v[44:47]
	v_mfma_f32_16x16x32_bf16 v[40:43], v[172:175], v[188:191], v[40:43]
	v_mfma_f32_16x16x32_bf16 v[28:31], v[164:167], v[198:201], v[28:31]
	v_mfma_f32_16x16x32_bf16 v[24:27], v[172:175], v[198:201], v[24:27]
	v_mfma_f32_16x16x32_bf16 v[12:15], v[164:167], v[206:209], v[12:15]
	v_mfma_f32_16x16x32_bf16 v[8:11], v[172:175], v[206:209], v[8:11]
	s_barrier
; #define PG8_STAGE(bufoff, gbase, voff) do { _Pragma("unroll") for (int _i = 0; _i < 2; ++_i) \
;         __builtin_amdgcn_global_load_lds((const unsigned*)((const char*)(gbase) + (voff)[_i]), (LAS unsigned*)(lds + (bufoff) + ldsw + _i * 8192), 16, 0, 0); } while (0)
; #define PG8_LDA(dst, b, h) do { _Pragma("unroll") for (int m = 0; m < 4; ++m) _Pragma("unroll") for (int k = 0; k < 2; ++k) dst[m][k] = *(const LAS bf16x8*)(lds + PG8_SA(b, h) + aoff + m * 2048 + k * 1024); } while (0)
; #define PG8_LDB(dst, b, h) do { _Pragma("unroll") for (int n = 0; n < 2; ++n) _Pragma("unroll") for (int k = 0; k < 2; ++k) dst[n][k] = *(const LAS bf16x8*)(lds + PG8_SB(b, h) + boff + n * 2048 + k * 1024); } while (0)
; #define PG8_MMA(ai, bj, At, Bt) do { __builtin_amdgcn_s_setprio(1); _Pragma("unroll") for (int m = 0; m < 4; ++m) _Pragma("unroll") for (int n = 0; n < 2; ++n) _Pragma("unroll") for (int k = 0; k < 2; ++k) \
;         acc[ai][bj][m][n] = __builtin_amdgcn_mfma_f32_16x16x32_bf16(Bt[n][k], At[m][k], acc[ai][bj][m][n], 0, 0, 0); __builtin_amdgcn_s_setprio(0); } while (0)
; #define PG8_WAIT_V(n) asm volatile("s_waitcnt vmcnt(" #n ")" ::: "memory")
; #define PG8_WAIT_L(n) asm volatile("s_waitcnt lgkmcnt(" #n ")" ::: "memory")
; #define PG8_BAR __builtin_amdgcn_s_barrier()
; #define PG8_SCHED __builtin_amdgcn_sched_barrier(0)
; template <class Epi>
; DEVI void gemm_phase(LAS unsigned char* lds, const bf16_t* gA, const bf16_t* gBt, const int lda, const int ldb, const int K, const StaticOrder S_, const Epi E) {
;     ...
;             PG8_STAGE(PG8_SB(0, 1), b2 + hstepB, voffB);
;             PG8_WAIT_V(6); PG8_BAR; PG8_MMA(1, 1, At, B1); PG8_BAR;
;             PG8_LDB(B0, 1, 0); PG8_SCHED; PG8_LDA(At, 1, 0); PG8_STAGE(PG8_SA(0, 1), a2 + hstepA, voffA);
;             PG8_WAIT_L(8); PG8_BAR; PG8_WAIT_L(0); PG8_MMA(0, 0, At, B0); PG8_BAR; PG8_SCHED;
;             PG8_LDB(B1, 1, 1); PG8_STAGE(PG8_SB(1, 0), b3, voffB);
	s_add_u32 s40, s40, s2
	s_addc_u32 s41, s41, s3
	s_add_i32 s78, s34, s18
	v_lshl_add_u64 v[232:233], s[40:41], 0, v[130:131]
	s_mov_b32 m0, s78
	v_lshl_add_u64 v[234:235], s[40:41], 0, v[134:135]
	global_load_lds_dwordx4 v[232:233], off
	s_add_i32 m0, s78, 0x2000
	s_nop 0
	global_load_lds_dwordx4 v[234:235], off
	s_waitcnt vmcnt(6)
	s_barrier
	v_mfma_f32_16x16x32_bf16 v[52:55], v[210:213], v[176:179], v[52:55]
	v_mfma_f32_16x16x32_bf16 v[48:51], v[218:221], v[176:179], v[48:51]
	v_mfma_f32_16x16x32_bf16 v[36:39], v[210:213], v[184:187], v[36:39]
	v_mfma_f32_16x16x32_bf16 v[32:35], v[218:221], v[184:187], v[32:35]
	v_mfma_f32_16x16x32_bf16 v[20:23], v[210:213], v[192:195], v[20:23]
	v_mfma_f32_16x16x32_bf16 v[16:19], v[218:221], v[192:195], v[16:19]
	v_mfma_f32_16x16x32_bf16 v[4:7], v[210:213], v[202:205], v[4:7]
	v_mfma_f32_16x16x32_bf16 v[0:3], v[218:221], v[202:205], v[0:3]
	v_mfma_f32_16x16x32_bf16 v[52:55], v[214:217], v[180:183], v[52:55]
	v_mfma_f32_16x16x32_bf16 v[48:51], v[222:225], v[180:183], v[48:51]
	v_mfma_f32_16x16x32_bf16 v[36:39], v[214:217], v[188:191], v[36:39]
	v_mfma_f32_16x16x32_bf16 v[32:35], v[222:225], v[188:191], v[32:35]
	v_mfma_f32_16x16x32_bf16 v[20:23], v[214:217], v[198:201], v[20:23]
	v_mfma_f32_16x16x32_bf16 v[16:19], v[222:225], v[198:201], v[16:19]
	v_mfma_f32_16x16x32_bf16 v[4:7], v[214:217], v[206:209], v[4:7]
	v_mfma_f32_16x16x32_bf16 v[0:3], v[222:225], v[206:209], v[0:3]
	s_barrier
	ds_read_b128 v[160:163], v156
	ds_read_b128 v[164:167], v156 offset:1024
	ds_read_b128 v[168:171], v156 offset:2048
	ds_read_b128 v[172:175], v156 offset:3072
	s_add_u32 s16, s16, s0
	s_addc_u32 s17, s17, s1
	s_mov_b32 m0, s21
	v_lshl_add_u64 v[210:211], s[16:17], 0, v[128:129]
	ds_read_b128 v[176:179], v154 offset:32768
	ds_read_b128 v[180:183], v154 offset:33792
	ds_read_b128 v[184:187], v154 offset:34816
	ds_read_b128 v[188:191], v154 offset:35840
	ds_read_b128 v[192:195], v154 offset:36864
	ds_read_b128 v[198:201], v154 offset:37888
	ds_read_b128 v[202:205], v154 offset:38912
	ds_read_b128 v[206:209], v154 offset:39936
	global_load_lds_dwordx4 v[210:211], off
	v_lshl_add_u64 v[210:211], s[16:17], 0, v[132:133]
	s_mov_b32 m0, s22
	s_nop 0
	global_load_lds_dwordx4 v[210:211], off
	s_waitcnt lgkmcnt(8)
	s_barrier
	s_waitcnt lgkmcnt(0)
	v_mfma_f32_16x16x32_bf16 v[124:127], v[160:163], v[176:179], v[124:127]
	v_mfma_f32_16x16x32_bf16 v[120:123], v[168:171], v[176:179], v[120:123]
	v_mfma_f32_16x16x32_bf16 v[108:111], v[160:163], v[184:187], v[108:111]
	v_mfma_f32_16x16x32_bf16 v[104:107], v[168:171], v[184:187], v[104:107]
	v_mfma_f32_16x16x32_bf16 v[92:95], v[160:163], v[192:195], v[92:95]
	v_mfma_f32_16x16x32_bf16 v[88:91], v[168:171], v[192:195], v[88:91]
	v_mfma_f32_16x16x32_bf16 v[76:79], v[160:163], v[202:205], v[76:79]
	v_mfma_f32_16x16x32_bf16 v[72:75], v[168:171], v[202:205], v[72:75]
	v_mfma_f32_16x16x32_bf16 v[124:127], v[164:167], v[180:183], v[124:127]
	v_mfma_f32_16x16x32_bf16 v[120:123], v[172:175], v[180:183], v[120:123]
	v_mfma_f32_16x16x32_bf16 v[108:111], v[164:167], v[188:191], v[108:111]
	v_mfma_f32_16x16x32_bf16 v[104:107], v[172:175], v[188:191], v[104:107]
	v_mfma_f32_16x16x32_bf16 v[92:95], v[164:167], v[198:201], v[92:95]
	v_mfma_f32_16x16x32_bf16 v[88:91], v[172:175], v[198:201], v[88:91]
	v_mfma_f32_16x16x32_bf16 v[76:79], v[164:167], v[206:209], v[76:79]
	v_mfma_f32_16x16x32_bf16 v[72:75], v[172:175], v[206:209], v[72:75]
	s_barrier
	s_add_i32 s16, s35, s18
	v_lshl_add_u64 v[144:145], v[144:145], 0, s[46:47]
	s_mov_b32 m0, s16
	ds_read_b128 v[210:213], v157
	ds_read_b128 v[214:217], v157 offset:1024
	ds_read_b128 v[218:221], v157 offset:2048
	ds_read_b128 v[222:225], v157 offset:3072
	global_load_lds_dwordx4 v[144:145], off
	v_lshl_add_u64 v[144:145], v[226:227], 0, s[46:47]
	s_add_i32 m0, s16, 0x2000
	s_nop 0
	global_load_lds_dwordx4 v[144:145], off
	s_barrier
; #define LAS __attribute__((address_space(3)))
; #define PG8_STAGE(bufoff, gbase, voff) do { _Pragma("unroll") for (int _i = 0; _i < 2; ++_i) \
;         __builtin_amdgcn_global_load_lds((const unsigned*)((const char*)(gbase) + (voff)[_i]), (LAS unsigned*)(lds + (bufoff) + ldsw + _i * 8192), 16, 0, 0); } while (0)
; #define PG8_LDA(dst, b, h) do { _Pragma("unroll") for (int m = 0; m < 4; ++m) _Pragma("unroll") for (int k = 0; k < 2; ++k) dst[m][k] = *(const LAS bf16x8*)(lds + PG8_SA(b, h) + aoff + m * 2048 + k * 1024); } while (0)
; #define PG8_MMA(ai, bj, At, Bt) do { __builtin_amdgcn_s_setprio(1); _Pragma("unroll") for (int m = 0; m < 4; ++m) _Pragma("unroll") for (int n = 0; n < 2; ++n) _Pragma("unroll") for (int k = 0; k < 2; ++k) \
;         acc[ai][bj][m][n] = __builtin_amdgcn_mfma_f32_16x16x32_bf16(Bt[n][k], At[m][k], acc[ai][bj][m][n], 0, 0, 0); __builtin_amdgcn_s_setprio(0); } while (0)
; #define PG8_WAIT_V(n) asm volatile("s_waitcnt vmcnt(" #n ")" ::: "memory")
; #define PG8_WAIT_L(n) asm volatile("s_waitcnt lgkmcnt(" #n ")" ::: "memory")
; #define PG8_BAR __builtin_amdgcn_s_barrier()
; #define PG8_SCHED __builtin_amdgcn_sched_barrier(0)
; template <class Epi>
; DEVI void gemm_phase(LAS unsigned char* lds, const bf16_t* gA, const bf16_t* gBt, const int lda, const int ldb, const int K, const StaticOrder S_, const Epi E) {
;     ...
;             PG8_BAR; PG8_WAIT_L(0); PG8_MMA(0, 1, At, B1); PG8_BAR;
;             PG8_LDA(At, 1, 1); PG8_STAGE(PG8_SA(1, 0), a3, voffA);
;             PG8_BAR; PG8_WAIT_L(0); PG8_MMA(1, 0, At, B0); PG8_BAR; PG8_SCHED;
;             PG8_STAGE(PG8_SB(1, 1), b3 + hstepB, voffB);
;             PG8_WAIT_V(6); PG8_BAR; PG8_MMA(1, 1, At, B1); PG8_BAR;
;         }
;         E(acc, cur, wr, wc, fr, fq, (const LAS float*)(lds + STAGE_BYTES + (ui & 1) * 2048));
	s_waitcnt lgkmcnt(0)
	v_mfma_f32_16x16x32_bf16 v[116:119], v[210:213], v[176:179], v[116:119]
	v_mfma_f32_16x16x32_bf16 v[112:115], v[218:221], v[176:179], v[112:115]
	v_mfma_f32_16x16x32_bf16 v[100:103], v[210:213], v[184:187], v[100:103]
	v_mfma_f32_16x16x32_bf16 v[96:99], v[218:221], v[184:187], v[96:99]
	v_mfma_f32_16x16x32_bf16 v[84:87], v[210:213], v[192:195], v[84:87]
	v_mfma_f32_16x16x32_bf16 v[80:83], v[218:221], v[192:195], v[80:83]
	v_mfma_f32_16x16x32_bf16 v[68:71], v[210:213], v[202:205], v[68:71]
	v_mfma_f32_16x16x32_bf16 v[64:67], v[218:221], v[202:205], v[64:67]
	v_mfma_f32_16x16x32_bf16 v[116:119], v[214:217], v[180:183], v[116:119]
	v_mfma_f32_16x16x32_bf16 v[112:115], v[222:225], v[180:183], v[112:115]
	v_mfma_f32_16x16x32_bf16 v[100:103], v[214:217], v[188:191], v[100:103]
	v_mfma_f32_16x16x32_bf16 v[96:99], v[222:225], v[188:191], v[96:99]
	v_mfma_f32_16x16x32_bf16 v[84:87], v[214:217], v[198:201], v[84:87]
	v_mfma_f32_16x16x32_bf16 v[80:83], v[222:225], v[198:201], v[80:83]
	v_mfma_f32_16x16x32_bf16 v[68:71], v[214:217], v[206:209], v[68:71]
	v_mfma_f32_16x16x32_bf16 v[64:67], v[222:225], v[206:209], v[64:67]
	s_mov_b32 m0, s23
	v_lshl_add_u64 v[144:145], v[228:229], 0, s[46:47]
	s_barrier
	ds_read_b128 v[176:179], v154 offset:49152
	ds_read_b128 v[180:183], v154 offset:50176
	ds_read_b128 v[184:187], v154 offset:51200
	ds_read_b128 v[188:191], v154 offset:52224
	ds_read_b128 v[192:195], v154 offset:53248
	ds_read_b128 v[198:201], v154 offset:54272
	ds_read_b128 v[202:205], v154 offset:55296
	ds_read_b128 v[206:209], v154 offset:56320
	global_load_lds_dwordx4 v[144:145], off
	v_lshl_add_u64 v[144:145], v[230:231], 0, s[46:47]
	s_mov_b32 m0, s24
	s_nop 0
	global_load_lds_dwordx4 v[144:145], off
	s_barrier
	s_waitcnt lgkmcnt(0)
	v_mfma_f32_16x16x32_bf16 v[60:63], v[160:163], v[176:179], v[60:63]
	v_mfma_f32_16x16x32_bf16 v[56:59], v[168:171], v[176:179], v[56:59]
	v_mfma_f32_16x16x32_bf16 v[44:47], v[160:163], v[184:187], v[44:47]
	v_mfma_f32_16x16x32_bf16 v[40:43], v[168:171], v[184:187], v[40:43]
	v_mfma_f32_16x16x32_bf16 v[28:31], v[160:163], v[192:195], v[28:31]
	v_mfma_f32_16x16x32_bf16 v[24:27], v[168:171], v[192:195], v[24:27]
	v_mfma_f32_16x16x32_bf16 v[12:15], v[160:163], v[202:205], v[12:15]
	v_mfma_f32_16x16x32_bf16 v[8:11], v[168:171], v[202:205], v[8:11]
	v_mfma_f32_16x16x32_bf16 v[60:63], v[164:167], v[180:183], v[60:63]
	v_mfma_f32_16x16x32_bf16 v[56:59], v[172:175], v[180:183], v[56:59]
	v_mfma_f32_16x16x32_bf16 v[44:47], v[164:167], v[188:191], v[44:47]
	v_mfma_f32_16x16x32_bf16 v[40:43], v[172:175], v[188:191], v[40:43]
	v_mfma_f32_16x16x32_bf16 v[28:31], v[164:167], v[198:201], v[28:31]
	v_mfma_f32_16x16x32_bf16 v[24:27], v[172:175], v[198:201], v[24:27]
	v_mfma_f32_16x16x32_bf16 v[12:15], v[164:167], v[206:209], v[12:15]
	v_mfma_f32_16x16x32_bf16 v[8:11], v[172:175], v[206:209], v[8:11]
	s_barrier
	s_add_i32 s16, s50, s18
	v_lshl_add_u64 v[144:145], v[232:233], 0, s[46:47]
	s_mov_b32 m0, s16
	s_nop 0
	global_load_lds_dwordx4 v[144:145], off
	v_lshl_add_u64 v[144:145], v[234:235], 0, s[46:47]
	s_add_i32 m0, s16, 0x2000
	s_nop 0
	global_load_lds_dwordx4 v[144:145], off
	s_waitcnt vmcnt(6)
	s_barrier
	v_mfma_f32_16x16x32_bf16 v[52:55], v[210:213], v[176:179], v[52:55]
	v_mfma_f32_16x16x32_bf16 v[48:51], v[218:221], v[176:179], v[48:51]
	v_mfma_f32_16x16x32_bf16 v[36:39], v[210:213], v[184:187], v[36:39]
	v_mfma_f32_16x16x32_bf16 v[32:35], v[218:221], v[184:187], v[32:35]
	v_mfma_f32_16x16x32_bf16 v[20:23], v[210:213], v[192:195], v[20:23]
	v_mfma_f32_16x16x32_bf16 v[16:19], v[218:221], v[192:195], v[16:19]
	v_mfma_f32_16x16x32_bf16 v[4:7], v[210:213], v[202:205], v[4:7]
	v_mfma_f32_16x16x32_bf16 v[0:3], v[218:221], v[202:205], v[0:3]
	v_mfma_f32_16x16x32_bf16 v[52:55], v[214:217], v[180:183], v[52:55]
	v_mfma_f32_16x16x32_bf16 v[48:51], v[222:225], v[180:183], v[48:51]
	v_mfma_f32_16x16x32_bf16 v[36:39], v[214:217], v[188:191], v[36:39]
	v_mfma_f32_16x16x32_bf16 v[32:35], v[222:225], v[188:191], v[32:35]
	v_mfma_f32_16x16x32_bf16 v[20:23], v[214:217], v[198:201], v[20:23]
	v_mfma_f32_16x16x32_bf16 v[16:19], v[222:225], v[198:201], v[16:19]
	v_mfma_f32_16x16x32_bf16 v[4:7], v[214:217], v[206:209], v[4:7]
	v_mfma_f32_16x16x32_bf16 v[0:3], v[222:225], v[206:209], v[0:3]
	s_add_u32 s14, s14, 0x100
	s_addc_u32 s15, s15, 0
	s_add_u32 s64, s64, 0x100
	s_addc_u32 s65, s65, 0
	s_cmp_ge_i32 s77, s25
	s_mov_b32 s16, s77
	s_barrier
	s_cbranch_scc0 .LBB0_744
	v_readlane_b32 s78, v240, 54
	v_readlane_b32 s79, v240, 55

; #define PG8_STAGE(bufoff, gbase, voff) do { _Pragma("unroll") for (int _i = 0; _i < 2; ++_i) \
;         __builtin_amdgcn_global_load_lds((const unsigned*)((const char*)(gbase) + (voff)[_i]), (LAS unsigned*)(lds + (bufoff) + ldsw + _i * 8192), 16, 0, 0); } while (0)
; #define PG8_LDA(dst, b, h) do { _Pragma("unroll") for (int m = 0; m < 4; ++m) _Pragma("unroll") for (int k = 0; k < 2; ++k) dst[m][k] = *(const LAS bf16x8*)(lds + PG8_SA(b, h) + aoff + m * 2048 + k * 1024); } while (0)
; #define PG8_LDB(dst, b, h) do { _Pragma("unroll") for (int n = 0; n < 2; ++n) _Pragma("unroll") for (int k = 0; k < 2; ++k) dst[n][k] = *(const LAS bf16x8*)(lds + PG8_SB(b, h) + boff + n * 2048 + k * 1024); } while (0)
; #define PG8_MMA(ai, bj, At, Bt) do { __builtin_amdgcn_s_setprio(1); _Pragma("unroll") for (int m = 0; m < 4; ++m) _Pragma("unroll") for (int n = 0; n < 2; ++n) _Pragma("unroll") for (int k = 0; k < 2; ++k) \
;         acc[ai][bj][m][n] = __builtin_amdgcn_mfma_f32_16x16x32_bf16(Bt[n][k], At[m][k], acc[ai][bj][m][n], 0, 0, 0); __builtin_amdgcn_s_setprio(0); } while (0)
; #define PG8_WAIT_L(n) asm volatile("s_waitcnt lgkmcnt(" #n ")" ::: "memory")
; #define PG8_BAR __builtin_amdgcn_s_barrier()
; #define PG8_SCHED __builtin_amdgcn_sched_barrier(0)
; template <class Epi>
; DEVI void gemm_phase(LAS unsigned char* lds, const bf16_t* gA, const bf16_t* gBt, const int lda, const int ldb, const int K, const StaticOrder S_, const Epi E) {
;     ...
;             PG8_LDB(B0, 0, 0); PG8_SCHED; PG8_LDA(At, 0, 0); PG8_STAGE(PG8_SA(1, 1), a1 + hstepA, voffA);
;             PG8_WAIT_L(8); PG8_BAR; PG8_WAIT_L(0); PG8_MMA(0, 0, At, B0); PG8_BAR; PG8_SCHED;
;             PG8_LDB(B1, 0, 1); PG8_STAGE(PG8_SB(0, 0), b2, voffB);
;             PG8_BAR; PG8_WAIT_L(0); PG8_MMA(0, 1, At, B1); PG8_BAR;
;             PG8_LDA(At, 0, 1); PG8_STAGE(PG8_SA(0, 0), a2, voffA);
;             PG8_BAR; PG8_WAIT_L(0); PG8_MMA(1, 0, At, B0); PG8_BAR; PG8_SCHED;
.LBB0_800:
	ds_read_b128 v[160:163], v153
	ds_read_b128 v[164:167], v153 offset:1024
	ds_read_b128 v[168:171], v153 offset:2048
	ds_read_b128 v[172:175], v153 offset:3072
	s_add_i32 s76, s16, 2
	s_add_u32 s40, s14, 0x80
	s_addc_u32 s17, s15, 0
	s_cmp_eq_u32 s26, s16
	s_cselect_b32 s16, s48, s40
	s_cselect_b32 s17, s49, s17
	s_cselect_b32 s41, s61, s65
	s_cselect_b32 s40, s60, s64
	v_lshl_add_u64 v[144:145], s[14:15], 0, v[138:139]
	s_add_i32 m0, s19, 0xc000
	ds_read_b128 v[176:179], v154
	ds_read_b128 v[180:183], v154 offset:1024
	ds_read_b128 v[184:187], v154 offset:2048
	ds_read_b128 v[188:191], v154 offset:3072
	ds_read_b128 v[192:195], v154 offset:4096
	ds_read_b128 v[198:201], v154 offset:5120
	ds_read_b128 v[202:205], v154 offset:6144
	ds_read_b128 v[206:209], v154 offset:7168
	global_load_lds_dwordx4 v[144:145], off
	v_lshl_add_u64 v[144:145], s[14:15], 0, v[140:141]
	s_add_i32 m0, s19, 0xe000
	s_nop 0
	global_load_lds_dwordx4 v[144:145], off
	s_waitcnt lgkmcnt(8)
	s_barrier
	s_waitcnt lgkmcnt(0)
	v_mfma_f32_16x16x32_bf16 v[124:127], v[160:163], v[176:179], v[124:127]
	v_mfma_f32_16x16x32_bf16 v[120:123], v[168:171], v[176:179], v[120:123]
	v_mfma_f32_16x16x32_bf16 v[108:111], v[160:163], v[184:187], v[108:111]
	v_mfma_f32_16x16x32_bf16 v[104:107], v[168:171], v[184:187], v[104:107]
	v_mfma_f32_16x16x32_bf16 v[92:95], v[160:163], v[192:195], v[92:95]
	v_mfma_f32_16x16x32_bf16 v[88:91], v[168:171], v[192:195], v[88:91]
	v_mfma_f32_16x16x32_bf16 v[76:79], v[160:163], v[202:205], v[76:79]
	v_mfma_f32_16x16x32_bf16 v[72:75], v[168:171], v[202:205], v[72:75]
	v_mfma_f32_16x16x32_bf16 v[124:127], v[164:167], v[180:183], v[124:127]
	v_mfma_f32_16x16x32_bf16 v[120:123], v[172:175], v[180:183], v[120:123]
	v_mfma_f32_16x16x32_bf16 v[108:111], v[164:167], v[188:191], v[108:111]
	v_mfma_f32_16x16x32_bf16 v[104:107], v[172:175], v[188:191], v[104:107]
	v_mfma_f32_16x16x32_bf16 v[92:95], v[164:167], v[198:201], v[92:95]
	v_mfma_f32_16x16x32_bf16 v[88:91], v[172:175], v[198:201], v[88:91]
	v_mfma_f32_16x16x32_bf16 v[76:79], v[164:167], v[206:209], v[76:79]
	v_mfma_f32_16x16x32_bf16 v[72:75], v[172:175], v[206:209], v[72:75]
	s_barrier
	s_add_i32 s77, s31, s18
	v_lshl_add_u64 v[144:145], s[40:41], 0, v[130:131]
	s_mov_b32 m0, s77
	ds_read_b128 v[210:213], v155
	ds_read_b128 v[214:217], v155 offset:1024
	ds_read_b128 v[218:221], v155 offset:2048
	ds_read_b128 v[222:225], v155 offset:3072
	global_load_lds_dwordx4 v[144:145], off
	v_lshl_add_u64 v[226:227], s[40:41], 0, v[134:135]
	s_add_i32 m0, s77, 0x2000
	s_nop 0
	global_load_lds_dwordx4 v[226:227], off
	s_barrier
	s_waitcnt lgkmcnt(0)
	v_mfma_f32_16x16x32_bf16 v[116:119], v[210:213], v[176:179], v[116:119]
	v_mfma_f32_16x16x32_bf16 v[112:115], v[218:221], v[176:179], v[112:115]
	v_mfma_f32_16x16x32_bf16 v[100:103], v[210:213], v[184:187], v[100:103]
	v_mfma_f32_16x16x32_bf16 v[96:99], v[218:221], v[184:187], v[96:99]
	v_mfma_f32_16x16x32_bf16 v[84:87], v[210:213], v[192:195], v[84:87]
	v_mfma_f32_16x16x32_bf16 v[80:83], v[218:221], v[192:195], v[80:83]
	v_mfma_f32_16x16x32_bf16 v[68:71], v[210:213], v[202:205], v[68:71]
	v_mfma_f32_16x16x32_bf16 v[64:67], v[218:221], v[202:205], v[64:67]
	v_mfma_f32_16x16x32_bf16 v[116:119], v[214:217], v[180:183], v[116:119]
	v_mfma_f32_16x16x32_bf16 v[112:115], v[222:225], v[180:183], v[112:115]
	v_mfma_f32_16x16x32_bf16 v[100:103], v[214:217], v[188:191], v[100:103]
	v_mfma_f32_16x16x32_bf16 v[96:99], v[222:225], v[188:191], v[96:99]
	v_mfma_f32_16x16x32_bf16 v[84:87], v[214:217], v[198:201], v[84:87]
	v_mfma_f32_16x16x32_bf16 v[80:83], v[222:225], v[198:201], v[80:83]
	v_mfma_f32_16x16x32_bf16 v[68:71], v[214:217], v[206:209], v[68:71]
	v_mfma_f32_16x16x32_bf16 v[64:67], v[222:225], v[206:209], v[64:67]
	s_mov_b32 m0, s19
	v_lshl_add_u64 v[228:229], s[16:17], 0, v[128:129]
	s_barrier
	ds_read_b128 v[176:179], v154 offset:16384
	ds_read_b128 v[180:183], v154 offset:17408
	ds_read_b128 v[184:187], v154 offset:18432
	ds_read_b128 v[188:191], v154 offset:19456
	ds_read_b128 v[192:195], v154 offset:20480
	ds_read_b128 v[198:201], v154 offset:21504
	ds_read_b128 v[202:205], v154 offset:22528
	ds_read_b128 v[206:209], v154 offset:23552
	global_load_lds_dwordx4 v[228:229], off
	v_lshl_add_u64 v[230:231], s[16:17], 0, v[132:133]
	s_mov_b32 m0, s20
	s_nop 0
	global_load_lds_dwordx4 v[230:231], off
	s_barrier
	s_waitcnt lgkmcnt(0)
	v_mfma_f32_16x16x32_bf16 v[60:63], v[160:163], v[176:179], v[60:63]
	v_mfma_f32_16x16x32_bf16 v[56:59], v[168:171], v[176:179], v[56:59]
	v_mfma_f32_16x16x32_bf16 v[44:47], v[160:163], v[184:187], v[44:47]
	v_mfma_f32_16x16x32_bf16 v[40:43], v[168:171], v[184:187], v[40:43]
	v_mfma_f32_16x16x32_bf16 v[28:31], v[160:163], v[192:195], v[28:31]
	v_mfma_f32_16x16x32_bf16 v[24:27], v[168:171], v[192:195], v[24:27]
	v_mfma_f32_16x16x32_bf16 v[12:15], v[160:163], v[202:205], v[12:15]
	v_mfma_f32_16x16x32_bf16 v[8:11], v[168:171], v[202:205], v[8:11]
	v_mfma_f32_16x16x32_bf16 v[60:63], v[164:167], v[180:183], v[60:63]
	v_mfma_f32_16x16x32_bf16 v[56:59], v[172:175], v[180:183], v[56:59]
	v_mfma_f32_16x16x32_bf16 v[44:47], v[164:167], v[188:191], v[44:47]
	v_mfma_f32_16x16x32_bf16 v[40:43], v[172:175], v[188:191], v[40:43]
	v_mfma_f32_16x16x32_bf16 v[28:31], v[164:167], v[198:201], v[28:31]
	v_mfma_f32_16x16x32_bf16 v[24:27], v[172:175], v[198:201], v[24:27]
	v_mfma_f32_16x16x32_bf16 v[12:15], v[164:167], v[206:209], v[12:15]
	v_mfma_f32_16x16x32_bf16 v[8:11], v[172:175], v[206:209], v[8:11]
	s_barrier
; #define PG8_STAGE(bufoff, gbase, voff) do { _Pragma("unroll") for (int _i = 0; _i < 2; ++_i) \
;         __builtin_amdgcn_global_load_lds((const unsigned*)((const char*)(gbase) + (voff)[_i]), (LAS unsigned*)(lds + (bufoff) + ldsw + _i * 8192), 16, 0, 0); } while (0)
; #define PG8_LDA(dst, b, h) do { _Pragma("unroll") for (int m = 0; m < 4; ++m) _Pragma("unroll") for (int k = 0; k < 2; ++k) dst[m][k] = *(const LAS bf16x8*)(lds + PG8_SA(b, h) + aoff + m * 2048 + k * 1024); } while (0)
; #define PG8_LDB(dst, b, h) do { _Pragma("unroll") for (int n = 0; n < 2; ++n) _Pragma("unroll") for (int k = 0; k < 2; ++k) dst[n][k] = *(const LAS bf16x8*)(lds + PG8_SB(b, h) + boff + n * 2048 + k * 1024); } while (0)
; #define PG8_MMA(ai, bj, At, Bt) do { __builtin_amdgcn_s_setprio(1); _Pragma("unroll") for (int m = 0; m < 4; ++m) _Pragma("unroll") for (int n = 0; n < 2; ++n) _Pragma("unroll") for (int k = 0; k < 2; ++k) \
;         acc[ai][bj][m][n] = __builtin_amdgcn_mfma_f32_16x16x32_bf16(Bt[n][k], At[m][k], acc[ai][bj][m][n], 0, 0, 0); __builtin_amdgcn_s_setprio(0); } while (0)
; #define PG8_WAIT_V(n) asm volatile("s_waitcnt vmcnt(" #n ")" ::: "memory")
; #define PG8_WAIT_L(n) asm volatile("s_waitcnt lgkmcnt(" #n ")" ::: "memory")
; #define PG8_BAR __builtin_amdgcn_s_barrier()
; #define PG8_SCHED __builtin_amdgcn_sched_barrier(0)
; template <class Epi>
; DEVI void gemm_phase(LAS unsigned char* lds, const bf16_t* gA, const bf16_t* gBt, const int lda, const int ldb, const int K, const StaticOrder S_, const Epi E) {
;     ...
;             PG8_STAGE(PG8_SB(0, 1), b2 + hstepB, voffB);
;             PG8_WAIT_V(6); PG8_BAR; PG8_MMA(1, 1, At, B1); PG8_BAR;
;             PG8_LDB(B0, 1, 0); PG8_SCHED; PG8_LDA(At, 1, 0); PG8_STAGE(PG8_SA(0, 1), a2 + hstepA, voffA);
;             PG8_WAIT_L(8); PG8_BAR; PG8_WAIT_L(0); PG8_MMA(0, 0, At, B0); PG8_BAR; PG8_SCHED;
;             PG8_LDB(B1, 1, 1); PG8_STAGE(PG8_SB(1, 0), b3, voffB);
;             PG8_BAR; PG8_WAIT_L(0); PG8_MMA(0, 1, At, B1); PG8_BAR;
	s_add_u32 s40, s40, s2
	s_addc_u32 s41, s41, s3
	s_add_i32 s77, s34, s18
	v_lshl_add_u64 v[232:233], s[40:41], 0, v[130:131]
	s_mov_b32 m0, s77
	v_lshl_add_u64 v[234:235], s[40:41], 0, v[134:135]
	global_load_lds_dwordx4 v[232:233], off
	s_add_i32 m0, s77, 0x2000
	s_nop 0
	global_load_lds_dwordx4 v[234:235], off
	s_waitcnt vmcnt(6)
	s_barrier
	v_mfma_f32_16x16x32_bf16 v[52:55], v[210:213], v[176:179], v[52:55]
	v_mfma_f32_16x16x32_bf16 v[48:51], v[218:221], v[176:179], v[48:51]
	v_mfma_f32_16x16x32_bf16 v[36:39], v[210:213], v[184:187], v[36:39]
	v_mfma_f32_16x16x32_bf16 v[32:35], v[218:221], v[184:187], v[32:35]
	v_mfma_f32_16x16x32_bf16 v[20:23], v[210:213], v[192:195], v[20:23]
	v_mfma_f32_16x16x32_bf16 v[16:19], v[218:221], v[192:195], v[16:19]
	v_mfma_f32_16x16x32_bf16 v[4:7], v[210:213], v[202:205], v[4:7]
	v_mfma_f32_16x16x32_bf16 v[0:3], v[218:221], v[202:205], v[0:3]
	v_mfma_f32_16x16x32_bf16 v[52:55], v[214:217], v[180:183], v[52:55]
	v_mfma_f32_16x16x32_bf16 v[48:51], v[222:225], v[180:183], v[48:51]
	v_mfma_f32_16x16x32_bf16 v[36:39], v[214:217], v[188:191], v[36:39]
	v_mfma_f32_16x16x32_bf16 v[32:35], v[222:225], v[188:191], v[32:35]
	v_mfma_f32_16x16x32_bf16 v[20:23], v[214:217], v[198:201], v[20:23]
	v_mfma_f32_16x16x32_bf16 v[16:19], v[222:225], v[198:201], v[16:19]
	v_mfma_f32_16x16x32_bf16 v[4:7], v[214:217], v[206:209], v[4:7]
	v_mfma_f32_16x16x32_bf16 v[0:3], v[222:225], v[206:209], v[0:3]
	s_barrier
	ds_read_b128 v[160:163], v156
	ds_read_b128 v[164:167], v156 offset:1024
	ds_read_b128 v[168:171], v156 offset:2048
	ds_read_b128 v[172:175], v156 offset:3072
	s_add_u32 s16, s16, s0
	s_addc_u32 s17, s17, s1
	s_mov_b32 m0, s21
	v_lshl_add_u64 v[210:211], s[16:17], 0, v[128:129]
	ds_read_b128 v[176:179], v154 offset:32768
	ds_read_b128 v[180:183], v154 offset:33792
	ds_read_b128 v[184:187], v154 offset:34816
	ds_read_b128 v[188:191], v154 offset:35840
	ds_read_b128 v[192:195], v154 offset:36864
	ds_read_b128 v[198:201], v154 offset:37888
	ds_read_b128 v[202:205], v154 offset:38912
	ds_read_b128 v[206:209], v154 offset:39936
	global_load_lds_dwordx4 v[210:211], off
	v_lshl_add_u64 v[210:211], s[16:17], 0, v[132:133]
	s_mov_b32 m0, s22
	s_nop 0
	global_load_lds_dwordx4 v[210:211], off
	s_waitcnt lgkmcnt(8)
	s_barrier
	s_waitcnt lgkmcnt(0)
	v_mfma_f32_16x16x32_bf16 v[124:127], v[160:163], v[176:179], v[124:127]
	v_mfma_f32_16x16x32_bf16 v[120:123], v[168:171], v[176:179], v[120:123]
	v_mfma_f32_16x16x32_bf16 v[108:111], v[160:163], v[184:187], v[108:111]
	v_mfma_f32_16x16x32_bf16 v[104:107], v[168:171], v[184:187], v[104:107]
	v_mfma_f32_16x16x32_bf16 v[92:95], v[160:163], v[192:195], v[92:95]
	v_mfma_f32_16x16x32_bf16 v[88:91], v[168:171], v[192:195], v[88:91]
	v_mfma_f32_16x16x32_bf16 v[76:79], v[160:163], v[202:205], v[76:79]
	v_mfma_f32_16x16x32_bf16 v[72:75], v[168:171], v[202:205], v[72:75]
	v_mfma_f32_16x16x32_bf16 v[124:127], v[164:167], v[180:183], v[124:127]
	v_mfma_f32_16x16x32_bf16 v[120:123], v[172:175], v[180:183], v[120:123]
	v_mfma_f32_16x16x32_bf16 v[108:111], v[164:167], v[188:191], v[108:111]
	v_mfma_f32_16x16x32_bf16 v[104:107], v[172:175], v[188:191], v[104:107]
	v_mfma_f32_16x16x32_bf16 v[92:95], v[164:167], v[198:201], v[92:95]
	v_mfma_f32_16x16x32_bf16 v[88:91], v[172:175], v[198:201], v[88:91]
	v_mfma_f32_16x16x32_bf16 v[76:79], v[164:167], v[206:209], v[76:79]
	v_mfma_f32_16x16x32_bf16 v[72:75], v[172:175], v[206:209], v[72:75]
	s_barrier
	s_add_i32 s16, s35, s18
	v_lshl_add_u64 v[144:145], v[144:145], 0, s[46:47]
	s_mov_b32 m0, s16
	ds_read_b128 v[210:213], v157
	ds_read_b128 v[214:217], v157 offset:1024
	ds_read_b128 v[218:221], v157 offset:2048
	ds_read_b128 v[222:225], v157 offset:3072
	global_load_lds_dwordx4 v[144:145], off
	v_lshl_add_u64 v[144:145], v[226:227], 0, s[46:47]
	s_add_i32 m0, s16, 0x2000
	s_nop 0
	global_load_lds_dwordx4 v[144:145], off
	s_barrier
; #define PG8_STAGE(bufoff, gbase, voff) do { _Pragma("unroll") for (int _i = 0; _i < 2; ++_i) \
;         __builtin_amdgcn_global_load_lds((const unsigned*)((const char*)(gbase) + (voff)[_i]), (LAS unsigned*)(lds + (bufoff) + ldsw + _i * 8192), 16, 0, 0); } while (0)
; #define PG8_LDA(dst, b, h) do { _Pragma("unroll") for (int m = 0; m < 4; ++m) _Pragma("unroll") for (int k = 0; k < 2; ++k) dst[m][k] = *(const LAS bf16x8*)(lds + PG8_SA(b, h) + aoff + m * 2048 + k * 1024); } while (0)
; #define PG8_MMA(ai, bj, At, Bt) do { __builtin_amdgcn_s_setprio(1); _Pragma("unroll") for (int m = 0; m < 4; ++m) _Pragma("unroll") for (int n = 0; n < 2; ++n) _Pragma("unroll") for (int k = 0; k < 2; ++k) \
;         acc[ai][bj][m][n] = __builtin_amdgcn_mfma_f32_16x16x32_bf16(Bt[n][k], At[m][k], acc[ai][bj][m][n], 0, 0, 0); __builtin_amdgcn_s_setprio(0); } while (0)
; #define PG8_WAIT_V(n) asm volatile("s_waitcnt vmcnt(" #n ")" ::: "memory")
; #define PG8_WAIT_L(n) asm volatile("s_waitcnt lgkmcnt(" #n ")" ::: "memory")
; #define PG8_BAR __builtin_amdgcn_s_barrier()
; #define PG8_SCHED __builtin_amdgcn_sched_barrier(0)
; template <class Epi>
; DEVI void gemm_phase(LAS unsigned char* lds, const bf16_t* gA, const bf16_t* gBt, const int lda, const int ldb, const int K, const StaticOrder S_, const Epi E) {
;     ...
;             PG8_BAR; PG8_WAIT_L(0); PG8_MMA(0, 1, At, B1); PG8_BAR;
;             PG8_LDA(At, 1, 1); PG8_STAGE(PG8_SA(1, 0), a3, voffA);
;             PG8_BAR; PG8_WAIT_L(0); PG8_MMA(1, 0, At, B0); PG8_BAR; PG8_SCHED;
;             PG8_STAGE(PG8_SB(1, 1), b3 + hstepB, voffB);
;             PG8_WAIT_V(6); PG8_BAR; PG8_MMA(1, 1, At, B1); PG8_BAR;
;         }
	s_waitcnt lgkmcnt(0)
	v_mfma_f32_16x16x32_bf16 v[116:119], v[210:213], v[176:179], v[116:119]
	v_mfma_f32_16x16x32_bf16 v[112:115], v[218:221], v[176:179], v[112:115]
	v_mfma_f32_16x16x32_bf16 v[100:103], v[210:213], v[184:187], v[100:103]
	v_mfma_f32_16x16x32_bf16 v[96:99], v[218:221], v[184:187], v[96:99]
	v_mfma_f32_16x16x32_bf16 v[84:87], v[210:213], v[192:195], v[84:87]
	v_mfma_f32_16x16x32_bf16 v[80:83], v[218:221], v[192:195], v[80:83]
	v_mfma_f32_16x16x32_bf16 v[68:71], v[210:213], v[202:205], v[68:71]
	v_mfma_f32_16x16x32_bf16 v[64:67], v[218:221], v[202:205], v[64:67]
	v_mfma_f32_16x16x32_bf16 v[116:119], v[214:217], v[180:183], v[116:119]
	v_mfma_f32_16x16x32_bf16 v[112:115], v[222:225], v[180:183], v[112:115]
	v_mfma_f32_16x16x32_bf16 v[100:103], v[214:217], v[188:191], v[100:103]
	v_mfma_f32_16x16x32_bf16 v[96:99], v[222:225], v[188:191], v[96:99]
	v_mfma_f32_16x16x32_bf16 v[84:87], v[214:217], v[198:201], v[84:87]
	v_mfma_f32_16x16x32_bf16 v[80:83], v[222:225], v[198:201], v[80:83]
	v_mfma_f32_16x16x32_bf16 v[68:71], v[214:217], v[206:209], v[68:71]
	v_mfma_f32_16x16x32_bf16 v[64:67], v[222:225], v[206:209], v[64:67]
	s_mov_b32 m0, s23
	v_lshl_add_u64 v[144:145], v[228:229], 0, s[46:47]
	s_barrier
	ds_read_b128 v[176:179], v154 offset:49152
	ds_read_b128 v[180:183], v154 offset:50176
	ds_read_b128 v[184:187], v154 offset:51200
	ds_read_b128 v[188:191], v154 offset:52224
	ds_read_b128 v[192:195], v154 offset:53248
	ds_read_b128 v[198:201], v154 offset:54272
	ds_read_b128 v[202:205], v154 offset:55296
	ds_read_b128 v[206:209], v154 offset:56320
	global_load_lds_dwordx4 v[144:145], off
	v_lshl_add_u64 v[144:145], v[230:231], 0, s[46:47]
	s_mov_b32 m0, s24
	s_nop 0
	global_load_lds_dwordx4 v[144:145], off
	s_barrier
	s_waitcnt lgkmcnt(0)
	v_mfma_f32_16x16x32_bf16 v[60:63], v[160:163], v[176:179], v[60:63]
	v_mfma_f32_16x16x32_bf16 v[56:59], v[168:171], v[176:179], v[56:59]
	v_mfma_f32_16x16x32_bf16 v[44:47], v[160:163], v[184:187], v[44:47]
	v_mfma_f32_16x16x32_bf16 v[40:43], v[168:171], v[184:187], v[40:43]
	v_mfma_f32_16x16x32_bf16 v[28:31], v[160:163], v[192:195], v[28:31]
	v_mfma_f32_16x16x32_bf16 v[24:27], v[168:171], v[192:195], v[24:27]
	v_mfma_f32_16x16x32_bf16 v[12:15], v[160:163], v[202:205], v[12:15]
	v_mfma_f32_16x16x32_bf16 v[8:11], v[168:171], v[202:205], v[8:11]
	v_mfma_f32_16x16x32_bf16 v[60:63], v[164:167], v[180:183], v[60:63]
	v_mfma_f32_16x16x32_bf16 v[56:59], v[172:175], v[180:183], v[56:59]
	v_mfma_f32_16x16x32_bf16 v[44:47], v[164:167], v[188:191], v[44:47]
	v_mfma_f32_16x16x32_bf16 v[40:43], v[172:175], v[188:191], v[40:43]
	v_mfma_f32_16x16x32_bf16 v[28:31], v[164:167], v[198:201], v[28:31]
	v_mfma_f32_16x16x32_bf16 v[24:27], v[172:175], v[198:201], v[24:27]
	v_mfma_f32_16x16x32_bf16 v[12:15], v[164:167], v[206:209], v[12:15]
	v_mfma_f32_16x16x32_bf16 v[8:11], v[172:175], v[206:209], v[8:11]
	s_barrier
	s_add_i32 s16, s50, s18
	v_lshl_add_u64 v[144:145], v[232:233], 0, s[46:47]
	s_mov_b32 m0, s16
	s_nop 0
	global_load_lds_dwordx4 v[144:145], off
	v_lshl_add_u64 v[144:145], v[234:235], 0, s[46:47]
	s_add_i32 m0, s16, 0x2000
	s_nop 0
	global_load_lds_dwordx4 v[144:145], off
	s_waitcnt vmcnt(6)
	s_barrier
	v_mfma_f32_16x16x32_bf16 v[52:55], v[210:213], v[176:179], v[52:55]
	v_mfma_f32_16x16x32_bf16 v[48:51], v[218:221], v[176:179], v[48:51]
	v_mfma_f32_16x16x32_bf16 v[36:39], v[210:213], v[184:187], v[36:39]
	v_mfma_f32_16x16x32_bf16 v[32:35], v[218:221], v[184:187], v[32:35]
	v_mfma_f32_16x16x32_bf16 v[20:23], v[210:213], v[192:195], v[20:23]
	v_mfma_f32_16x16x32_bf16 v[16:19], v[218:221], v[192:195], v[16:19]
	v_mfma_f32_16x16x32_bf16 v[4:7], v[210:213], v[202:205], v[4:7]
	v_mfma_f32_16x16x32_bf16 v[0:3], v[218:221], v[202:205], v[0:3]
	v_mfma_f32_16x16x32_bf16 v[52:55], v[214:217], v[180:183], v[52:55]
	v_mfma_f32_16x16x32_bf16 v[48:51], v[222:225], v[180:183], v[48:51]
	v_mfma_f32_16x16x32_bf16 v[36:39], v[214:217], v[188:191], v[36:39]
	v_mfma_f32_16x16x32_bf16 v[32:35], v[222:225], v[188:191], v[32:35]
	v_mfma_f32_16x16x32_bf16 v[20:23], v[214:217], v[198:201], v[20:23]
	v_mfma_f32_16x16x32_bf16 v[16:19], v[222:225], v[198:201], v[16:19]
	v_mfma_f32_16x16x32_bf16 v[4:7], v[214:217], v[206:209], v[4:7]
	v_mfma_f32_16x16x32_bf16 v[0:3], v[222:225], v[206:209], v[0:3]
	s_add_u32 s14, s14, 0x100
	s_addc_u32 s15, s15, 0
	s_add_u32 s64, s64, 0x100
	s_addc_u32 s65, s65, 0
	s_cmp_ge_i32 s76, s25
	s_mov_b32 s16, s76
	s_barrier
	s_cbranch_scc0 .LBB0_800

; #define PG8_STAGE(bufoff, gbase, voff) do { _Pragma("unroll") for (int _i = 0; _i < 2; ++_i) \
;         __builtin_amdgcn_global_load_lds((const unsigned*)((const char*)(gbase) + (voff)[_i]), (LAS unsigned*)(lds + (bufoff) + ldsw + _i * 8192), 16, 0, 0); } while (0)
; #define PG8_LDA(dst, b, h) do { _Pragma("unroll") for (int m = 0; m < 4; ++m) _Pragma("unroll") for (int k = 0; k < 2; ++k) dst[m][k] = *(const LAS bf16x8*)(lds + PG8_SA(b, h) + aoff + m * 2048 + k * 1024); } while (0)
; #define PG8_LDB(dst, b, h) do { _Pragma("unroll") for (int n = 0; n < 2; ++n) _Pragma("unroll") for (int k = 0; k < 2; ++k) dst[n][k] = *(const LAS bf16x8*)(lds + PG8_SB(b, h) + boff + n * 2048 + k * 1024); } while (0)
; #define PG8_MMA(ai, bj, At, Bt) do { __builtin_amdgcn_s_setprio(1); _Pragma("unroll") for (int m = 0; m < 4; ++m) _Pragma("unroll") for (int n = 0; n < 2; ++n) _Pragma("unroll") for (int k = 0; k < 2; ++k) \
;         acc[ai][bj][m][n] = __builtin_amdgcn_mfma_f32_16x16x32_bf16(Bt[n][k], At[m][k], acc[ai][bj][m][n], 0, 0, 0); __builtin_amdgcn_s_setprio(0); } while (0)
; #define PG8_WAIT_L(n) asm volatile("s_waitcnt lgkmcnt(" #n ")" ::: "memory")
; #define PG8_BAR __builtin_amdgcn_s_barrier()
; #define PG8_SCHED __builtin_amdgcn_sched_barrier(0)
; template <class Epi>
; DEVI void gemm_phase(LAS unsigned char* lds, const bf16_t* gA, const bf16_t* gBt, const int lda, const int ldb, const int K, const StaticOrder S_, const Epi E) {
;     ...
;             PG8_LDB(B0, 0, 0); PG8_SCHED; PG8_LDA(At, 0, 0); PG8_STAGE(PG8_SA(1, 1), a1 + hstepA, voffA);
;             PG8_WAIT_L(8); PG8_BAR; PG8_WAIT_L(0); PG8_MMA(0, 0, At, B0); PG8_BAR; PG8_SCHED;
;             PG8_LDB(B1, 0, 1); PG8_STAGE(PG8_SB(0, 0), b2, voffB);
;             PG8_BAR; PG8_WAIT_L(0); PG8_MMA(0, 1, At, B1); PG8_BAR;
;             PG8_LDA(At, 0, 1); PG8_STAGE(PG8_SA(0, 0), a2, voffA);
;             PG8_BAR; PG8_WAIT_L(0); PG8_MMA(1, 0, At, B0); PG8_BAR; PG8_SCHED;
.LBB0_1301:
	ds_read_b128 v[128:131], v201
	ds_read_b128 v[132:135], v201 offset:1024
	ds_read_b128 v[136:139], v201 offset:2048
	ds_read_b128 v[140:143], v201 offset:3072
	s_add_i32 s72, s16, 2
	s_add_u32 s40, s14, 0x80
	s_addc_u32 s17, s15, 0
	s_cmp_eq_u32 s19, s16
	s_cselect_b32 s16, s12, s40
	s_cselect_b32 s17, s13, s17
	s_cselect_b32 s41, s43, s71
	s_cselect_b32 s40, s42, s70
	v_lshl_add_u64 v[164:165], s[14:15], 0, v[174:175]
	s_add_i32 m0, s82, 0xc000
	ds_read_b128 v[144:147], v202
	ds_read_b128 v[148:151], v202 offset:1024
	ds_read_b128 v[152:155], v202 offset:2048
	ds_read_b128 v[156:159], v202 offset:3072
	ds_read_b128 v[160:163], v202 offset:4096
	ds_read_b128 v[180:183], v202 offset:5120
	ds_read_b128 v[184:187], v202 offset:6144
	ds_read_b128 v[188:191], v202 offset:7168
	global_load_lds_dwordx4 v[164:165], off
	v_lshl_add_u64 v[164:165], s[14:15], 0, v[176:177]
	s_add_i32 m0, s82, 0xe000
	s_nop 0
	global_load_lds_dwordx4 v[164:165], off
	s_waitcnt lgkmcnt(8)
	s_barrier
	s_waitcnt lgkmcnt(0)
	v_mfma_f32_16x16x32_bf16 v[124:127], v[128:131], v[144:147], v[124:127]
	v_mfma_f32_16x16x32_bf16 v[120:123], v[136:139], v[144:147], v[120:123]
	v_mfma_f32_16x16x32_bf16 v[108:111], v[128:131], v[152:155], v[108:111]
	v_mfma_f32_16x16x32_bf16 v[104:107], v[136:139], v[152:155], v[104:107]
	v_mfma_f32_16x16x32_bf16 v[92:95], v[128:131], v[160:163], v[92:95]
	v_mfma_f32_16x16x32_bf16 v[88:91], v[136:139], v[160:163], v[88:91]
	v_mfma_f32_16x16x32_bf16 v[76:79], v[128:131], v[184:187], v[76:79]
	v_mfma_f32_16x16x32_bf16 v[72:75], v[136:139], v[184:187], v[72:75]
	v_mfma_f32_16x16x32_bf16 v[124:127], v[132:135], v[148:151], v[124:127]
	v_mfma_f32_16x16x32_bf16 v[120:123], v[140:143], v[148:151], v[120:123]
	v_mfma_f32_16x16x32_bf16 v[108:111], v[132:135], v[156:159], v[108:111]
	v_mfma_f32_16x16x32_bf16 v[104:107], v[140:143], v[156:159], v[104:107]
	v_mfma_f32_16x16x32_bf16 v[92:95], v[132:135], v[180:183], v[92:95]
	v_mfma_f32_16x16x32_bf16 v[88:91], v[140:143], v[180:183], v[88:91]
	v_mfma_f32_16x16x32_bf16 v[76:79], v[132:135], v[188:191], v[76:79]
	v_mfma_f32_16x16x32_bf16 v[72:75], v[140:143], v[188:191], v[72:75]
	s_barrier
	s_add_i32 s73, s29, s20
	v_lshl_add_u64 v[164:165], s[40:41], 0, v[168:169]
	s_mov_b32 m0, s73
	ds_read_b128 v[192:195], v203
	ds_read_b128 v[206:209], v203 offset:1024
	ds_read_b128 v[210:213], v203 offset:2048
	ds_read_b128 v[214:217], v203 offset:3072
	global_load_lds_dwordx4 v[164:165], off
	v_lshl_add_u64 v[218:219], s[40:41], 0, v[172:173]
	s_add_i32 m0, s73, 0x2000
	s_nop 0
	global_load_lds_dwordx4 v[218:219], off
	s_barrier
	s_waitcnt lgkmcnt(0)
	v_mfma_f32_16x16x32_bf16 v[116:119], v[192:195], v[144:147], v[116:119]
	v_mfma_f32_16x16x32_bf16 v[112:115], v[210:213], v[144:147], v[112:115]
	v_mfma_f32_16x16x32_bf16 v[100:103], v[192:195], v[152:155], v[100:103]
	v_mfma_f32_16x16x32_bf16 v[96:99], v[210:213], v[152:155], v[96:99]
	v_mfma_f32_16x16x32_bf16 v[84:87], v[192:195], v[160:163], v[84:87]
	v_mfma_f32_16x16x32_bf16 v[80:83], v[210:213], v[160:163], v[80:83]
	v_mfma_f32_16x16x32_bf16 v[68:71], v[192:195], v[184:187], v[68:71]
	v_mfma_f32_16x16x32_bf16 v[64:67], v[210:213], v[184:187], v[64:67]
	v_mfma_f32_16x16x32_bf16 v[116:119], v[206:209], v[148:151], v[116:119]
	v_mfma_f32_16x16x32_bf16 v[112:115], v[214:217], v[148:151], v[112:115]
	v_mfma_f32_16x16x32_bf16 v[100:103], v[206:209], v[156:159], v[100:103]
	v_mfma_f32_16x16x32_bf16 v[96:99], v[214:217], v[156:159], v[96:99]
	v_mfma_f32_16x16x32_bf16 v[84:87], v[206:209], v[180:183], v[84:87]
	v_mfma_f32_16x16x32_bf16 v[80:83], v[214:217], v[180:183], v[80:83]
	v_mfma_f32_16x16x32_bf16 v[68:71], v[206:209], v[188:191], v[68:71]
	v_mfma_f32_16x16x32_bf16 v[64:67], v[214:217], v[188:191], v[64:67]
	s_mov_b32 m0, s82
	v_lshl_add_u64 v[220:221], s[16:17], 0, v[166:167]
	s_barrier
	ds_read_b128 v[144:147], v202 offset:16384
	ds_read_b128 v[148:151], v202 offset:17408
	ds_read_b128 v[152:155], v202 offset:18432
	ds_read_b128 v[156:159], v202 offset:19456
	ds_read_b128 v[160:163], v202 offset:20480
	ds_read_b128 v[180:183], v202 offset:21504
	ds_read_b128 v[184:187], v202 offset:22528
	ds_read_b128 v[188:191], v202 offset:23552
	global_load_lds_dwordx4 v[220:221], off
	v_lshl_add_u64 v[222:223], s[16:17], 0, v[170:171]
	s_mov_b32 m0, s22
	s_nop 0
	global_load_lds_dwordx4 v[222:223], off
	s_barrier
	s_waitcnt lgkmcnt(0)
	v_mfma_f32_16x16x32_bf16 v[60:63], v[128:131], v[144:147], v[60:63]
	v_mfma_f32_16x16x32_bf16 v[56:59], v[136:139], v[144:147], v[56:59]
	v_mfma_f32_16x16x32_bf16 v[44:47], v[128:131], v[152:155], v[44:47]
	v_mfma_f32_16x16x32_bf16 v[40:43], v[136:139], v[152:155], v[40:43]
	v_mfma_f32_16x16x32_bf16 v[28:31], v[128:131], v[160:163], v[28:31]
	v_mfma_f32_16x16x32_bf16 v[24:27], v[136:139], v[160:163], v[24:27]
	v_mfma_f32_16x16x32_bf16 v[12:15], v[128:131], v[184:187], v[12:15]
	v_mfma_f32_16x16x32_bf16 v[8:11], v[136:139], v[184:187], v[8:11]
	v_mfma_f32_16x16x32_bf16 v[60:63], v[132:135], v[148:151], v[60:63]
	v_mfma_f32_16x16x32_bf16 v[56:59], v[140:143], v[148:151], v[56:59]
	v_mfma_f32_16x16x32_bf16 v[44:47], v[132:135], v[156:159], v[44:47]
	v_mfma_f32_16x16x32_bf16 v[40:43], v[140:143], v[156:159], v[40:43]
	v_mfma_f32_16x16x32_bf16 v[28:31], v[132:135], v[180:183], v[28:31]
	v_mfma_f32_16x16x32_bf16 v[24:27], v[140:143], v[180:183], v[24:27]
	v_mfma_f32_16x16x32_bf16 v[12:15], v[132:135], v[188:191], v[12:15]
	v_mfma_f32_16x16x32_bf16 v[8:11], v[140:143], v[188:191], v[8:11]
	s_barrier
; #define PG8_STAGE(bufoff, gbase, voff) do { _Pragma("unroll") for (int _i = 0; _i < 2; ++_i) \
;         __builtin_amdgcn_global_load_lds((const unsigned*)((const char*)(gbase) + (voff)[_i]), (LAS unsigned*)(lds + (bufoff) + ldsw + _i * 8192), 16, 0, 0); } while (0)
; #define PG8_LDA(dst, b, h) do { _Pragma("unroll") for (int m = 0; m < 4; ++m) _Pragma("unroll") for (int k = 0; k < 2; ++k) dst[m][k] = *(const LAS bf16x8*)(lds + PG8_SA(b, h) + aoff + m * 2048 + k * 1024); } while (0)
; #define PG8_LDB(dst, b, h) do { _Pragma("unroll") for (int n = 0; n < 2; ++n) _Pragma("unroll") for (int k = 0; k < 2; ++k) dst[n][k] = *(const LAS bf16x8*)(lds + PG8_SB(b, h) + boff + n * 2048 + k * 1024); } while (0)
; #define PG8_MMA(ai, bj, At, Bt) do { __builtin_amdgcn_s_setprio(1); _Pragma("unroll") for (int m = 0; m < 4; ++m) _Pragma("unroll") for (int n = 0; n < 2; ++n) _Pragma("unroll") for (int k = 0; k < 2; ++k) \
;         acc[ai][bj][m][n] = __builtin_amdgcn_mfma_f32_16x16x32_bf16(Bt[n][k], At[m][k], acc[ai][bj][m][n], 0, 0, 0); __builtin_amdgcn_s_setprio(0); } while (0)
; #define PG8_WAIT_V(n) asm volatile("s_waitcnt vmcnt(" #n ")" ::: "memory")
; #define PG8_WAIT_L(n) asm volatile("s_waitcnt lgkmcnt(" #n ")" ::: "memory")
; #define PG8_BAR __builtin_amdgcn_s_barrier()
; #define PG8_SCHED __builtin_amdgcn_sched_barrier(0)
; template <class Epi>
; DEVI void gemm_phase(LAS unsigned char* lds, const bf16_t* gA, const bf16_t* gBt, const int lda, const int ldb, const int K, const StaticOrder S_, const Epi E) {
;     ...
;             PG8_STAGE(PG8_SB(0, 1), b2 + hstepB, voffB);
;             PG8_WAIT_V(6); PG8_BAR; PG8_MMA(1, 1, At, B1); PG8_BAR;
;             PG8_LDB(B0, 1, 0); PG8_SCHED; PG8_LDA(At, 1, 0); PG8_STAGE(PG8_SA(0, 1), a2 + hstepA, voffA);
;             PG8_WAIT_L(8); PG8_BAR; PG8_WAIT_L(0); PG8_MMA(0, 0, At, B0); PG8_BAR; PG8_SCHED;
;             PG8_LDB(B1, 1, 1); PG8_STAGE(PG8_SB(1, 0), b3, voffB);
;             PG8_BAR; PG8_WAIT_L(0); PG8_MMA(0, 1, At, B1); PG8_BAR;
	s_add_u32 s40, s40, s2
	s_addc_u32 s41, s41, s3
	s_add_i32 s73, s50, s20
	v_lshl_add_u64 v[224:225], s[40:41], 0, v[168:169]
	s_mov_b32 m0, s73
	v_lshl_add_u64 v[226:227], s[40:41], 0, v[172:173]
	global_load_lds_dwordx4 v[224:225], off
	s_add_i32 m0, s73, 0x2000
	s_nop 0
	global_load_lds_dwordx4 v[226:227], off
	s_waitcnt vmcnt(6)
	s_barrier
	v_mfma_f32_16x16x32_bf16 v[52:55], v[192:195], v[144:147], v[52:55]
	v_mfma_f32_16x16x32_bf16 v[48:51], v[210:213], v[144:147], v[48:51]
	v_mfma_f32_16x16x32_bf16 v[36:39], v[192:195], v[152:155], v[36:39]
	v_mfma_f32_16x16x32_bf16 v[32:35], v[210:213], v[152:155], v[32:35]
	v_mfma_f32_16x16x32_bf16 v[20:23], v[192:195], v[160:163], v[20:23]
	v_mfma_f32_16x16x32_bf16 v[16:19], v[210:213], v[160:163], v[16:19]
	v_mfma_f32_16x16x32_bf16 v[4:7], v[192:195], v[184:187], v[4:7]
	v_mfma_f32_16x16x32_bf16 v[0:3], v[210:213], v[184:187], v[0:3]
	v_mfma_f32_16x16x32_bf16 v[52:55], v[206:209], v[148:151], v[52:55]
	v_mfma_f32_16x16x32_bf16 v[48:51], v[214:217], v[148:151], v[48:51]
	v_mfma_f32_16x16x32_bf16 v[36:39], v[206:209], v[156:159], v[36:39]
	v_mfma_f32_16x16x32_bf16 v[32:35], v[214:217], v[156:159], v[32:35]
	v_mfma_f32_16x16x32_bf16 v[20:23], v[206:209], v[180:183], v[20:23]
	v_mfma_f32_16x16x32_bf16 v[16:19], v[214:217], v[180:183], v[16:19]
	v_mfma_f32_16x16x32_bf16 v[4:7], v[206:209], v[188:191], v[4:7]
	v_mfma_f32_16x16x32_bf16 v[0:3], v[214:217], v[188:191], v[0:3]
	s_add_i32 s40, 0, 0x18000
	v_add_u32_e32 v140, s40, v199
	s_barrier
	ds_read_b128 v[128:131], v140
	ds_read_b128 v[132:135], v140 offset:1024
	ds_read_b128 v[136:139], v140 offset:2048
	ds_read_b128 v[140:143], v140 offset:3072
	s_add_u32 s16, s16, s0
	s_addc_u32 s17, s17, s1
	s_mov_b32 m0, s23
	v_lshl_add_u64 v[192:193], s[16:17], 0, v[166:167]
	ds_read_b128 v[144:147], v202 offset:32768
	ds_read_b128 v[148:151], v202 offset:33792
	ds_read_b128 v[152:155], v202 offset:34816
	ds_read_b128 v[156:159], v202 offset:35840
	ds_read_b128 v[160:163], v202 offset:36864
	ds_read_b128 v[180:183], v202 offset:37888
	ds_read_b128 v[184:187], v202 offset:38912
	ds_read_b128 v[188:191], v202 offset:39936
	global_load_lds_dwordx4 v[192:193], off
	v_lshl_add_u64 v[192:193], s[16:17], 0, v[170:171]
	s_mov_b32 m0, s24
	s_nop 0
	global_load_lds_dwordx4 v[192:193], off
	s_waitcnt lgkmcnt(8)
	s_barrier
	s_waitcnt lgkmcnt(0)
	v_mfma_f32_16x16x32_bf16 v[124:127], v[128:131], v[144:147], v[124:127]
	v_mfma_f32_16x16x32_bf16 v[120:123], v[136:139], v[144:147], v[120:123]
	v_mfma_f32_16x16x32_bf16 v[108:111], v[128:131], v[152:155], v[108:111]
	v_mfma_f32_16x16x32_bf16 v[104:107], v[136:139], v[152:155], v[104:107]
	v_mfma_f32_16x16x32_bf16 v[92:95], v[128:131], v[160:163], v[92:95]
	v_mfma_f32_16x16x32_bf16 v[88:91], v[136:139], v[160:163], v[88:91]
	v_mfma_f32_16x16x32_bf16 v[76:79], v[128:131], v[184:187], v[76:79]
	v_mfma_f32_16x16x32_bf16 v[72:75], v[136:139], v[184:187], v[72:75]
	v_mfma_f32_16x16x32_bf16 v[124:127], v[132:135], v[148:151], v[124:127]
	v_mfma_f32_16x16x32_bf16 v[120:123], v[140:143], v[148:151], v[120:123]
	v_mfma_f32_16x16x32_bf16 v[108:111], v[132:135], v[156:159], v[108:111]
	v_mfma_f32_16x16x32_bf16 v[104:107], v[140:143], v[156:159], v[104:107]
	v_mfma_f32_16x16x32_bf16 v[92:95], v[132:135], v[180:183], v[92:95]
	v_mfma_f32_16x16x32_bf16 v[88:91], v[140:143], v[180:183], v[88:91]
	v_mfma_f32_16x16x32_bf16 v[76:79], v[132:135], v[188:191], v[76:79]
	v_mfma_f32_16x16x32_bf16 v[72:75], v[140:143], v[188:191], v[72:75]
	s_barrier
	s_add_i32 s16, 0, 0x1c000
	s_add_i32 s17, s40, s20
	v_add_u32_e32 v205, s16, v199
	v_lshl_add_u64 v[164:165], v[164:165], 0, s[8:9]
	s_mov_b32 m0, s17
	ds_read_b128 v[192:195], v205
	ds_read_b128 v[206:209], v205 offset:1024
	ds_read_b128 v[210:213], v205 offset:2048
	ds_read_b128 v[214:217], v205 offset:3072
	global_load_lds_dwordx4 v[164:165], off
	v_lshl_add_u64 v[164:165], v[218:219], 0, s[8:9]
	s_add_i32 m0, s17, 0x2000
	s_nop 0
	global_load_lds_dwordx4 v[164:165], off
	s_barrier
; #define PG8_STAGE(bufoff, gbase, voff) do { _Pragma("unroll") for (int _i = 0; _i < 2; ++_i) \
;         __builtin_amdgcn_global_load_lds((const unsigned*)((const char*)(gbase) + (voff)[_i]), (LAS unsigned*)(lds + (bufoff) + ldsw + _i * 8192), 16, 0, 0); } while (0)
; #define PG8_LDA(dst, b, h) do { _Pragma("unroll") for (int m = 0; m < 4; ++m) _Pragma("unroll") for (int k = 0; k < 2; ++k) dst[m][k] = *(const LAS bf16x8*)(lds + PG8_SA(b, h) + aoff + m * 2048 + k * 1024); } while (0)
; #define PG8_MMA(ai, bj, At, Bt) do { __builtin_amdgcn_s_setprio(1); _Pragma("unroll") for (int m = 0; m < 4; ++m) _Pragma("unroll") for (int n = 0; n < 2; ++n) _Pragma("unroll") for (int k = 0; k < 2; ++k) \
;         acc[ai][bj][m][n] = __builtin_amdgcn_mfma_f32_16x16x32_bf16(Bt[n][k], At[m][k], acc[ai][bj][m][n], 0, 0, 0); __builtin_amdgcn_s_setprio(0); } while (0)
; #define PG8_WAIT_V(n) asm volatile("s_waitcnt vmcnt(" #n ")" ::: "memory")
; #define PG8_WAIT_L(n) asm volatile("s_waitcnt lgkmcnt(" #n ")" ::: "memory")
; #define PG8_BAR __builtin_amdgcn_s_barrier()
; #define PG8_SCHED __builtin_amdgcn_sched_barrier(0)
; template <class Epi>
; DEVI void gemm_phase(LAS unsigned char* lds, const bf16_t* gA, const bf16_t* gBt, const int lda, const int ldb, const int K, const StaticOrder S_, const Epi E) {
;     ...
;             PG8_BAR; PG8_WAIT_L(0); PG8_MMA(0, 1, At, B1); PG8_BAR;
;             PG8_LDA(At, 1, 1); PG8_STAGE(PG8_SA(1, 0), a3, voffA);
;             PG8_BAR; PG8_WAIT_L(0); PG8_MMA(1, 0, At, B0); PG8_BAR; PG8_SCHED;
;             PG8_STAGE(PG8_SB(1, 1), b3 + hstepB, voffB);
;             PG8_WAIT_V(6); PG8_BAR; PG8_MMA(1, 1, At, B1); PG8_BAR;
;         }
	s_waitcnt lgkmcnt(0)
	v_mfma_f32_16x16x32_bf16 v[116:119], v[192:195], v[144:147], v[116:119]
	v_mfma_f32_16x16x32_bf16 v[112:115], v[210:213], v[144:147], v[112:115]
	v_mfma_f32_16x16x32_bf16 v[100:103], v[192:195], v[152:155], v[100:103]
	v_mfma_f32_16x16x32_bf16 v[96:99], v[210:213], v[152:155], v[96:99]
	v_mfma_f32_16x16x32_bf16 v[84:87], v[192:195], v[160:163], v[84:87]
	v_mfma_f32_16x16x32_bf16 v[80:83], v[210:213], v[160:163], v[80:83]
	v_mfma_f32_16x16x32_bf16 v[68:71], v[192:195], v[184:187], v[68:71]
	v_mfma_f32_16x16x32_bf16 v[64:67], v[210:213], v[184:187], v[64:67]
	v_mfma_f32_16x16x32_bf16 v[116:119], v[206:209], v[148:151], v[116:119]
	v_mfma_f32_16x16x32_bf16 v[112:115], v[214:217], v[148:151], v[112:115]
	v_mfma_f32_16x16x32_bf16 v[100:103], v[206:209], v[156:159], v[100:103]
	v_mfma_f32_16x16x32_bf16 v[96:99], v[214:217], v[156:159], v[96:99]
	v_mfma_f32_16x16x32_bf16 v[84:87], v[206:209], v[180:183], v[84:87]
	v_mfma_f32_16x16x32_bf16 v[80:83], v[214:217], v[180:183], v[80:83]
	v_mfma_f32_16x16x32_bf16 v[68:71], v[206:209], v[188:191], v[68:71]
	v_mfma_f32_16x16x32_bf16 v[64:67], v[214:217], v[188:191], v[64:67]
	s_mov_b32 m0, s26
	v_lshl_add_u64 v[164:165], v[220:221], 0, s[8:9]
	s_barrier
	ds_read_b128 v[144:147], v202 offset:49152
	ds_read_b128 v[148:151], v202 offset:50176
	ds_read_b128 v[152:155], v202 offset:51200
	ds_read_b128 v[156:159], v202 offset:52224
	ds_read_b128 v[160:163], v202 offset:53248
	ds_read_b128 v[180:183], v202 offset:54272
	ds_read_b128 v[184:187], v202 offset:55296
	ds_read_b128 v[188:191], v202 offset:56320
	global_load_lds_dwordx4 v[164:165], off
	v_lshl_add_u64 v[164:165], v[222:223], 0, s[8:9]
	s_mov_b32 m0, s27
	s_nop 0
	global_load_lds_dwordx4 v[164:165], off
	s_barrier
	s_waitcnt lgkmcnt(0)
	v_mfma_f32_16x16x32_bf16 v[60:63], v[128:131], v[144:147], v[60:63]
	v_mfma_f32_16x16x32_bf16 v[56:59], v[136:139], v[144:147], v[56:59]
	v_mfma_f32_16x16x32_bf16 v[44:47], v[128:131], v[152:155], v[44:47]
	v_mfma_f32_16x16x32_bf16 v[40:43], v[136:139], v[152:155], v[40:43]
	v_mfma_f32_16x16x32_bf16 v[28:31], v[128:131], v[160:163], v[28:31]
	v_mfma_f32_16x16x32_bf16 v[24:27], v[136:139], v[160:163], v[24:27]
	v_mfma_f32_16x16x32_bf16 v[12:15], v[128:131], v[184:187], v[12:15]
	v_mfma_f32_16x16x32_bf16 v[8:11], v[136:139], v[184:187], v[8:11]
	v_mfma_f32_16x16x32_bf16 v[60:63], v[132:135], v[148:151], v[60:63]
	v_mfma_f32_16x16x32_bf16 v[56:59], v[140:143], v[148:151], v[56:59]
	v_mfma_f32_16x16x32_bf16 v[44:47], v[132:135], v[156:159], v[44:47]
	v_mfma_f32_16x16x32_bf16 v[40:43], v[140:143], v[156:159], v[40:43]
	v_mfma_f32_16x16x32_bf16 v[28:31], v[132:135], v[180:183], v[28:31]
	v_mfma_f32_16x16x32_bf16 v[24:27], v[140:143], v[180:183], v[24:27]
	v_mfma_f32_16x16x32_bf16 v[12:15], v[132:135], v[188:191], v[12:15]
	v_mfma_f32_16x16x32_bf16 v[8:11], v[140:143], v[188:191], v[8:11]
	s_barrier
	s_add_i32 s16, s16, s20
	v_lshl_add_u64 v[128:129], v[224:225], 0, s[8:9]
	s_mov_b32 m0, s16
	s_nop 0
	global_load_lds_dwordx4 v[128:129], off
	v_lshl_add_u64 v[128:129], v[226:227], 0, s[8:9]
	s_add_i32 m0, s16, 0x2000
	s_nop 0
	global_load_lds_dwordx4 v[128:129], off
	s_waitcnt vmcnt(6)
	s_barrier
	v_mfma_f32_16x16x32_bf16 v[52:55], v[192:195], v[144:147], v[52:55]
	v_mfma_f32_16x16x32_bf16 v[48:51], v[210:213], v[144:147], v[48:51]
	v_mfma_f32_16x16x32_bf16 v[36:39], v[192:195], v[152:155], v[36:39]
	v_mfma_f32_16x16x32_bf16 v[32:35], v[210:213], v[152:155], v[32:35]
	v_mfma_f32_16x16x32_bf16 v[20:23], v[192:195], v[160:163], v[20:23]
	v_mfma_f32_16x16x32_bf16 v[16:19], v[210:213], v[160:163], v[16:19]
	v_mfma_f32_16x16x32_bf16 v[4:7], v[192:195], v[184:187], v[4:7]
	v_mfma_f32_16x16x32_bf16 v[0:3], v[210:213], v[184:187], v[0:3]
	v_mfma_f32_16x16x32_bf16 v[52:55], v[206:209], v[148:151], v[52:55]
	v_mfma_f32_16x16x32_bf16 v[48:51], v[214:217], v[148:151], v[48:51]
	v_mfma_f32_16x16x32_bf16 v[36:39], v[206:209], v[156:159], v[36:39]
	v_mfma_f32_16x16x32_bf16 v[32:35], v[214:217], v[156:159], v[32:35]
	v_mfma_f32_16x16x32_bf16 v[20:23], v[206:209], v[180:183], v[20:23]
	v_mfma_f32_16x16x32_bf16 v[16:19], v[214:217], v[180:183], v[16:19]
	v_mfma_f32_16x16x32_bf16 v[4:7], v[206:209], v[188:191], v[4:7]
	v_mfma_f32_16x16x32_bf16 v[0:3], v[214:217], v[188:191], v[0:3]
	s_add_u32 s14, s14, 0x100
	s_addc_u32 s15, s15, 0
	s_add_u32 s70, s70, 0x100
	s_addc_u32 s71, s71, 0
	s_cmp_ge_i32 s72, s25
	s_mov_b32 s16, s72
	s_barrier
	s_cbranch_scc0 .LBB0_1301

; #define PG8_STAGE(bufoff, gbase, voff) do { _Pragma("unroll") for (int _i = 0; _i < 2; ++_i) \
;         __builtin_amdgcn_global_load_lds((const unsigned*)((const char*)(gbase) + (voff)[_i]), (LAS unsigned*)(lds + (bufoff) + ldsw + _i * 8192), 16, 0, 0); } while (0)
; #define PG8_LDA(dst, b, h) do { _Pragma("unroll") for (int m = 0; m < 4; ++m) _Pragma("unroll") for (int k = 0; k < 2; ++k) dst[m][k] = *(const LAS bf16x8*)(lds + PG8_SA(b, h) + aoff + m * 2048 + k * 1024); } while (0)
; #define PG8_LDB(dst, b, h) do { _Pragma("unroll") for (int n = 0; n < 2; ++n) _Pragma("unroll") for (int k = 0; k < 2; ++k) dst[n][k] = *(const LAS bf16x8*)(lds + PG8_SB(b, h) + boff + n * 2048 + k * 1024); } while (0)
; #define PG8_MMA(ai, bj, At, Bt) do { __builtin_amdgcn_s_setprio(1); _Pragma("unroll") for (int m = 0; m < 4; ++m) _Pragma("unroll") for (int n = 0; n < 2; ++n) _Pragma("unroll") for (int k = 0; k < 2; ++k) \
;         acc[ai][bj][m][n] = __builtin_amdgcn_mfma_f32_16x16x32_bf16(Bt[n][k], At[m][k], acc[ai][bj][m][n], 0, 0, 0); __builtin_amdgcn_s_setprio(0); } while (0)
; #define PG8_WAIT_L(n) asm volatile("s_waitcnt lgkmcnt(" #n ")" ::: "memory")
; #define PG8_BAR __builtin_amdgcn_s_barrier()
; #define PG8_SCHED __builtin_amdgcn_sched_barrier(0)
; template <class Epi>
; DEVI void gemm_phase(LAS unsigned char* lds, const bf16_t* gA, const bf16_t* gBt, const int lda, const int ldb, const int K, const StaticOrder S_, const Epi E) {
;     ...
;             PG8_LDB(B0, 0, 0); PG8_SCHED; PG8_LDA(At, 0, 0); PG8_STAGE(PG8_SA(1, 1), a1 + hstepA, voffA);
;             PG8_WAIT_L(8); PG8_BAR; PG8_WAIT_L(0); PG8_MMA(0, 0, At, B0); PG8_BAR; PG8_SCHED;
;             PG8_LDB(B1, 0, 1); PG8_STAGE(PG8_SB(0, 0), b2, voffB);
;             PG8_BAR; PG8_WAIT_L(0); PG8_MMA(0, 1, At, B1); PG8_BAR;
;             PG8_LDA(At, 0, 1); PG8_STAGE(PG8_SA(0, 0), a2, voffA);
;             PG8_BAR; PG8_WAIT_L(0); PG8_MMA(1, 0, At, B0); PG8_BAR; PG8_SCHED;
.LBB0_1445:
	ds_read_b128 v[158:161], v151
	ds_read_b128 v[162:165], v151 offset:1024
	ds_read_b128 v[166:169], v151 offset:2048
	ds_read_b128 v[170:173], v151 offset:3072
	s_add_i32 s79, s16, 2
	s_add_u32 s70, s14, 0x80
	s_addc_u32 s17, s15, 0
	s_cmp_eq_u32 s26, s16
	s_cselect_b32 s16, s40, s70
	s_cselect_b32 s17, s41, s17
	s_cselect_b32 s71, s67, s78
	s_cselect_b32 s70, s66, s77
	v_lshl_add_u64 v[144:145], s[14:15], 0, v[138:139]
	s_add_i32 m0, s19, 0xc000
	ds_read_b128 v[174:177], v152
	ds_read_b128 v[178:181], v152 offset:1024
	ds_read_b128 v[182:185], v152 offset:2048
	ds_read_b128 v[186:189], v152 offset:3072
	ds_read_b128 v[190:193], v152 offset:4096
	ds_read_b128 v[198:201], v152 offset:5120
	ds_read_b128 v[202:205], v152 offset:6144
	ds_read_b128 v[206:209], v152 offset:7168
	global_load_lds_dwordx4 v[144:145], off
	v_lshl_add_u64 v[144:145], s[14:15], 0, v[140:141]
	s_add_i32 m0, s19, 0xe000
	s_nop 0
	global_load_lds_dwordx4 v[144:145], off
	s_waitcnt lgkmcnt(8)
	s_barrier
	s_waitcnt lgkmcnt(0)
	v_mfma_f32_16x16x32_bf16 v[120:123], v[158:161], v[174:177], v[120:123]
	v_mfma_f32_16x16x32_bf16 v[116:119], v[166:169], v[174:177], v[116:119]
	v_mfma_f32_16x16x32_bf16 v[108:111], v[158:161], v[182:185], v[108:111]
	v_mfma_f32_16x16x32_bf16 v[100:103], v[166:169], v[182:185], v[100:103]
	v_mfma_f32_16x16x32_bf16 v[92:95], v[158:161], v[190:193], v[92:95]
	v_mfma_f32_16x16x32_bf16 v[84:87], v[166:169], v[190:193], v[84:87]
	v_mfma_f32_16x16x32_bf16 v[76:79], v[158:161], v[202:205], v[76:79]
	v_mfma_f32_16x16x32_bf16 v[68:71], v[166:169], v[202:205], v[68:71]
	v_mfma_f32_16x16x32_bf16 v[120:123], v[162:165], v[178:181], v[120:123]
	v_mfma_f32_16x16x32_bf16 v[116:119], v[170:173], v[178:181], v[116:119]
	v_mfma_f32_16x16x32_bf16 v[108:111], v[162:165], v[186:189], v[108:111]
	v_mfma_f32_16x16x32_bf16 v[100:103], v[170:173], v[186:189], v[100:103]
	v_mfma_f32_16x16x32_bf16 v[92:95], v[162:165], v[198:201], v[92:95]
	v_mfma_f32_16x16x32_bf16 v[84:87], v[170:173], v[198:201], v[84:87]
	v_mfma_f32_16x16x32_bf16 v[76:79], v[162:165], v[206:209], v[76:79]
	v_mfma_f32_16x16x32_bf16 v[68:71], v[170:173], v[206:209], v[68:71]
	s_barrier
	s_add_i32 s80, s34, s18
	v_lshl_add_u64 v[144:145], s[70:71], 0, v[130:131]
	s_mov_b32 m0, s80
	ds_read_b128 v[210:213], v153
	ds_read_b128 v[214:217], v153 offset:1024
	ds_read_b128 v[218:221], v153 offset:2048
	ds_read_b128 v[222:225], v153 offset:3072
	global_load_lds_dwordx4 v[144:145], off
	v_lshl_add_u64 v[194:195], s[70:71], 0, v[134:135]
	s_add_i32 m0, s80, 0x2000
	s_nop 0
	global_load_lds_dwordx4 v[194:195], off
	s_barrier
	s_waitcnt lgkmcnt(0)
	v_mfma_f32_16x16x32_bf16 v[124:127], v[210:213], v[174:177], v[124:127]
	v_mfma_f32_16x16x32_bf16 v[112:115], v[218:221], v[174:177], v[112:115]
	v_mfma_f32_16x16x32_bf16 v[104:107], v[210:213], v[182:185], v[104:107]
	v_mfma_f32_16x16x32_bf16 v[96:99], v[218:221], v[182:185], v[96:99]
	v_mfma_f32_16x16x32_bf16 v[88:91], v[210:213], v[190:193], v[88:91]
	v_mfma_f32_16x16x32_bf16 v[80:83], v[218:221], v[190:193], v[80:83]
	v_mfma_f32_16x16x32_bf16 v[72:75], v[210:213], v[202:205], v[72:75]
	v_mfma_f32_16x16x32_bf16 v[64:67], v[218:221], v[202:205], v[64:67]
	v_mfma_f32_16x16x32_bf16 v[124:127], v[214:217], v[178:181], v[124:127]
	v_mfma_f32_16x16x32_bf16 v[112:115], v[222:225], v[178:181], v[112:115]
	v_mfma_f32_16x16x32_bf16 v[104:107], v[214:217], v[186:189], v[104:107]
	v_mfma_f32_16x16x32_bf16 v[96:99], v[222:225], v[186:189], v[96:99]
	v_mfma_f32_16x16x32_bf16 v[88:91], v[214:217], v[198:201], v[88:91]
	v_mfma_f32_16x16x32_bf16 v[80:83], v[222:225], v[198:201], v[80:83]
	v_mfma_f32_16x16x32_bf16 v[72:75], v[214:217], v[206:209], v[72:75]
	v_mfma_f32_16x16x32_bf16 v[64:67], v[222:225], v[206:209], v[64:67]
	s_mov_b32 m0, s19
	v_lshl_add_u64 v[226:227], s[16:17], 0, v[128:129]
	s_barrier
	ds_read_b128 v[174:177], v152 offset:16384
	ds_read_b128 v[178:181], v152 offset:17408
	ds_read_b128 v[182:185], v152 offset:18432
	ds_read_b128 v[186:189], v152 offset:19456
	ds_read_b128 v[190:193], v152 offset:20480
	ds_read_b128 v[198:201], v152 offset:21504
	ds_read_b128 v[202:205], v152 offset:22528
	ds_read_b128 v[206:209], v152 offset:23552
	global_load_lds_dwordx4 v[226:227], off
	v_lshl_add_u64 v[228:229], s[16:17], 0, v[132:133]
	s_mov_b32 m0, s20
	s_nop 0
	global_load_lds_dwordx4 v[228:229], off
	s_barrier
	s_waitcnt lgkmcnt(0)
	v_mfma_f32_16x16x32_bf16 v[60:63], v[158:161], v[174:177], v[60:63]
	v_mfma_f32_16x16x32_bf16 v[56:59], v[166:169], v[174:177], v[56:59]
	v_mfma_f32_16x16x32_bf16 v[44:47], v[158:161], v[182:185], v[44:47]
	v_mfma_f32_16x16x32_bf16 v[40:43], v[166:169], v[182:185], v[40:43]
	v_mfma_f32_16x16x32_bf16 v[28:31], v[158:161], v[190:193], v[28:31]
	v_mfma_f32_16x16x32_bf16 v[24:27], v[166:169], v[190:193], v[24:27]
	v_mfma_f32_16x16x32_bf16 v[12:15], v[158:161], v[202:205], v[12:15]
	v_mfma_f32_16x16x32_bf16 v[8:11], v[166:169], v[202:205], v[8:11]
	v_mfma_f32_16x16x32_bf16 v[60:63], v[162:165], v[178:181], v[60:63]
	v_mfma_f32_16x16x32_bf16 v[56:59], v[170:173], v[178:181], v[56:59]
	v_mfma_f32_16x16x32_bf16 v[44:47], v[162:165], v[186:189], v[44:47]
	v_mfma_f32_16x16x32_bf16 v[40:43], v[170:173], v[186:189], v[40:43]
	v_mfma_f32_16x16x32_bf16 v[28:31], v[162:165], v[198:201], v[28:31]
	v_mfma_f32_16x16x32_bf16 v[24:27], v[170:173], v[198:201], v[24:27]
	v_mfma_f32_16x16x32_bf16 v[12:15], v[162:165], v[206:209], v[12:15]
	v_mfma_f32_16x16x32_bf16 v[8:11], v[170:173], v[206:209], v[8:11]
	s_barrier
; #define PG8_STAGE(bufoff, gbase, voff) do { _Pragma("unroll") for (int _i = 0; _i < 2; ++_i) \
;         __builtin_amdgcn_global_load_lds((const unsigned*)((const char*)(gbase) + (voff)[_i]), (LAS unsigned*)(lds + (bufoff) + ldsw + _i * 8192), 16, 0, 0); } while (0)
; #define PG8_LDA(dst, b, h) do { _Pragma("unroll") for (int m = 0; m < 4; ++m) _Pragma("unroll") for (int k = 0; k < 2; ++k) dst[m][k] = *(const LAS bf16x8*)(lds + PG8_SA(b, h) + aoff + m * 2048 + k * 1024); } while (0)
; #define PG8_LDB(dst, b, h) do { _Pragma("unroll") for (int n = 0; n < 2; ++n) _Pragma("unroll") for (int k = 0; k < 2; ++k) dst[n][k] = *(const LAS bf16x8*)(lds + PG8_SB(b, h) + boff + n * 2048 + k * 1024); } while (0)
; #define PG8_MMA(ai, bj, At, Bt) do { __builtin_amdgcn_s_setprio(1); _Pragma("unroll") for (int m = 0; m < 4; ++m) _Pragma("unroll") for (int n = 0; n < 2; ++n) _Pragma("unroll") for (int k = 0; k < 2; ++k) \
;         acc[ai][bj][m][n] = __builtin_amdgcn_mfma_f32_16x16x32_bf16(Bt[n][k], At[m][k], acc[ai][bj][m][n], 0, 0, 0); __builtin_amdgcn_s_setprio(0); } while (0)
; #define PG8_WAIT_V(n) asm volatile("s_waitcnt vmcnt(" #n ")" ::: "memory")
; #define PG8_WAIT_L(n) asm volatile("s_waitcnt lgkmcnt(" #n ")" ::: "memory")
; #define PG8_BAR __builtin_amdgcn_s_barrier()
; #define PG8_SCHED __builtin_amdgcn_sched_barrier(0)
; template <class Epi>
; DEVI void gemm_phase(LAS unsigned char* lds, const bf16_t* gA, const bf16_t* gBt, const int lda, const int ldb, const int K, const StaticOrder S_, const Epi E) {
;     ...
;             PG8_STAGE(PG8_SB(0, 1), b2 + hstepB, voffB);
;             PG8_WAIT_V(6); PG8_BAR; PG8_MMA(1, 1, At, B1); PG8_BAR;
;             PG8_LDB(B0, 1, 0); PG8_SCHED; PG8_LDA(At, 1, 0); PG8_STAGE(PG8_SA(0, 1), a2 + hstepA, voffA);
;             PG8_WAIT_L(8); PG8_BAR; PG8_WAIT_L(0); PG8_MMA(0, 0, At, B0); PG8_BAR; PG8_SCHED;
;             PG8_LDB(B1, 1, 1); PG8_STAGE(PG8_SB(1, 0), b3, voffB);
;             PG8_BAR; PG8_WAIT_L(0); PG8_MMA(0, 1, At, B1); PG8_BAR;
	s_add_u32 s70, s70, s2
	s_addc_u32 s71, s71, s3
	s_add_i32 s80, s35, s18
	v_lshl_add_u64 v[230:231], s[70:71], 0, v[130:131]
	s_mov_b32 m0, s80
	v_lshl_add_u64 v[232:233], s[70:71], 0, v[134:135]
	global_load_lds_dwordx4 v[230:231], off
	s_add_i32 m0, s80, 0x2000
	s_nop 0
	global_load_lds_dwordx4 v[232:233], off
	s_waitcnt vmcnt(6)
	s_barrier
	v_mfma_f32_16x16x32_bf16 v[52:55], v[210:213], v[174:177], v[52:55]
	v_mfma_f32_16x16x32_bf16 v[48:51], v[218:221], v[174:177], v[48:51]
	v_mfma_f32_16x16x32_bf16 v[36:39], v[210:213], v[182:185], v[36:39]
	v_mfma_f32_16x16x32_bf16 v[32:35], v[218:221], v[182:185], v[32:35]
	v_mfma_f32_16x16x32_bf16 v[20:23], v[210:213], v[190:193], v[20:23]
	v_mfma_f32_16x16x32_bf16 v[16:19], v[218:221], v[190:193], v[16:19]
	v_mfma_f32_16x16x32_bf16 v[4:7], v[210:213], v[202:205], v[4:7]
	v_mfma_f32_16x16x32_bf16 v[0:3], v[218:221], v[202:205], v[0:3]
	v_mfma_f32_16x16x32_bf16 v[52:55], v[214:217], v[178:181], v[52:55]
	v_mfma_f32_16x16x32_bf16 v[48:51], v[222:225], v[178:181], v[48:51]
	v_mfma_f32_16x16x32_bf16 v[36:39], v[214:217], v[186:189], v[36:39]
	v_mfma_f32_16x16x32_bf16 v[32:35], v[222:225], v[186:189], v[32:35]
	v_mfma_f32_16x16x32_bf16 v[20:23], v[214:217], v[198:201], v[20:23]
	v_mfma_f32_16x16x32_bf16 v[16:19], v[222:225], v[198:201], v[16:19]
	v_mfma_f32_16x16x32_bf16 v[4:7], v[214:217], v[206:209], v[4:7]
	v_mfma_f32_16x16x32_bf16 v[0:3], v[222:225], v[206:209], v[0:3]
	s_barrier
	ds_read_b128 v[158:161], v154
	ds_read_b128 v[162:165], v154 offset:1024
	ds_read_b128 v[166:169], v154 offset:2048
	ds_read_b128 v[170:173], v154 offset:3072
	s_add_u32 s16, s16, s0
	s_addc_u32 s17, s17, s1
	s_mov_b32 m0, s21
	v_lshl_add_u64 v[210:211], s[16:17], 0, v[128:129]
	ds_read_b128 v[174:177], v152 offset:32768
	ds_read_b128 v[178:181], v152 offset:33792
	ds_read_b128 v[182:185], v152 offset:34816
	ds_read_b128 v[186:189], v152 offset:35840
	ds_read_b128 v[190:193], v152 offset:36864
	ds_read_b128 v[198:201], v152 offset:37888
	ds_read_b128 v[202:205], v152 offset:38912
	ds_read_b128 v[206:209], v152 offset:39936
	global_load_lds_dwordx4 v[210:211], off
	v_lshl_add_u64 v[210:211], s[16:17], 0, v[132:133]
	s_mov_b32 m0, s22
	s_nop 0
	global_load_lds_dwordx4 v[210:211], off
	s_waitcnt lgkmcnt(8)
	s_barrier
	s_waitcnt lgkmcnt(0)
	v_mfma_f32_16x16x32_bf16 v[120:123], v[158:161], v[174:177], v[120:123]
	v_mfma_f32_16x16x32_bf16 v[116:119], v[166:169], v[174:177], v[116:119]
	v_mfma_f32_16x16x32_bf16 v[108:111], v[158:161], v[182:185], v[108:111]
	v_mfma_f32_16x16x32_bf16 v[100:103], v[166:169], v[182:185], v[100:103]
	v_mfma_f32_16x16x32_bf16 v[92:95], v[158:161], v[190:193], v[92:95]
	v_mfma_f32_16x16x32_bf16 v[84:87], v[166:169], v[190:193], v[84:87]
	v_mfma_f32_16x16x32_bf16 v[76:79], v[158:161], v[202:205], v[76:79]
	v_mfma_f32_16x16x32_bf16 v[68:71], v[166:169], v[202:205], v[68:71]
	v_mfma_f32_16x16x32_bf16 v[120:123], v[162:165], v[178:181], v[120:123]
	v_mfma_f32_16x16x32_bf16 v[116:119], v[170:173], v[178:181], v[116:119]
	v_mfma_f32_16x16x32_bf16 v[108:111], v[162:165], v[186:189], v[108:111]
	v_mfma_f32_16x16x32_bf16 v[100:103], v[170:173], v[186:189], v[100:103]
	v_mfma_f32_16x16x32_bf16 v[92:95], v[162:165], v[198:201], v[92:95]
	v_mfma_f32_16x16x32_bf16 v[84:87], v[170:173], v[198:201], v[84:87]
	v_mfma_f32_16x16x32_bf16 v[76:79], v[162:165], v[206:209], v[76:79]
	v_mfma_f32_16x16x32_bf16 v[68:71], v[170:173], v[206:209], v[68:71]
	s_barrier
	s_add_i32 s16, s49, s18
	v_lshl_add_u64 v[144:145], v[144:145], 0, s[64:65]
	s_mov_b32 m0, s16
	ds_read_b128 v[210:213], v155
	ds_read_b128 v[214:217], v155 offset:1024
	ds_read_b128 v[218:221], v155 offset:2048
	ds_read_b128 v[222:225], v155 offset:3072
	global_load_lds_dwordx4 v[144:145], off
	v_lshl_add_u64 v[144:145], v[194:195], 0, s[64:65]
	s_add_i32 m0, s16, 0x2000
	s_nop 0
	global_load_lds_dwordx4 v[144:145], off
	s_barrier
; #define PG8_STAGE(bufoff, gbase, voff) do { _Pragma("unroll") for (int _i = 0; _i < 2; ++_i) \
;         __builtin_amdgcn_global_load_lds((const unsigned*)((const char*)(gbase) + (voff)[_i]), (LAS unsigned*)(lds + (bufoff) + ldsw + _i * 8192), 16, 0, 0); } while (0)
; #define PG8_LDA(dst, b, h) do { _Pragma("unroll") for (int m = 0; m < 4; ++m) _Pragma("unroll") for (int k = 0; k < 2; ++k) dst[m][k] = *(const LAS bf16x8*)(lds + PG8_SA(b, h) + aoff + m * 2048 + k * 1024); } while (0)
; #define PG8_MMA(ai, bj, At, Bt) do { __builtin_amdgcn_s_setprio(1); _Pragma("unroll") for (int m = 0; m < 4; ++m) _Pragma("unroll") for (int n = 0; n < 2; ++n) _Pragma("unroll") for (int k = 0; k < 2; ++k) \
;         acc[ai][bj][m][n] = __builtin_amdgcn_mfma_f32_16x16x32_bf16(Bt[n][k], At[m][k], acc[ai][bj][m][n], 0, 0, 0); __builtin_amdgcn_s_setprio(0); } while (0)
; #define PG8_WAIT_V(n) asm volatile("s_waitcnt vmcnt(" #n ")" ::: "memory")
; #define PG8_WAIT_L(n) asm volatile("s_waitcnt lgkmcnt(" #n ")" ::: "memory")
; #define PG8_BAR __builtin_amdgcn_s_barrier()
; #define PG8_SCHED __builtin_amdgcn_sched_barrier(0)
; template <class Epi>
; DEVI void gemm_phase(LAS unsigned char* lds, const bf16_t* gA, const bf16_t* gBt, const int lda, const int ldb, const int K, const StaticOrder S_, const Epi E) {
;     ...
;             PG8_BAR; PG8_WAIT_L(0); PG8_MMA(0, 1, At, B1); PG8_BAR;
;             PG8_LDA(At, 1, 1); PG8_STAGE(PG8_SA(1, 0), a3, voffA);
;             PG8_BAR; PG8_WAIT_L(0); PG8_MMA(1, 0, At, B0); PG8_BAR; PG8_SCHED;
;             PG8_STAGE(PG8_SB(1, 1), b3 + hstepB, voffB);
;             PG8_WAIT_V(6); PG8_BAR; PG8_MMA(1, 1, At, B1); PG8_BAR;
;         }
	s_waitcnt lgkmcnt(0)
	v_mfma_f32_16x16x32_bf16 v[124:127], v[210:213], v[174:177], v[124:127]
	v_mfma_f32_16x16x32_bf16 v[112:115], v[218:221], v[174:177], v[112:115]
	v_mfma_f32_16x16x32_bf16 v[104:107], v[210:213], v[182:185], v[104:107]
	v_mfma_f32_16x16x32_bf16 v[96:99], v[218:221], v[182:185], v[96:99]
	v_mfma_f32_16x16x32_bf16 v[88:91], v[210:213], v[190:193], v[88:91]
	v_mfma_f32_16x16x32_bf16 v[80:83], v[218:221], v[190:193], v[80:83]
	v_mfma_f32_16x16x32_bf16 v[72:75], v[210:213], v[202:205], v[72:75]
	v_mfma_f32_16x16x32_bf16 v[64:67], v[218:221], v[202:205], v[64:67]
	v_mfma_f32_16x16x32_bf16 v[124:127], v[214:217], v[178:181], v[124:127]
	v_mfma_f32_16x16x32_bf16 v[112:115], v[222:225], v[178:181], v[112:115]
	v_mfma_f32_16x16x32_bf16 v[104:107], v[214:217], v[186:189], v[104:107]
	v_mfma_f32_16x16x32_bf16 v[96:99], v[222:225], v[186:189], v[96:99]
	v_mfma_f32_16x16x32_bf16 v[88:91], v[214:217], v[198:201], v[88:91]
	v_mfma_f32_16x16x32_bf16 v[80:83], v[222:225], v[198:201], v[80:83]
	v_mfma_f32_16x16x32_bf16 v[72:75], v[214:217], v[206:209], v[72:75]
	v_mfma_f32_16x16x32_bf16 v[64:67], v[222:225], v[206:209], v[64:67]
	s_mov_b32 m0, s23
	v_lshl_add_u64 v[144:145], v[226:227], 0, s[64:65]
	s_barrier
	ds_read_b128 v[174:177], v152 offset:49152
	ds_read_b128 v[178:181], v152 offset:50176
	ds_read_b128 v[182:185], v152 offset:51200
	ds_read_b128 v[186:189], v152 offset:52224
	ds_read_b128 v[190:193], v152 offset:53248
	ds_read_b128 v[198:201], v152 offset:54272
	ds_read_b128 v[202:205], v152 offset:55296
	ds_read_b128 v[206:209], v152 offset:56320
	global_load_lds_dwordx4 v[144:145], off
	v_lshl_add_u64 v[144:145], v[228:229], 0, s[64:65]
	s_mov_b32 m0, s24
	s_nop 0
	global_load_lds_dwordx4 v[144:145], off
	s_barrier
	s_waitcnt lgkmcnt(0)
	v_mfma_f32_16x16x32_bf16 v[60:63], v[158:161], v[174:177], v[60:63]
	v_mfma_f32_16x16x32_bf16 v[56:59], v[166:169], v[174:177], v[56:59]
	v_mfma_f32_16x16x32_bf16 v[44:47], v[158:161], v[182:185], v[44:47]
	v_mfma_f32_16x16x32_bf16 v[40:43], v[166:169], v[182:185], v[40:43]
	v_mfma_f32_16x16x32_bf16 v[28:31], v[158:161], v[190:193], v[28:31]
	v_mfma_f32_16x16x32_bf16 v[24:27], v[166:169], v[190:193], v[24:27]
	v_mfma_f32_16x16x32_bf16 v[12:15], v[158:161], v[202:205], v[12:15]
	v_mfma_f32_16x16x32_bf16 v[8:11], v[166:169], v[202:205], v[8:11]
	v_mfma_f32_16x16x32_bf16 v[60:63], v[162:165], v[178:181], v[60:63]
	v_mfma_f32_16x16x32_bf16 v[56:59], v[170:173], v[178:181], v[56:59]
	v_mfma_f32_16x16x32_bf16 v[44:47], v[162:165], v[186:189], v[44:47]
	v_mfma_f32_16x16x32_bf16 v[40:43], v[170:173], v[186:189], v[40:43]
	v_mfma_f32_16x16x32_bf16 v[28:31], v[162:165], v[198:201], v[28:31]
	v_mfma_f32_16x16x32_bf16 v[24:27], v[170:173], v[198:201], v[24:27]
	v_mfma_f32_16x16x32_bf16 v[12:15], v[162:165], v[206:209], v[12:15]
	v_mfma_f32_16x16x32_bf16 v[8:11], v[170:173], v[206:209], v[8:11]
	s_barrier
	s_add_i32 s16, s31, s18
	v_lshl_add_u64 v[144:145], v[230:231], 0, s[64:65]
	s_mov_b32 m0, s16
	s_nop 0
	global_load_lds_dwordx4 v[144:145], off
	v_lshl_add_u64 v[144:145], v[232:233], 0, s[64:65]
	s_add_i32 m0, s16, 0x2000
	s_nop 0
	global_load_lds_dwordx4 v[144:145], off
	s_waitcnt vmcnt(6)
	s_barrier
	v_mfma_f32_16x16x32_bf16 v[52:55], v[210:213], v[174:177], v[52:55]
	v_mfma_f32_16x16x32_bf16 v[48:51], v[218:221], v[174:177], v[48:51]
	v_mfma_f32_16x16x32_bf16 v[36:39], v[210:213], v[182:185], v[36:39]
	v_mfma_f32_16x16x32_bf16 v[32:35], v[218:221], v[182:185], v[32:35]
	v_mfma_f32_16x16x32_bf16 v[20:23], v[210:213], v[190:193], v[20:23]
	v_mfma_f32_16x16x32_bf16 v[16:19], v[218:221], v[190:193], v[16:19]
	v_mfma_f32_16x16x32_bf16 v[4:7], v[210:213], v[202:205], v[4:7]
	v_mfma_f32_16x16x32_bf16 v[0:3], v[218:221], v[202:205], v[0:3]
	v_mfma_f32_16x16x32_bf16 v[52:55], v[214:217], v[178:181], v[52:55]
	v_mfma_f32_16x16x32_bf16 v[48:51], v[222:225], v[178:181], v[48:51]
	v_mfma_f32_16x16x32_bf16 v[36:39], v[214:217], v[186:189], v[36:39]
	v_mfma_f32_16x16x32_bf16 v[32:35], v[222:225], v[186:189], v[32:35]
	v_mfma_f32_16x16x32_bf16 v[20:23], v[214:217], v[198:201], v[20:23]
	v_mfma_f32_16x16x32_bf16 v[16:19], v[222:225], v[198:201], v[16:19]
	v_mfma_f32_16x16x32_bf16 v[4:7], v[214:217], v[206:209], v[4:7]
	v_mfma_f32_16x16x32_bf16 v[0:3], v[222:225], v[206:209], v[0:3]
	s_add_u32 s14, s14, 0x100
	s_addc_u32 s15, s15, 0
	s_add_u32 s77, s77, 0x100
	s_addc_u32 s78, s78, 0
	s_cmp_ge_i32 s79, s25
	s_mov_b32 s16, s79
	s_barrier
	s_cbranch_scc0 .LBB0_1445

; #define PG8_STAGE(bufoff, gbase, voff) do { _Pragma("unroll") for (int _i = 0; _i < 2; ++_i) \
;         __builtin_amdgcn_global_load_lds((const unsigned*)((const char*)(gbase) + (voff)[_i]), (LAS unsigned*)(lds + (bufoff) + ldsw + _i * 8192), 16, 0, 0); } while (0)
; #define PG8_LDA(dst, b, h) do { _Pragma("unroll") for (int m = 0; m < 4; ++m) _Pragma("unroll") for (int k = 0; k < 2; ++k) dst[m][k] = *(const LAS bf16x8*)(lds + PG8_SA(b, h) + aoff + m * 2048 + k * 1024); } while (0)
; #define PG8_LDB(dst, b, h) do { _Pragma("unroll") for (int n = 0; n < 2; ++n) _Pragma("unroll") for (int k = 0; k < 2; ++k) dst[n][k] = *(const LAS bf16x8*)(lds + PG8_SB(b, h) + boff + n * 2048 + k * 1024); } while (0)
; #define PG8_MMA(ai, bj, At, Bt) do { __builtin_amdgcn_s_setprio(1); _Pragma("unroll") for (int m = 0; m < 4; ++m) _Pragma("unroll") for (int n = 0; n < 2; ++n) _Pragma("unroll") for (int k = 0; k < 2; ++k) \
;         acc[ai][bj][m][n] = __builtin_amdgcn_mfma_f32_16x16x32_bf16(Bt[n][k], At[m][k], acc[ai][bj][m][n], 0, 0, 0); __builtin_amdgcn_s_setprio(0); } while (0)
; #define PG8_WAIT_L(n) asm volatile("s_waitcnt lgkmcnt(" #n ")" ::: "memory")
; #define PG8_BAR __builtin_amdgcn_s_barrier()
; #define PG8_SCHED __builtin_amdgcn_sched_barrier(0)
; template <class Epi>
; DEVI void gemm_phase(LAS unsigned char* lds, const bf16_t* gA, const bf16_t* gBt, const int lda, const int ldb, const int K, const StaticOrder S_, const Epi E) {
;     ...
;             PG8_LDB(B0, 0, 0); PG8_SCHED; PG8_LDA(At, 0, 0); PG8_STAGE(PG8_SA(1, 1), a1 + hstepA, voffA);
;             PG8_WAIT_L(8); PG8_BAR; PG8_WAIT_L(0); PG8_MMA(0, 0, At, B0); PG8_BAR; PG8_SCHED;
;             PG8_LDB(B1, 0, 1); PG8_STAGE(PG8_SB(0, 0), b2, voffB);
;             PG8_BAR; PG8_WAIT_L(0); PG8_MMA(0, 1, At, B1); PG8_BAR;
;             PG8_LDA(At, 0, 1); PG8_STAGE(PG8_SA(0, 0), a2, voffA);
;             PG8_BAR; PG8_WAIT_L(0); PG8_MMA(1, 0, At, B0); PG8_BAR; PG8_SCHED;
.LBB0_1574:
	ds_read_b128 v[128:131], v201
	ds_read_b128 v[132:135], v201 offset:1024
	ds_read_b128 v[136:139], v201 offset:2048
	ds_read_b128 v[140:143], v201 offset:3072
	s_add_i32 s75, s16, 2
	s_add_u32 s40, s14, 0x80
	s_addc_u32 s17, s15, 0
	s_cmp_eq_u32 s19, s16
	s_cselect_b32 s16, s12, s40
	s_cselect_b32 s17, s13, s17
	s_cselect_b32 s41, s43, s71
	s_cselect_b32 s40, s42, s70
	v_lshl_add_u64 v[164:165], s[14:15], 0, v[174:175]
	s_add_i32 m0, s74, 0xc000
	ds_read_b128 v[144:147], v202
	ds_read_b128 v[148:151], v202 offset:1024
	ds_read_b128 v[152:155], v202 offset:2048
	ds_read_b128 v[156:159], v202 offset:3072
	ds_read_b128 v[160:163], v202 offset:4096
	ds_read_b128 v[180:183], v202 offset:5120
	ds_read_b128 v[184:187], v202 offset:6144
	ds_read_b128 v[188:191], v202 offset:7168
	global_load_lds_dwordx4 v[164:165], off
	v_lshl_add_u64 v[164:165], s[14:15], 0, v[176:177]
	s_add_i32 m0, s74, 0xe000
	s_nop 0
	global_load_lds_dwordx4 v[164:165], off
	s_waitcnt lgkmcnt(8)
	s_barrier
	s_waitcnt lgkmcnt(0)
	v_mfma_f32_16x16x32_bf16 v[124:127], v[128:131], v[144:147], v[124:127]
	v_mfma_f32_16x16x32_bf16 v[120:123], v[136:139], v[144:147], v[120:123]
	v_mfma_f32_16x16x32_bf16 v[108:111], v[128:131], v[152:155], v[108:111]
	v_mfma_f32_16x16x32_bf16 v[104:107], v[136:139], v[152:155], v[104:107]
	v_mfma_f32_16x16x32_bf16 v[92:95], v[128:131], v[160:163], v[92:95]
	v_mfma_f32_16x16x32_bf16 v[88:91], v[136:139], v[160:163], v[88:91]
	v_mfma_f32_16x16x32_bf16 v[76:79], v[128:131], v[184:187], v[76:79]
	v_mfma_f32_16x16x32_bf16 v[72:75], v[136:139], v[184:187], v[72:75]
	v_mfma_f32_16x16x32_bf16 v[124:127], v[132:135], v[148:151], v[124:127]
	v_mfma_f32_16x16x32_bf16 v[120:123], v[140:143], v[148:151], v[120:123]
	v_mfma_f32_16x16x32_bf16 v[108:111], v[132:135], v[156:159], v[108:111]
	v_mfma_f32_16x16x32_bf16 v[104:107], v[140:143], v[156:159], v[104:107]
	v_mfma_f32_16x16x32_bf16 v[92:95], v[132:135], v[180:183], v[92:95]
	v_mfma_f32_16x16x32_bf16 v[88:91], v[140:143], v[180:183], v[88:91]
	v_mfma_f32_16x16x32_bf16 v[76:79], v[132:135], v[188:191], v[76:79]
	v_mfma_f32_16x16x32_bf16 v[72:75], v[140:143], v[188:191], v[72:75]
	s_barrier
	s_add_i32 s76, s29, s20
	v_lshl_add_u64 v[164:165], s[40:41], 0, v[168:169]
	s_mov_b32 m0, s76
	ds_read_b128 v[192:195], v203
	ds_read_b128 v[206:209], v203 offset:1024
	ds_read_b128 v[210:213], v203 offset:2048
	ds_read_b128 v[214:217], v203 offset:3072
	global_load_lds_dwordx4 v[164:165], off
	v_lshl_add_u64 v[218:219], s[40:41], 0, v[172:173]
	s_add_i32 m0, s76, 0x2000
	s_nop 0
	global_load_lds_dwordx4 v[218:219], off
	s_barrier
	s_waitcnt lgkmcnt(0)
	v_mfma_f32_16x16x32_bf16 v[116:119], v[192:195], v[144:147], v[116:119]
	v_mfma_f32_16x16x32_bf16 v[112:115], v[210:213], v[144:147], v[112:115]
	v_mfma_f32_16x16x32_bf16 v[100:103], v[192:195], v[152:155], v[100:103]
	v_mfma_f32_16x16x32_bf16 v[96:99], v[210:213], v[152:155], v[96:99]
	v_mfma_f32_16x16x32_bf16 v[84:87], v[192:195], v[160:163], v[84:87]
	v_mfma_f32_16x16x32_bf16 v[80:83], v[210:213], v[160:163], v[80:83]
	v_mfma_f32_16x16x32_bf16 v[68:71], v[192:195], v[184:187], v[68:71]
	v_mfma_f32_16x16x32_bf16 v[64:67], v[210:213], v[184:187], v[64:67]
	v_mfma_f32_16x16x32_bf16 v[116:119], v[206:209], v[148:151], v[116:119]
	v_mfma_f32_16x16x32_bf16 v[112:115], v[214:217], v[148:151], v[112:115]
	v_mfma_f32_16x16x32_bf16 v[100:103], v[206:209], v[156:159], v[100:103]
	v_mfma_f32_16x16x32_bf16 v[96:99], v[214:217], v[156:159], v[96:99]
	v_mfma_f32_16x16x32_bf16 v[84:87], v[206:209], v[180:183], v[84:87]
	v_mfma_f32_16x16x32_bf16 v[80:83], v[214:217], v[180:183], v[80:83]
	v_mfma_f32_16x16x32_bf16 v[68:71], v[206:209], v[188:191], v[68:71]
	v_mfma_f32_16x16x32_bf16 v[64:67], v[214:217], v[188:191], v[64:67]
	s_mov_b32 m0, s74
	v_lshl_add_u64 v[220:221], s[16:17], 0, v[166:167]
	s_barrier
	ds_read_b128 v[144:147], v202 offset:16384
	ds_read_b128 v[148:151], v202 offset:17408
	ds_read_b128 v[152:155], v202 offset:18432
	ds_read_b128 v[156:159], v202 offset:19456
	ds_read_b128 v[160:163], v202 offset:20480
	ds_read_b128 v[180:183], v202 offset:21504
	ds_read_b128 v[184:187], v202 offset:22528
	ds_read_b128 v[188:191], v202 offset:23552
	global_load_lds_dwordx4 v[220:221], off
	v_lshl_add_u64 v[222:223], s[16:17], 0, v[170:171]
	s_mov_b32 m0, s22
	s_nop 0
	global_load_lds_dwordx4 v[222:223], off
	s_barrier
	s_waitcnt lgkmcnt(0)
	v_mfma_f32_16x16x32_bf16 v[60:63], v[128:131], v[144:147], v[60:63]
	v_mfma_f32_16x16x32_bf16 v[56:59], v[136:139], v[144:147], v[56:59]
	v_mfma_f32_16x16x32_bf16 v[44:47], v[128:131], v[152:155], v[44:47]
	v_mfma_f32_16x16x32_bf16 v[40:43], v[136:139], v[152:155], v[40:43]
	v_mfma_f32_16x16x32_bf16 v[28:31], v[128:131], v[160:163], v[28:31]
	v_mfma_f32_16x16x32_bf16 v[24:27], v[136:139], v[160:163], v[24:27]
	v_mfma_f32_16x16x32_bf16 v[12:15], v[128:131], v[184:187], v[12:15]
	v_mfma_f32_16x16x32_bf16 v[8:11], v[136:139], v[184:187], v[8:11]
	v_mfma_f32_16x16x32_bf16 v[60:63], v[132:135], v[148:151], v[60:63]
	v_mfma_f32_16x16x32_bf16 v[56:59], v[140:143], v[148:151], v[56:59]
	v_mfma_f32_16x16x32_bf16 v[44:47], v[132:135], v[156:159], v[44:47]
	v_mfma_f32_16x16x32_bf16 v[40:43], v[140:143], v[156:159], v[40:43]
	v_mfma_f32_16x16x32_bf16 v[28:31], v[132:135], v[180:183], v[28:31]
	v_mfma_f32_16x16x32_bf16 v[24:27], v[140:143], v[180:183], v[24:27]
	v_mfma_f32_16x16x32_bf16 v[12:15], v[132:135], v[188:191], v[12:15]
	v_mfma_f32_16x16x32_bf16 v[8:11], v[140:143], v[188:191], v[8:11]
	s_barrier
; #define PG8_STAGE(bufoff, gbase, voff) do { _Pragma("unroll") for (int _i = 0; _i < 2; ++_i) \
;         __builtin_amdgcn_global_load_lds((const unsigned*)((const char*)(gbase) + (voff)[_i]), (LAS unsigned*)(lds + (bufoff) + ldsw + _i * 8192), 16, 0, 0); } while (0)
; #define PG8_LDA(dst, b, h) do { _Pragma("unroll") for (int m = 0; m < 4; ++m) _Pragma("unroll") for (int k = 0; k < 2; ++k) dst[m][k] = *(const LAS bf16x8*)(lds + PG8_SA(b, h) + aoff + m * 2048 + k * 1024); } while (0)
; #define PG8_LDB(dst, b, h) do { _Pragma("unroll") for (int n = 0; n < 2; ++n) _Pragma("unroll") for (int k = 0; k < 2; ++k) dst[n][k] = *(const LAS bf16x8*)(lds + PG8_SB(b, h) + boff + n * 2048 + k * 1024); } while (0)
; #define PG8_MMA(ai, bj, At, Bt) do { __builtin_amdgcn_s_setprio(1); _Pragma("unroll") for (int m = 0; m < 4; ++m) _Pragma("unroll") for (int n = 0; n < 2; ++n) _Pragma("unroll") for (int k = 0; k < 2; ++k) \
;         acc[ai][bj][m][n] = __builtin_amdgcn_mfma_f32_16x16x32_bf16(Bt[n][k], At[m][k], acc[ai][bj][m][n], 0, 0, 0); __builtin_amdgcn_s_setprio(0); } while (0)
; #define PG8_WAIT_V(n) asm volatile("s_waitcnt vmcnt(" #n ")" ::: "memory")
; #define PG8_WAIT_L(n) asm volatile("s_waitcnt lgkmcnt(" #n ")" ::: "memory")
; #define PG8_BAR __builtin_amdgcn_s_barrier()
; #define PG8_SCHED __builtin_amdgcn_sched_barrier(0)
; template <class Epi>
; DEVI void gemm_phase(LAS unsigned char* lds, const bf16_t* gA, const bf16_t* gBt, const int lda, const int ldb, const int K, const StaticOrder S_, const Epi E) {
;     ...
;             PG8_STAGE(PG8_SB(0, 1), b2 + hstepB, voffB);
;             PG8_WAIT_V(6); PG8_BAR; PG8_MMA(1, 1, At, B1); PG8_BAR;
;             PG8_LDB(B0, 1, 0); PG8_SCHED; PG8_LDA(At, 1, 0); PG8_STAGE(PG8_SA(0, 1), a2 + hstepA, voffA);
;             PG8_WAIT_L(8); PG8_BAR; PG8_WAIT_L(0); PG8_MMA(0, 0, At, B0); PG8_BAR; PG8_SCHED;
;             PG8_LDB(B1, 1, 1); PG8_STAGE(PG8_SB(1, 0), b3, voffB);
;             PG8_BAR; PG8_WAIT_L(0); PG8_MMA(0, 1, At, B1); PG8_BAR;
	s_add_u32 s40, s40, s2
	s_addc_u32 s41, s41, s3
	s_add_i32 s76, s50, s20
	v_lshl_add_u64 v[224:225], s[40:41], 0, v[168:169]
	s_mov_b32 m0, s76
	v_lshl_add_u64 v[226:227], s[40:41], 0, v[172:173]
	global_load_lds_dwordx4 v[224:225], off
	s_add_i32 m0, s76, 0x2000
	s_nop 0
	global_load_lds_dwordx4 v[226:227], off
	s_waitcnt vmcnt(6)
	s_barrier
	v_mfma_f32_16x16x32_bf16 v[52:55], v[192:195], v[144:147], v[52:55]
	v_mfma_f32_16x16x32_bf16 v[48:51], v[210:213], v[144:147], v[48:51]
	v_mfma_f32_16x16x32_bf16 v[36:39], v[192:195], v[152:155], v[36:39]
	v_mfma_f32_16x16x32_bf16 v[32:35], v[210:213], v[152:155], v[32:35]
	v_mfma_f32_16x16x32_bf16 v[20:23], v[192:195], v[160:163], v[20:23]
	v_mfma_f32_16x16x32_bf16 v[16:19], v[210:213], v[160:163], v[16:19]
	v_mfma_f32_16x16x32_bf16 v[4:7], v[192:195], v[184:187], v[4:7]
	v_mfma_f32_16x16x32_bf16 v[0:3], v[210:213], v[184:187], v[0:3]
	v_mfma_f32_16x16x32_bf16 v[52:55], v[206:209], v[148:151], v[52:55]
	v_mfma_f32_16x16x32_bf16 v[48:51], v[214:217], v[148:151], v[48:51]
	v_mfma_f32_16x16x32_bf16 v[36:39], v[206:209], v[156:159], v[36:39]
	v_mfma_f32_16x16x32_bf16 v[32:35], v[214:217], v[156:159], v[32:35]
	v_mfma_f32_16x16x32_bf16 v[20:23], v[206:209], v[180:183], v[20:23]
	v_mfma_f32_16x16x32_bf16 v[16:19], v[214:217], v[180:183], v[16:19]
	v_mfma_f32_16x16x32_bf16 v[4:7], v[206:209], v[188:191], v[4:7]
	v_mfma_f32_16x16x32_bf16 v[0:3], v[214:217], v[188:191], v[0:3]
	s_add_i32 s40, 0, 0x18000
	v_add_u32_e32 v140, s40, v199
	s_barrier
	ds_read_b128 v[128:131], v140
	ds_read_b128 v[132:135], v140 offset:1024
	ds_read_b128 v[136:139], v140 offset:2048
	ds_read_b128 v[140:143], v140 offset:3072
	s_add_u32 s16, s16, s0
	s_addc_u32 s17, s17, s1
	s_mov_b32 m0, s23
	v_lshl_add_u64 v[192:193], s[16:17], 0, v[166:167]
	ds_read_b128 v[144:147], v202 offset:32768
	ds_read_b128 v[148:151], v202 offset:33792
	ds_read_b128 v[152:155], v202 offset:34816
	ds_read_b128 v[156:159], v202 offset:35840
	ds_read_b128 v[160:163], v202 offset:36864
	ds_read_b128 v[180:183], v202 offset:37888
	ds_read_b128 v[184:187], v202 offset:38912
	ds_read_b128 v[188:191], v202 offset:39936
	global_load_lds_dwordx4 v[192:193], off
	v_lshl_add_u64 v[192:193], s[16:17], 0, v[170:171]
	s_mov_b32 m0, s24
	s_nop 0
	global_load_lds_dwordx4 v[192:193], off
	s_waitcnt lgkmcnt(8)
	s_barrier
	s_waitcnt lgkmcnt(0)
	v_mfma_f32_16x16x32_bf16 v[124:127], v[128:131], v[144:147], v[124:127]
	v_mfma_f32_16x16x32_bf16 v[120:123], v[136:139], v[144:147], v[120:123]
	v_mfma_f32_16x16x32_bf16 v[108:111], v[128:131], v[152:155], v[108:111]
	v_mfma_f32_16x16x32_bf16 v[104:107], v[136:139], v[152:155], v[104:107]
	v_mfma_f32_16x16x32_bf16 v[92:95], v[128:131], v[160:163], v[92:95]
	v_mfma_f32_16x16x32_bf16 v[88:91], v[136:139], v[160:163], v[88:91]
	v_mfma_f32_16x16x32_bf16 v[76:79], v[128:131], v[184:187], v[76:79]
	v_mfma_f32_16x16x32_bf16 v[72:75], v[136:139], v[184:187], v[72:75]
	v_mfma_f32_16x16x32_bf16 v[124:127], v[132:135], v[148:151], v[124:127]
	v_mfma_f32_16x16x32_bf16 v[120:123], v[140:143], v[148:151], v[120:123]
	v_mfma_f32_16x16x32_bf16 v[108:111], v[132:135], v[156:159], v[108:111]
	v_mfma_f32_16x16x32_bf16 v[104:107], v[140:143], v[156:159], v[104:107]
	v_mfma_f32_16x16x32_bf16 v[92:95], v[132:135], v[180:183], v[92:95]
	v_mfma_f32_16x16x32_bf16 v[88:91], v[140:143], v[180:183], v[88:91]
	v_mfma_f32_16x16x32_bf16 v[76:79], v[132:135], v[188:191], v[76:79]
	v_mfma_f32_16x16x32_bf16 v[72:75], v[140:143], v[188:191], v[72:75]
	s_barrier
	s_add_i32 s16, 0, 0x1c000
	s_add_i32 s17, s40, s20
	v_add_u32_e32 v205, s16, v199
	v_lshl_add_u64 v[164:165], v[164:165], 0, s[8:9]
	s_mov_b32 m0, s17
	ds_read_b128 v[192:195], v205
	ds_read_b128 v[206:209], v205 offset:1024
	ds_read_b128 v[210:213], v205 offset:2048
	ds_read_b128 v[214:217], v205 offset:3072
	global_load_lds_dwordx4 v[164:165], off
	v_lshl_add_u64 v[164:165], v[218:219], 0, s[8:9]
	s_add_i32 m0, s17, 0x2000
	s_nop 0
	global_load_lds_dwordx4 v[164:165], off
	s_barrier
; #define LAS __attribute__((address_space(3)))
; #define PG8_STAGE(bufoff, gbase, voff) do { _Pragma("unroll") for (int _i = 0; _i < 2; ++_i) \
;         __builtin_amdgcn_global_load_lds((const unsigned*)((const char*)(gbase) + (voff)[_i]), (LAS unsigned*)(lds + (bufoff) + ldsw + _i * 8192), 16, 0, 0); } while (0)
; #define PG8_LDA(dst, b, h) do { _Pragma("unroll") for (int m = 0; m < 4; ++m) _Pragma("unroll") for (int k = 0; k < 2; ++k) dst[m][k] = *(const LAS bf16x8*)(lds + PG8_SA(b, h) + aoff + m * 2048 + k * 1024); } while (0)
; #define PG8_MMA(ai, bj, At, Bt) do { __builtin_amdgcn_s_setprio(1); _Pragma("unroll") for (int m = 0; m < 4; ++m) _Pragma("unroll") for (int n = 0; n < 2; ++n) _Pragma("unroll") for (int k = 0; k < 2; ++k) \
;         acc[ai][bj][m][n] = __builtin_amdgcn_mfma_f32_16x16x32_bf16(Bt[n][k], At[m][k], acc[ai][bj][m][n], 0, 0, 0); __builtin_amdgcn_s_setprio(0); } while (0)
; #define PG8_WAIT_V(n) asm volatile("s_waitcnt vmcnt(" #n ")" ::: "memory")
; #define PG8_WAIT_L(n) asm volatile("s_waitcnt lgkmcnt(" #n ")" ::: "memory")
; #define PG8_BAR __builtin_amdgcn_s_barrier()
; #define PG8_SCHED __builtin_amdgcn_sched_barrier(0)
; template <class Epi>
; DEVI void gemm_phase(LAS unsigned char* lds, const bf16_t* gA, const bf16_t* gBt, const int lda, const int ldb, const int K, const StaticOrder S_, const Epi E) {
;     ...
;             PG8_BAR; PG8_WAIT_L(0); PG8_MMA(0, 1, At, B1); PG8_BAR;
;             PG8_LDA(At, 1, 1); PG8_STAGE(PG8_SA(1, 0), a3, voffA);
;             PG8_BAR; PG8_WAIT_L(0); PG8_MMA(1, 0, At, B0); PG8_BAR; PG8_SCHED;
;             PG8_STAGE(PG8_SB(1, 1), b3 + hstepB, voffB);
;             PG8_WAIT_V(6); PG8_BAR; PG8_MMA(1, 1, At, B1); PG8_BAR;
;         }
;         E(acc, cur, wr, wc, fr, fq, (const LAS float*)(lds + STAGE_BYTES + (ui & 1) * 2048));
;         if (!has_next) break;
; #pragma unroll
;         for (int a = 0; a < 2; ++a)
; #pragma unroll
;             for (int b = 0; b < 2; ++b)
; #pragma unroll
;                 for (int m = 0; m < 4; ++m)
; #pragma unroll
;                     for (int n = 0; n < 2; ++n) acc[a][b][m][n] = (f32x4){0.f, 0.f, 0.f, 0.f};
;         cur = nxt; cA = nA; cB = nB; ++ui;
;         rs_prefetch(cur, ui & 1);
;     }
	s_waitcnt lgkmcnt(0)
	v_mfma_f32_16x16x32_bf16 v[116:119], v[192:195], v[144:147], v[116:119]
	v_mfma_f32_16x16x32_bf16 v[112:115], v[210:213], v[144:147], v[112:115]
	v_mfma_f32_16x16x32_bf16 v[100:103], v[192:195], v[152:155], v[100:103]
	v_mfma_f32_16x16x32_bf16 v[96:99], v[210:213], v[152:155], v[96:99]
	v_mfma_f32_16x16x32_bf16 v[84:87], v[192:195], v[160:163], v[84:87]
	v_mfma_f32_16x16x32_bf16 v[80:83], v[210:213], v[160:163], v[80:83]
	v_mfma_f32_16x16x32_bf16 v[68:71], v[192:195], v[184:187], v[68:71]
	v_mfma_f32_16x16x32_bf16 v[64:67], v[210:213], v[184:187], v[64:67]
	v_mfma_f32_16x16x32_bf16 v[116:119], v[206:209], v[148:151], v[116:119]
	v_mfma_f32_16x16x32_bf16 v[112:115], v[214:217], v[148:151], v[112:115]
	v_mfma_f32_16x16x32_bf16 v[100:103], v[206:209], v[156:159], v[100:103]
	v_mfma_f32_16x16x32_bf16 v[96:99], v[214:217], v[156:159], v[96:99]
	v_mfma_f32_16x16x32_bf16 v[84:87], v[206:209], v[180:183], v[84:87]
	v_mfma_f32_16x16x32_bf16 v[80:83], v[214:217], v[180:183], v[80:83]
	v_mfma_f32_16x16x32_bf16 v[68:71], v[206:209], v[188:191], v[68:71]
	v_mfma_f32_16x16x32_bf16 v[64:67], v[214:217], v[188:191], v[64:67]
	s_mov_b32 m0, s26
	v_lshl_add_u64 v[164:165], v[220:221], 0, s[8:9]
	s_barrier
	ds_read_b128 v[144:147], v202 offset:49152
	ds_read_b128 v[148:151], v202 offset:50176
	ds_read_b128 v[152:155], v202 offset:51200
	ds_read_b128 v[156:159], v202 offset:52224
	ds_read_b128 v[160:163], v202 offset:53248
	ds_read_b128 v[180:183], v202 offset:54272
	ds_read_b128 v[184:187], v202 offset:55296
	ds_read_b128 v[188:191], v202 offset:56320
	global_load_lds_dwordx4 v[164:165], off
	v_lshl_add_u64 v[164:165], v[222:223], 0, s[8:9]
	s_mov_b32 m0, s27
	s_nop 0
	global_load_lds_dwordx4 v[164:165], off
	s_barrier
	s_waitcnt lgkmcnt(0)
	v_mfma_f32_16x16x32_bf16 v[60:63], v[128:131], v[144:147], v[60:63]
	v_mfma_f32_16x16x32_bf16 v[56:59], v[136:139], v[144:147], v[56:59]
	v_mfma_f32_16x16x32_bf16 v[44:47], v[128:131], v[152:155], v[44:47]
	v_mfma_f32_16x16x32_bf16 v[40:43], v[136:139], v[152:155], v[40:43]
	v_mfma_f32_16x16x32_bf16 v[28:31], v[128:131], v[160:163], v[28:31]
	v_mfma_f32_16x16x32_bf16 v[24:27], v[136:139], v[160:163], v[24:27]
	v_mfma_f32_16x16x32_bf16 v[12:15], v[128:131], v[184:187], v[12:15]
	v_mfma_f32_16x16x32_bf16 v[8:11], v[136:139], v[184:187], v[8:11]
	v_mfma_f32_16x16x32_bf16 v[60:63], v[132:135], v[148:151], v[60:63]
	v_mfma_f32_16x16x32_bf16 v[56:59], v[140:143], v[148:151], v[56:59]
	v_mfma_f32_16x16x32_bf16 v[44:47], v[132:135], v[156:159], v[44:47]
	v_mfma_f32_16x16x32_bf16 v[40:43], v[140:143], v[156:159], v[40:43]
	v_mfma_f32_16x16x32_bf16 v[28:31], v[132:135], v[180:183], v[28:31]
	v_mfma_f32_16x16x32_bf16 v[24:27], v[140:143], v[180:183], v[24:27]
	v_mfma_f32_16x16x32_bf16 v[12:15], v[132:135], v[188:191], v[12:15]
	v_mfma_f32_16x16x32_bf16 v[8:11], v[140:143], v[188:191], v[8:11]
	s_barrier
	s_add_i32 s16, s16, s20
	v_lshl_add_u64 v[128:129], v[224:225], 0, s[8:9]
	s_mov_b32 m0, s16
	s_nop 0
	global_load_lds_dwordx4 v[128:129], off
	v_lshl_add_u64 v[128:129], v[226:227], 0, s[8:9]
	s_add_i32 m0, s16, 0x2000
	s_nop 0
	global_load_lds_dwordx4 v[128:129], off
	s_waitcnt vmcnt(6)
	s_barrier
	v_mfma_f32_16x16x32_bf16 v[52:55], v[192:195], v[144:147], v[52:55]
	v_mfma_f32_16x16x32_bf16 v[48:51], v[210:213], v[144:147], v[48:51]
	v_mfma_f32_16x16x32_bf16 v[36:39], v[192:195], v[152:155], v[36:39]
	v_mfma_f32_16x16x32_bf16 v[32:35], v[210:213], v[152:155], v[32:35]
	v_mfma_f32_16x16x32_bf16 v[20:23], v[192:195], v[160:163], v[20:23]
	v_mfma_f32_16x16x32_bf16 v[16:19], v[210:213], v[160:163], v[16:19]
	v_mfma_f32_16x16x32_bf16 v[4:7], v[192:195], v[184:187], v[4:7]
	v_mfma_f32_16x16x32_bf16 v[0:3], v[210:213], v[184:187], v[0:3]
	v_mfma_f32_16x16x32_bf16 v[52:55], v[206:209], v[148:151], v[52:55]
	v_mfma_f32_16x16x32_bf16 v[48:51], v[214:217], v[148:151], v[48:51]
	v_mfma_f32_16x16x32_bf16 v[36:39], v[206:209], v[156:159], v[36:39]
	v_mfma_f32_16x16x32_bf16 v[32:35], v[214:217], v[156:159], v[32:35]
	v_mfma_f32_16x16x32_bf16 v[20:23], v[206:209], v[180:183], v[20:23]
	v_mfma_f32_16x16x32_bf16 v[16:19], v[214:217], v[180:183], v[16:19]
	v_mfma_f32_16x16x32_bf16 v[4:7], v[206:209], v[188:191], v[4:7]
	v_mfma_f32_16x16x32_bf16 v[0:3], v[214:217], v[188:191], v[0:3]
	s_add_u32 s14, s14, 0x100
	s_addc_u32 s15, s15, 0
	s_add_u32 s70, s70, 0x100
	s_addc_u32 s71, s71, 0
	s_cmp_ge_i32 s75, s25
	s_mov_b32 s16, s75
	s_barrier
	s_cbranch_scc0 .LBB0_1574
	v_readlane_b32 s76, v238, 50
	v_readlane_b32 s77, v238, 51
	v_readlane_b32 s78, v238, 52
	v_readlane_b32 s79, v238, 53
	v_readlane_b32 s80, v238, 54
	v_readlane_b32 s81, v238, 55
	v_readlane_b32 s82, v238, 56
	v_readlane_b32 s83, v238, 57

; #define PG8_STAGE(bufoff, gbase, voff) do { _Pragma("unroll") for (int _i = 0; _i < 2; ++_i) \
;         __builtin_amdgcn_global_load_lds((const unsigned*)((const char*)(gbase) + (voff)[_i]), (LAS unsigned*)(lds + (bufoff) + ldsw + _i * 8192), 16, 0, 0); } while (0)
; #define PG8_LDA(dst, b, h) do { _Pragma("unroll") for (int m = 0; m < 4; ++m) _Pragma("unroll") for (int k = 0; k < 2; ++k) dst[m][k] = *(const LAS bf16x8*)(lds + PG8_SA(b, h) + aoff + m * 2048 + k * 1024); } while (0)
; #define PG8_LDB(dst, b, h) do { _Pragma("unroll") for (int n = 0; n < 2; ++n) _Pragma("unroll") for (int k = 0; k < 2; ++k) dst[n][k] = *(const LAS bf16x8*)(lds + PG8_SB(b, h) + boff + n * 2048 + k * 1024); } while (0)
; #define PG8_MMA(ai, bj, At, Bt) do { __builtin_amdgcn_s_setprio(1); _Pragma("unroll") for (int m = 0; m < 4; ++m) _Pragma("unroll") for (int n = 0; n < 2; ++n) _Pragma("unroll") for (int k = 0; k < 2; ++k) \
;         acc[ai][bj][m][n] = __builtin_amdgcn_mfma_f32_16x16x32_bf16(Bt[n][k], At[m][k], acc[ai][bj][m][n], 0, 0, 0); __builtin_amdgcn_s_setprio(0); } while (0)
; #define PG8_WAIT_L(n) asm volatile("s_waitcnt lgkmcnt(" #n ")" ::: "memory")
; #define PG8_BAR __builtin_amdgcn_s_barrier()
; #define PG8_SCHED __builtin_amdgcn_sched_barrier(0)
; template <class Epi>
; DEVI void gemm_phase(LAS unsigned char* lds, const bf16_t* gA, const bf16_t* gBt, const int lda, const int ldb, const int K, const StaticOrder S_, const Epi E) {
;     ...
;             PG8_LDB(B0, 0, 0); PG8_SCHED; PG8_LDA(At, 0, 0); PG8_STAGE(PG8_SA(1, 1), a1 + hstepA, voffA);
;             PG8_WAIT_L(8); PG8_BAR; PG8_WAIT_L(0); PG8_MMA(0, 0, At, B0); PG8_BAR; PG8_SCHED;
;             PG8_LDB(B1, 0, 1); PG8_STAGE(PG8_SB(0, 0), b2, voffB);
;             PG8_BAR; PG8_WAIT_L(0); PG8_MMA(0, 1, At, B1); PG8_BAR;
;             PG8_LDA(At, 0, 1); PG8_STAGE(PG8_SA(0, 0), a2, voffA);
;             PG8_BAR; PG8_WAIT_L(0); PG8_MMA(1, 0, At, B0); PG8_BAR; PG8_SCHED;
.LBB0_1848:
	ds_read_b128 v[128:131], v201
	ds_read_b128 v[132:135], v201 offset:1024
	ds_read_b128 v[136:139], v201 offset:2048
	ds_read_b128 v[140:143], v201 offset:3072
	s_add_i32 s64, s16, 2
	s_add_u32 s38, s14, 0x80
	s_addc_u32 s17, s15, 0
	s_cmp_eq_u32 s19, s16
	s_cselect_b32 s16, s12, s38
	s_cselect_b32 s17, s13, s17
	s_cselect_b32 s39, s41, s57
	s_cselect_b32 s38, s40, s56
	v_lshl_add_u64 v[164:165], s[14:15], 0, v[174:175]
	s_add_i32 m0, s61, 0xc000
	ds_read_b128 v[144:147], v202
	ds_read_b128 v[148:151], v202 offset:1024
	ds_read_b128 v[152:155], v202 offset:2048
	ds_read_b128 v[156:159], v202 offset:3072
	ds_read_b128 v[160:163], v202 offset:4096
	ds_read_b128 v[180:183], v202 offset:5120
	ds_read_b128 v[184:187], v202 offset:6144
	ds_read_b128 v[188:191], v202 offset:7168
	global_load_lds_dwordx4 v[164:165], off
	v_lshl_add_u64 v[164:165], s[14:15], 0, v[176:177]
	s_add_i32 m0, s61, 0xe000
	s_nop 0
	global_load_lds_dwordx4 v[164:165], off
	s_waitcnt lgkmcnt(8)
	s_barrier
	s_waitcnt lgkmcnt(0)
	v_mfma_f32_16x16x32_bf16 v[124:127], v[128:131], v[144:147], v[124:127]
	v_mfma_f32_16x16x32_bf16 v[120:123], v[136:139], v[144:147], v[120:123]
	v_mfma_f32_16x16x32_bf16 v[108:111], v[128:131], v[152:155], v[108:111]
	v_mfma_f32_16x16x32_bf16 v[104:107], v[136:139], v[152:155], v[104:107]
	v_mfma_f32_16x16x32_bf16 v[92:95], v[128:131], v[160:163], v[92:95]
	v_mfma_f32_16x16x32_bf16 v[88:91], v[136:139], v[160:163], v[88:91]
	v_mfma_f32_16x16x32_bf16 v[76:79], v[128:131], v[184:187], v[76:79]
	v_mfma_f32_16x16x32_bf16 v[72:75], v[136:139], v[184:187], v[72:75]
	v_mfma_f32_16x16x32_bf16 v[124:127], v[132:135], v[148:151], v[124:127]
	v_mfma_f32_16x16x32_bf16 v[120:123], v[140:143], v[148:151], v[120:123]
	v_mfma_f32_16x16x32_bf16 v[108:111], v[132:135], v[156:159], v[108:111]
	v_mfma_f32_16x16x32_bf16 v[104:107], v[140:143], v[156:159], v[104:107]
	v_mfma_f32_16x16x32_bf16 v[92:95], v[132:135], v[180:183], v[92:95]
	v_mfma_f32_16x16x32_bf16 v[88:91], v[140:143], v[180:183], v[88:91]
	v_mfma_f32_16x16x32_bf16 v[76:79], v[132:135], v[188:191], v[76:79]
	v_mfma_f32_16x16x32_bf16 v[72:75], v[140:143], v[188:191], v[72:75]
	s_barrier
	s_add_i32 s65, s29, s20
	v_lshl_add_u64 v[164:165], s[38:39], 0, v[168:169]
	s_mov_b32 m0, s65
	ds_read_b128 v[192:195], v203
	ds_read_b128 v[206:209], v203 offset:1024
	ds_read_b128 v[210:213], v203 offset:2048
	ds_read_b128 v[214:217], v203 offset:3072
	global_load_lds_dwordx4 v[164:165], off
	v_lshl_add_u64 v[218:219], s[38:39], 0, v[172:173]
	s_add_i32 m0, s65, 0x2000
	s_nop 0
	global_load_lds_dwordx4 v[218:219], off
	s_barrier
	s_waitcnt lgkmcnt(0)
	v_mfma_f32_16x16x32_bf16 v[116:119], v[192:195], v[144:147], v[116:119]
	v_mfma_f32_16x16x32_bf16 v[112:115], v[210:213], v[144:147], v[112:115]
	v_mfma_f32_16x16x32_bf16 v[100:103], v[192:195], v[152:155], v[100:103]
	v_mfma_f32_16x16x32_bf16 v[96:99], v[210:213], v[152:155], v[96:99]
	v_mfma_f32_16x16x32_bf16 v[84:87], v[192:195], v[160:163], v[84:87]
	v_mfma_f32_16x16x32_bf16 v[80:83], v[210:213], v[160:163], v[80:83]
	v_mfma_f32_16x16x32_bf16 v[68:71], v[192:195], v[184:187], v[68:71]
	v_mfma_f32_16x16x32_bf16 v[64:67], v[210:213], v[184:187], v[64:67]
	v_mfma_f32_16x16x32_bf16 v[116:119], v[206:209], v[148:151], v[116:119]
	v_mfma_f32_16x16x32_bf16 v[112:115], v[214:217], v[148:151], v[112:115]
	v_mfma_f32_16x16x32_bf16 v[100:103], v[206:209], v[156:159], v[100:103]
	v_mfma_f32_16x16x32_bf16 v[96:99], v[214:217], v[156:159], v[96:99]
	v_mfma_f32_16x16x32_bf16 v[84:87], v[206:209], v[180:183], v[84:87]
	v_mfma_f32_16x16x32_bf16 v[80:83], v[214:217], v[180:183], v[80:83]
	v_mfma_f32_16x16x32_bf16 v[68:71], v[206:209], v[188:191], v[68:71]
	v_mfma_f32_16x16x32_bf16 v[64:67], v[214:217], v[188:191], v[64:67]
	s_mov_b32 m0, s61
	v_lshl_add_u64 v[220:221], s[16:17], 0, v[166:167]
	s_barrier
	ds_read_b128 v[144:147], v202 offset:16384
	ds_read_b128 v[148:151], v202 offset:17408
	ds_read_b128 v[152:155], v202 offset:18432
	ds_read_b128 v[156:159], v202 offset:19456
	ds_read_b128 v[160:163], v202 offset:20480
	ds_read_b128 v[180:183], v202 offset:21504
	ds_read_b128 v[184:187], v202 offset:22528
	ds_read_b128 v[188:191], v202 offset:23552
	global_load_lds_dwordx4 v[220:221], off
	v_lshl_add_u64 v[222:223], s[16:17], 0, v[170:171]
	s_mov_b32 m0, s22
	s_nop 0
	global_load_lds_dwordx4 v[222:223], off
	s_barrier
	s_waitcnt lgkmcnt(0)
	v_mfma_f32_16x16x32_bf16 v[60:63], v[128:131], v[144:147], v[60:63]
	v_mfma_f32_16x16x32_bf16 v[56:59], v[136:139], v[144:147], v[56:59]
	v_mfma_f32_16x16x32_bf16 v[44:47], v[128:131], v[152:155], v[44:47]
	v_mfma_f32_16x16x32_bf16 v[40:43], v[136:139], v[152:155], v[40:43]
	v_mfma_f32_16x16x32_bf16 v[28:31], v[128:131], v[160:163], v[28:31]
	v_mfma_f32_16x16x32_bf16 v[24:27], v[136:139], v[160:163], v[24:27]
	v_mfma_f32_16x16x32_bf16 v[12:15], v[128:131], v[184:187], v[12:15]
	v_mfma_f32_16x16x32_bf16 v[8:11], v[136:139], v[184:187], v[8:11]
	v_mfma_f32_16x16x32_bf16 v[60:63], v[132:135], v[148:151], v[60:63]
	v_mfma_f32_16x16x32_bf16 v[56:59], v[140:143], v[148:151], v[56:59]
	v_mfma_f32_16x16x32_bf16 v[44:47], v[132:135], v[156:159], v[44:47]
	v_mfma_f32_16x16x32_bf16 v[40:43], v[140:143], v[156:159], v[40:43]
	v_mfma_f32_16x16x32_bf16 v[28:31], v[132:135], v[180:183], v[28:31]
	v_mfma_f32_16x16x32_bf16 v[24:27], v[140:143], v[180:183], v[24:27]
	v_mfma_f32_16x16x32_bf16 v[12:15], v[132:135], v[188:191], v[12:15]
	v_mfma_f32_16x16x32_bf16 v[8:11], v[140:143], v[188:191], v[8:11]
	s_barrier
; #define PG8_STAGE(bufoff, gbase, voff) do { _Pragma("unroll") for (int _i = 0; _i < 2; ++_i) \
;         __builtin_amdgcn_global_load_lds((const unsigned*)((const char*)(gbase) + (voff)[_i]), (LAS unsigned*)(lds + (bufoff) + ldsw + _i * 8192), 16, 0, 0); } while (0)
; #define PG8_LDA(dst, b, h) do { _Pragma("unroll") for (int m = 0; m < 4; ++m) _Pragma("unroll") for (int k = 0; k < 2; ++k) dst[m][k] = *(const LAS bf16x8*)(lds + PG8_SA(b, h) + aoff + m * 2048 + k * 1024); } while (0)
; #define PG8_LDB(dst, b, h) do { _Pragma("unroll") for (int n = 0; n < 2; ++n) _Pragma("unroll") for (int k = 0; k < 2; ++k) dst[n][k] = *(const LAS bf16x8*)(lds + PG8_SB(b, h) + boff + n * 2048 + k * 1024); } while (0)
; #define PG8_MMA(ai, bj, At, Bt) do { __builtin_amdgcn_s_setprio(1); _Pragma("unroll") for (int m = 0; m < 4; ++m) _Pragma("unroll") for (int n = 0; n < 2; ++n) _Pragma("unroll") for (int k = 0; k < 2; ++k) \
;         acc[ai][bj][m][n] = __builtin_amdgcn_mfma_f32_16x16x32_bf16(Bt[n][k], At[m][k], acc[ai][bj][m][n], 0, 0, 0); __builtin_amdgcn_s_setprio(0); } while (0)
; #define PG8_WAIT_V(n) asm volatile("s_waitcnt vmcnt(" #n ")" ::: "memory")
; #define PG8_WAIT_L(n) asm volatile("s_waitcnt lgkmcnt(" #n ")" ::: "memory")
; #define PG8_BAR __builtin_amdgcn_s_barrier()
; #define PG8_SCHED __builtin_amdgcn_sched_barrier(0)
; template <class Epi>
; DEVI void gemm_phase(LAS unsigned char* lds, const bf16_t* gA, const bf16_t* gBt, const int lda, const int ldb, const int K, const StaticOrder S_, const Epi E) {
;     ...
;             PG8_STAGE(PG8_SB(0, 1), b2 + hstepB, voffB);
;             PG8_WAIT_V(6); PG8_BAR; PG8_MMA(1, 1, At, B1); PG8_BAR;
;             PG8_LDB(B0, 1, 0); PG8_SCHED; PG8_LDA(At, 1, 0); PG8_STAGE(PG8_SA(0, 1), a2 + hstepA, voffA);
;             PG8_WAIT_L(8); PG8_BAR; PG8_WAIT_L(0); PG8_MMA(0, 0, At, B0); PG8_BAR; PG8_SCHED;
;             PG8_LDB(B1, 1, 1); PG8_STAGE(PG8_SB(1, 0), b3, voffB);
;             PG8_BAR; PG8_WAIT_L(0); PG8_MMA(0, 1, At, B1); PG8_BAR;
	s_add_u32 s38, s38, s2
	s_addc_u32 s39, s39, s3
	s_add_i32 s65, s50, s20
	v_lshl_add_u64 v[224:225], s[38:39], 0, v[168:169]
	s_mov_b32 m0, s65
	v_lshl_add_u64 v[226:227], s[38:39], 0, v[172:173]
	global_load_lds_dwordx4 v[224:225], off
	s_add_i32 m0, s65, 0x2000
	s_nop 0
	global_load_lds_dwordx4 v[226:227], off
	s_waitcnt vmcnt(6)
	s_barrier
	v_mfma_f32_16x16x32_bf16 v[52:55], v[192:195], v[144:147], v[52:55]
	v_mfma_f32_16x16x32_bf16 v[48:51], v[210:213], v[144:147], v[48:51]
	v_mfma_f32_16x16x32_bf16 v[36:39], v[192:195], v[152:155], v[36:39]
	v_mfma_f32_16x16x32_bf16 v[32:35], v[210:213], v[152:155], v[32:35]
	v_mfma_f32_16x16x32_bf16 v[20:23], v[192:195], v[160:163], v[20:23]
	v_mfma_f32_16x16x32_bf16 v[16:19], v[210:213], v[160:163], v[16:19]
	v_mfma_f32_16x16x32_bf16 v[4:7], v[192:195], v[184:187], v[4:7]
	v_mfma_f32_16x16x32_bf16 v[0:3], v[210:213], v[184:187], v[0:3]
	v_mfma_f32_16x16x32_bf16 v[52:55], v[206:209], v[148:151], v[52:55]
	v_mfma_f32_16x16x32_bf16 v[48:51], v[214:217], v[148:151], v[48:51]
	v_mfma_f32_16x16x32_bf16 v[36:39], v[206:209], v[156:159], v[36:39]
	v_mfma_f32_16x16x32_bf16 v[32:35], v[214:217], v[156:159], v[32:35]
	v_mfma_f32_16x16x32_bf16 v[20:23], v[206:209], v[180:183], v[20:23]
	v_mfma_f32_16x16x32_bf16 v[16:19], v[214:217], v[180:183], v[16:19]
	v_mfma_f32_16x16x32_bf16 v[4:7], v[206:209], v[188:191], v[4:7]
	v_mfma_f32_16x16x32_bf16 v[0:3], v[214:217], v[188:191], v[0:3]
	s_add_i32 s38, 0, 0x18000
	v_add_u32_e32 v140, s38, v199
	s_barrier
	ds_read_b128 v[128:131], v140
	ds_read_b128 v[132:135], v140 offset:1024
	ds_read_b128 v[136:139], v140 offset:2048
	ds_read_b128 v[140:143], v140 offset:3072
	s_add_u32 s16, s16, s0
	s_addc_u32 s17, s17, s1
	s_mov_b32 m0, s23
	v_lshl_add_u64 v[192:193], s[16:17], 0, v[166:167]
	ds_read_b128 v[144:147], v202 offset:32768
	ds_read_b128 v[148:151], v202 offset:33792
	ds_read_b128 v[152:155], v202 offset:34816
	ds_read_b128 v[156:159], v202 offset:35840
	ds_read_b128 v[160:163], v202 offset:36864
	ds_read_b128 v[180:183], v202 offset:37888
	ds_read_b128 v[184:187], v202 offset:38912
	ds_read_b128 v[188:191], v202 offset:39936
	global_load_lds_dwordx4 v[192:193], off
	v_lshl_add_u64 v[192:193], s[16:17], 0, v[170:171]
	s_mov_b32 m0, s24
	s_nop 0
	global_load_lds_dwordx4 v[192:193], off
	s_waitcnt lgkmcnt(8)
	s_barrier
	s_waitcnt lgkmcnt(0)
	v_mfma_f32_16x16x32_bf16 v[124:127], v[128:131], v[144:147], v[124:127]
	v_mfma_f32_16x16x32_bf16 v[120:123], v[136:139], v[144:147], v[120:123]
	v_mfma_f32_16x16x32_bf16 v[108:111], v[128:131], v[152:155], v[108:111]
	v_mfma_f32_16x16x32_bf16 v[104:107], v[136:139], v[152:155], v[104:107]
	v_mfma_f32_16x16x32_bf16 v[92:95], v[128:131], v[160:163], v[92:95]
	v_mfma_f32_16x16x32_bf16 v[88:91], v[136:139], v[160:163], v[88:91]
	v_mfma_f32_16x16x32_bf16 v[76:79], v[128:131], v[184:187], v[76:79]
	v_mfma_f32_16x16x32_bf16 v[72:75], v[136:139], v[184:187], v[72:75]
	v_mfma_f32_16x16x32_bf16 v[124:127], v[132:135], v[148:151], v[124:127]
	v_mfma_f32_16x16x32_bf16 v[120:123], v[140:143], v[148:151], v[120:123]
	v_mfma_f32_16x16x32_bf16 v[108:111], v[132:135], v[156:159], v[108:111]
	v_mfma_f32_16x16x32_bf16 v[104:107], v[140:143], v[156:159], v[104:107]
	v_mfma_f32_16x16x32_bf16 v[92:95], v[132:135], v[180:183], v[92:95]
	v_mfma_f32_16x16x32_bf16 v[88:91], v[140:143], v[180:183], v[88:91]
	v_mfma_f32_16x16x32_bf16 v[76:79], v[132:135], v[188:191], v[76:79]
	v_mfma_f32_16x16x32_bf16 v[72:75], v[140:143], v[188:191], v[72:75]
	s_barrier
	s_add_i32 s16, 0, 0x1c000
	s_add_i32 s17, s38, s20
	v_add_u32_e32 v205, s16, v199
	v_lshl_add_u64 v[164:165], v[164:165], 0, s[8:9]
	s_mov_b32 m0, s17
	ds_read_b128 v[192:195], v205
	ds_read_b128 v[206:209], v205 offset:1024
	ds_read_b128 v[210:213], v205 offset:2048
	ds_read_b128 v[214:217], v205 offset:3072
	global_load_lds_dwordx4 v[164:165], off
	v_lshl_add_u64 v[164:165], v[218:219], 0, s[8:9]
	s_add_i32 m0, s17, 0x2000
	s_nop 0
	global_load_lds_dwordx4 v[164:165], off
	s_barrier
; #define LAS __attribute__((address_space(3)))
; #define PG8_STAGE(bufoff, gbase, voff) do { _Pragma("unroll") for (int _i = 0; _i < 2; ++_i) \
;         __builtin_amdgcn_global_load_lds((const unsigned*)((const char*)(gbase) + (voff)[_i]), (LAS unsigned*)(lds + (bufoff) + ldsw + _i * 8192), 16, 0, 0); } while (0)
; #define PG8_LDA(dst, b, h) do { _Pragma("unroll") for (int m = 0; m < 4; ++m) _Pragma("unroll") for (int k = 0; k < 2; ++k) dst[m][k] = *(const LAS bf16x8*)(lds + PG8_SA(b, h) + aoff + m * 2048 + k * 1024); } while (0)
; #define PG8_MMA(ai, bj, At, Bt) do { __builtin_amdgcn_s_setprio(1); _Pragma("unroll") for (int m = 0; m < 4; ++m) _Pragma("unroll") for (int n = 0; n < 2; ++n) _Pragma("unroll") for (int k = 0; k < 2; ++k) \
;         acc[ai][bj][m][n] = __builtin_amdgcn_mfma_f32_16x16x32_bf16(Bt[n][k], At[m][k], acc[ai][bj][m][n], 0, 0, 0); __builtin_amdgcn_s_setprio(0); } while (0)
; #define PG8_WAIT_V(n) asm volatile("s_waitcnt vmcnt(" #n ")" ::: "memory")
; #define PG8_WAIT_L(n) asm volatile("s_waitcnt lgkmcnt(" #n ")" ::: "memory")
; #define PG8_BAR __builtin_amdgcn_s_barrier()
; #define PG8_SCHED __builtin_amdgcn_sched_barrier(0)
; template <class Epi>
; DEVI void gemm_phase(LAS unsigned char* lds, const bf16_t* gA, const bf16_t* gBt, const int lda, const int ldb, const int K, const StaticOrder S_, const Epi E) {
;     ...
;             PG8_BAR; PG8_WAIT_L(0); PG8_MMA(0, 1, At, B1); PG8_BAR;
;             PG8_LDA(At, 1, 1); PG8_STAGE(PG8_SA(1, 0), a3, voffA);
;             PG8_BAR; PG8_WAIT_L(0); PG8_MMA(1, 0, At, B0); PG8_BAR; PG8_SCHED;
;             PG8_STAGE(PG8_SB(1, 1), b3 + hstepB, voffB);
;             PG8_WAIT_V(6); PG8_BAR; PG8_MMA(1, 1, At, B1); PG8_BAR;
;         }
;         E(acc, cur, wr, wc, fr, fq, (const LAS float*)(lds + STAGE_BYTES + (ui & 1) * 2048));
;         if (!has_next) break;
; #pragma unroll
;         for (int a = 0; a < 2; ++a)
; #pragma unroll
;             for (int b = 0; b < 2; ++b)
; #pragma unroll
;                 for (int m = 0; m < 4; ++m)
; #pragma unroll
;                     for (int n = 0; n < 2; ++n) acc[a][b][m][n] = (f32x4){0.f, 0.f, 0.f, 0.f};
;         cur = nxt; cA = nA; cB = nB; ++ui;
;         rs_prefetch(cur, ui & 1);
;     }
	s_waitcnt lgkmcnt(0)
	v_mfma_f32_16x16x32_bf16 v[116:119], v[192:195], v[144:147], v[116:119]
	v_mfma_f32_16x16x32_bf16 v[112:115], v[210:213], v[144:147], v[112:115]
	v_mfma_f32_16x16x32_bf16 v[100:103], v[192:195], v[152:155], v[100:103]
	v_mfma_f32_16x16x32_bf16 v[96:99], v[210:213], v[152:155], v[96:99]
	v_mfma_f32_16x16x32_bf16 v[84:87], v[192:195], v[160:163], v[84:87]
	v_mfma_f32_16x16x32_bf16 v[80:83], v[210:213], v[160:163], v[80:83]
	v_mfma_f32_16x16x32_bf16 v[68:71], v[192:195], v[184:187], v[68:71]
	v_mfma_f32_16x16x32_bf16 v[64:67], v[210:213], v[184:187], v[64:67]
	v_mfma_f32_16x16x32_bf16 v[116:119], v[206:209], v[148:151], v[116:119]
	v_mfma_f32_16x16x32_bf16 v[112:115], v[214:217], v[148:151], v[112:115]
	v_mfma_f32_16x16x32_bf16 v[100:103], v[206:209], v[156:159], v[100:103]
	v_mfma_f32_16x16x32_bf16 v[96:99], v[214:217], v[156:159], v[96:99]
	v_mfma_f32_16x16x32_bf16 v[84:87], v[206:209], v[180:183], v[84:87]
	v_mfma_f32_16x16x32_bf16 v[80:83], v[214:217], v[180:183], v[80:83]
	v_mfma_f32_16x16x32_bf16 v[68:71], v[206:209], v[188:191], v[68:71]
	v_mfma_f32_16x16x32_bf16 v[64:67], v[214:217], v[188:191], v[64:67]
	s_mov_b32 m0, s26
	v_lshl_add_u64 v[164:165], v[220:221], 0, s[8:9]
	s_barrier
	ds_read_b128 v[144:147], v202 offset:49152
	ds_read_b128 v[148:151], v202 offset:50176
	ds_read_b128 v[152:155], v202 offset:51200
	ds_read_b128 v[156:159], v202 offset:52224
	ds_read_b128 v[160:163], v202 offset:53248
	ds_read_b128 v[180:183], v202 offset:54272
	ds_read_b128 v[184:187], v202 offset:55296
	ds_read_b128 v[188:191], v202 offset:56320
	global_load_lds_dwordx4 v[164:165], off
	v_lshl_add_u64 v[164:165], v[222:223], 0, s[8:9]
	s_mov_b32 m0, s27
	s_nop 0
	global_load_lds_dwordx4 v[164:165], off
	s_barrier
	s_waitcnt lgkmcnt(0)
	v_mfma_f32_16x16x32_bf16 v[60:63], v[128:131], v[144:147], v[60:63]
	v_mfma_f32_16x16x32_bf16 v[56:59], v[136:139], v[144:147], v[56:59]
	v_mfma_f32_16x16x32_bf16 v[44:47], v[128:131], v[152:155], v[44:47]
	v_mfma_f32_16x16x32_bf16 v[40:43], v[136:139], v[152:155], v[40:43]
	v_mfma_f32_16x16x32_bf16 v[28:31], v[128:131], v[160:163], v[28:31]
	v_mfma_f32_16x16x32_bf16 v[24:27], v[136:139], v[160:163], v[24:27]
	v_mfma_f32_16x16x32_bf16 v[12:15], v[128:131], v[184:187], v[12:15]
	v_mfma_f32_16x16x32_bf16 v[8:11], v[136:139], v[184:187], v[8:11]
	v_mfma_f32_16x16x32_bf16 v[60:63], v[132:135], v[148:151], v[60:63]
	v_mfma_f32_16x16x32_bf16 v[56:59], v[140:143], v[148:151], v[56:59]
	v_mfma_f32_16x16x32_bf16 v[44:47], v[132:135], v[156:159], v[44:47]
	v_mfma_f32_16x16x32_bf16 v[40:43], v[140:143], v[156:159], v[40:43]
	v_mfma_f32_16x16x32_bf16 v[28:31], v[132:135], v[180:183], v[28:31]
	v_mfma_f32_16x16x32_bf16 v[24:27], v[140:143], v[180:183], v[24:27]
	v_mfma_f32_16x16x32_bf16 v[12:15], v[132:135], v[188:191], v[12:15]
	v_mfma_f32_16x16x32_bf16 v[8:11], v[140:143], v[188:191], v[8:11]
	s_barrier
	s_add_i32 s16, s16, s20
	v_lshl_add_u64 v[128:129], v[224:225], 0, s[8:9]
	s_mov_b32 m0, s16
	s_nop 0
	global_load_lds_dwordx4 v[128:129], off
	v_lshl_add_u64 v[128:129], v[226:227], 0, s[8:9]
	s_add_i32 m0, s16, 0x2000
	s_nop 0
	global_load_lds_dwordx4 v[128:129], off
	s_waitcnt vmcnt(6)
	s_barrier
	v_mfma_f32_16x16x32_bf16 v[52:55], v[192:195], v[144:147], v[52:55]
	v_mfma_f32_16x16x32_bf16 v[48:51], v[210:213], v[144:147], v[48:51]
	v_mfma_f32_16x16x32_bf16 v[36:39], v[192:195], v[152:155], v[36:39]
	v_mfma_f32_16x16x32_bf16 v[32:35], v[210:213], v[152:155], v[32:35]
	v_mfma_f32_16x16x32_bf16 v[20:23], v[192:195], v[160:163], v[20:23]
	v_mfma_f32_16x16x32_bf16 v[16:19], v[210:213], v[160:163], v[16:19]
	v_mfma_f32_16x16x32_bf16 v[4:7], v[192:195], v[184:187], v[4:7]
	v_mfma_f32_16x16x32_bf16 v[0:3], v[210:213], v[184:187], v[0:3]
	v_mfma_f32_16x16x32_bf16 v[52:55], v[206:209], v[148:151], v[52:55]
	v_mfma_f32_16x16x32_bf16 v[48:51], v[214:217], v[148:151], v[48:51]
	v_mfma_f32_16x16x32_bf16 v[36:39], v[206:209], v[156:159], v[36:39]
	v_mfma_f32_16x16x32_bf16 v[32:35], v[214:217], v[156:159], v[32:35]
	v_mfma_f32_16x16x32_bf16 v[20:23], v[206:209], v[180:183], v[20:23]
	v_mfma_f32_16x16x32_bf16 v[16:19], v[214:217], v[180:183], v[16:19]
	v_mfma_f32_16x16x32_bf16 v[4:7], v[206:209], v[188:191], v[4:7]
	v_mfma_f32_16x16x32_bf16 v[0:3], v[214:217], v[188:191], v[0:3]
	s_add_u32 s14, s14, 0x100
	s_addc_u32 s15, s15, 0
	s_add_u32 s56, s56, 0x100
	s_addc_u32 s57, s57, 0
	s_cmp_ge_i32 s64, s25
	s_mov_b32 s16, s64
	s_barrier
	s_cbranch_scc0 .LBB0_1848
	v_readlane_b32 s64, v241, 0
	v_readlane_b32 s66, v241, 2
	v_readlane_b32 s65, v241, 1
	v_readlane_b32 s67, v241, 3

; #define PG8_STAGE(bufoff, gbase, voff) do { _Pragma("unroll") for (int _i = 0; _i < 2; ++_i) \
;         __builtin_amdgcn_global_load_lds((const unsigned*)((const char*)(gbase) + (voff)[_i]), (LAS unsigned*)(lds + (bufoff) + ldsw + _i * 8192), 16, 0, 0); } while (0)
; #define PG8_LDA(dst, b, h) do { _Pragma("unroll") for (int m = 0; m < 4; ++m) _Pragma("unroll") for (int k = 0; k < 2; ++k) dst[m][k] = *(const LAS bf16x8*)(lds + PG8_SA(b, h) + aoff + m * 2048 + k * 1024); } while (0)
; #define PG8_LDB(dst, b, h) do { _Pragma("unroll") for (int n = 0; n < 2; ++n) _Pragma("unroll") for (int k = 0; k < 2; ++k) dst[n][k] = *(const LAS bf16x8*)(lds + PG8_SB(b, h) + boff + n * 2048 + k * 1024); } while (0)
; #define PG8_MMA(ai, bj, At, Bt) do { __builtin_amdgcn_s_setprio(1); _Pragma("unroll") for (int m = 0; m < 4; ++m) _Pragma("unroll") for (int n = 0; n < 2; ++n) _Pragma("unroll") for (int k = 0; k < 2; ++k) \
;         acc[ai][bj][m][n] = __builtin_amdgcn_mfma_f32_16x16x32_bf16(Bt[n][k], At[m][k], acc[ai][bj][m][n], 0, 0, 0); __builtin_amdgcn_s_setprio(0); } while (0)
; #define PG8_WAIT_L(n) asm volatile("s_waitcnt lgkmcnt(" #n ")" ::: "memory")
; #define PG8_BAR __builtin_amdgcn_s_barrier()
; #define PG8_SCHED __builtin_amdgcn_sched_barrier(0)
; template <class Epi>
; DEVI void gemm_phase(LAS unsigned char* lds, const bf16_t* gA, const bf16_t* gBt, const int lda, const int ldb, const int K, const StaticOrder S_, const Epi E) {
;     ...
;             PG8_LDB(B0, 0, 0); PG8_SCHED; PG8_LDA(At, 0, 0); PG8_STAGE(PG8_SA(1, 1), a1 + hstepA, voffA);
;             PG8_WAIT_L(8); PG8_BAR; PG8_WAIT_L(0); PG8_MMA(0, 0, At, B0); PG8_BAR; PG8_SCHED;
;             PG8_LDB(B1, 0, 1); PG8_STAGE(PG8_SB(0, 0), b2, voffB);
;             PG8_BAR; PG8_WAIT_L(0); PG8_MMA(0, 1, At, B1); PG8_BAR;
;             PG8_LDA(At, 0, 1); PG8_STAGE(PG8_SA(0, 0), a2, voffA);
;             PG8_BAR; PG8_WAIT_L(0); PG8_MMA(1, 0, At, B0); PG8_BAR; PG8_SCHED;
.LBB0_1980:
	ds_read_b128 v[160:163], v153
	ds_read_b128 v[164:167], v153 offset:1024
	ds_read_b128 v[168:171], v153 offset:2048
	ds_read_b128 v[172:175], v153 offset:3072
	s_add_i32 s70, s16, 2
	s_add_u32 s38, s14, 0x80
	s_addc_u32 s17, s15, 0
	s_cmp_eq_u32 s26, s16
	s_cselect_b32 s16, s54, s38
	s_cselect_b32 s17, s55, s17
	s_cselect_b32 s39, s57, s61
	s_cselect_b32 s38, s56, s60
	v_lshl_add_u64 v[144:145], s[14:15], 0, v[138:139]
	s_add_i32 m0, s19, 0xc000
	ds_read_b128 v[176:179], v154
	ds_read_b128 v[180:183], v154 offset:1024
	ds_read_b128 v[184:187], v154 offset:2048
	ds_read_b128 v[188:191], v154 offset:3072
	ds_read_b128 v[192:195], v154 offset:4096
	ds_read_b128 v[198:201], v154 offset:5120
	ds_read_b128 v[202:205], v154 offset:6144
	ds_read_b128 v[206:209], v154 offset:7168
	global_load_lds_dwordx4 v[144:145], off
	v_lshl_add_u64 v[144:145], s[14:15], 0, v[140:141]
	s_add_i32 m0, s19, 0xe000
	s_nop 0
	global_load_lds_dwordx4 v[144:145], off
	s_waitcnt lgkmcnt(8)
	s_barrier
	s_waitcnt lgkmcnt(0)
	v_mfma_f32_16x16x32_bf16 v[124:127], v[160:163], v[176:179], v[124:127]
	v_mfma_f32_16x16x32_bf16 v[120:123], v[168:171], v[176:179], v[120:123]
	v_mfma_f32_16x16x32_bf16 v[108:111], v[160:163], v[184:187], v[108:111]
	v_mfma_f32_16x16x32_bf16 v[104:107], v[168:171], v[184:187], v[104:107]
	v_mfma_f32_16x16x32_bf16 v[92:95], v[160:163], v[192:195], v[92:95]
	v_mfma_f32_16x16x32_bf16 v[88:91], v[168:171], v[192:195], v[88:91]
	v_mfma_f32_16x16x32_bf16 v[76:79], v[160:163], v[202:205], v[76:79]
	v_mfma_f32_16x16x32_bf16 v[72:75], v[168:171], v[202:205], v[72:75]
	v_mfma_f32_16x16x32_bf16 v[124:127], v[164:167], v[180:183], v[124:127]
	v_mfma_f32_16x16x32_bf16 v[120:123], v[172:175], v[180:183], v[120:123]
	v_mfma_f32_16x16x32_bf16 v[108:111], v[164:167], v[188:191], v[108:111]
	v_mfma_f32_16x16x32_bf16 v[104:107], v[172:175], v[188:191], v[104:107]
	v_mfma_f32_16x16x32_bf16 v[92:95], v[164:167], v[198:201], v[92:95]
	v_mfma_f32_16x16x32_bf16 v[88:91], v[172:175], v[198:201], v[88:91]
	v_mfma_f32_16x16x32_bf16 v[76:79], v[164:167], v[206:209], v[76:79]
	v_mfma_f32_16x16x32_bf16 v[72:75], v[172:175], v[206:209], v[72:75]
	s_barrier
	s_add_i32 s71, s31, s18
	v_lshl_add_u64 v[144:145], s[38:39], 0, v[130:131]
	s_mov_b32 m0, s71
	ds_read_b128 v[210:213], v155
	ds_read_b128 v[214:217], v155 offset:1024
	ds_read_b128 v[218:221], v155 offset:2048
	ds_read_b128 v[222:225], v155 offset:3072
	global_load_lds_dwordx4 v[144:145], off
	v_lshl_add_u64 v[226:227], s[38:39], 0, v[134:135]
	s_add_i32 m0, s71, 0x2000
	s_nop 0
	global_load_lds_dwordx4 v[226:227], off
	s_barrier
	s_waitcnt lgkmcnt(0)
	v_mfma_f32_16x16x32_bf16 v[116:119], v[210:213], v[176:179], v[116:119]
	v_mfma_f32_16x16x32_bf16 v[112:115], v[218:221], v[176:179], v[112:115]
	v_mfma_f32_16x16x32_bf16 v[100:103], v[210:213], v[184:187], v[100:103]
	v_mfma_f32_16x16x32_bf16 v[96:99], v[218:221], v[184:187], v[96:99]
	v_mfma_f32_16x16x32_bf16 v[84:87], v[210:213], v[192:195], v[84:87]
	v_mfma_f32_16x16x32_bf16 v[80:83], v[218:221], v[192:195], v[80:83]
	v_mfma_f32_16x16x32_bf16 v[68:71], v[210:213], v[202:205], v[68:71]
	v_mfma_f32_16x16x32_bf16 v[64:67], v[218:221], v[202:205], v[64:67]
	v_mfma_f32_16x16x32_bf16 v[116:119], v[214:217], v[180:183], v[116:119]
	v_mfma_f32_16x16x32_bf16 v[112:115], v[222:225], v[180:183], v[112:115]
	v_mfma_f32_16x16x32_bf16 v[100:103], v[214:217], v[188:191], v[100:103]
	v_mfma_f32_16x16x32_bf16 v[96:99], v[222:225], v[188:191], v[96:99]
	v_mfma_f32_16x16x32_bf16 v[84:87], v[214:217], v[198:201], v[84:87]
	v_mfma_f32_16x16x32_bf16 v[80:83], v[222:225], v[198:201], v[80:83]
	v_mfma_f32_16x16x32_bf16 v[68:71], v[214:217], v[206:209], v[68:71]
	v_mfma_f32_16x16x32_bf16 v[64:67], v[222:225], v[206:209], v[64:67]
	s_mov_b32 m0, s19
	v_lshl_add_u64 v[228:229], s[16:17], 0, v[128:129]
	s_barrier
	ds_read_b128 v[176:179], v154 offset:16384
	ds_read_b128 v[180:183], v154 offset:17408
	ds_read_b128 v[184:187], v154 offset:18432
	ds_read_b128 v[188:191], v154 offset:19456
	ds_read_b128 v[192:195], v154 offset:20480
	ds_read_b128 v[198:201], v154 offset:21504
	ds_read_b128 v[202:205], v154 offset:22528
	ds_read_b128 v[206:209], v154 offset:23552
	global_load_lds_dwordx4 v[228:229], off
	v_lshl_add_u64 v[230:231], s[16:17], 0, v[132:133]
	s_mov_b32 m0, s20
	s_nop 0
	global_load_lds_dwordx4 v[230:231], off
	s_barrier
	s_waitcnt lgkmcnt(0)
	v_mfma_f32_16x16x32_bf16 v[60:63], v[160:163], v[176:179], v[60:63]
	v_mfma_f32_16x16x32_bf16 v[56:59], v[168:171], v[176:179], v[56:59]
	v_mfma_f32_16x16x32_bf16 v[44:47], v[160:163], v[184:187], v[44:47]
	v_mfma_f32_16x16x32_bf16 v[40:43], v[168:171], v[184:187], v[40:43]
	v_mfma_f32_16x16x32_bf16 v[28:31], v[160:163], v[192:195], v[28:31]
	v_mfma_f32_16x16x32_bf16 v[24:27], v[168:171], v[192:195], v[24:27]
	v_mfma_f32_16x16x32_bf16 v[12:15], v[160:163], v[202:205], v[12:15]
	v_mfma_f32_16x16x32_bf16 v[8:11], v[168:171], v[202:205], v[8:11]
	v_mfma_f32_16x16x32_bf16 v[60:63], v[164:167], v[180:183], v[60:63]
	v_mfma_f32_16x16x32_bf16 v[56:59], v[172:175], v[180:183], v[56:59]
	v_mfma_f32_16x16x32_bf16 v[44:47], v[164:167], v[188:191], v[44:47]
	v_mfma_f32_16x16x32_bf16 v[40:43], v[172:175], v[188:191], v[40:43]
	v_mfma_f32_16x16x32_bf16 v[28:31], v[164:167], v[198:201], v[28:31]
	v_mfma_f32_16x16x32_bf16 v[24:27], v[172:175], v[198:201], v[24:27]
	v_mfma_f32_16x16x32_bf16 v[12:15], v[164:167], v[206:209], v[12:15]
	v_mfma_f32_16x16x32_bf16 v[8:11], v[172:175], v[206:209], v[8:11]
	s_barrier
; #define PG8_STAGE(bufoff, gbase, voff) do { _Pragma("unroll") for (int _i = 0; _i < 2; ++_i) \
;         __builtin_amdgcn_global_load_lds((const unsigned*)((const char*)(gbase) + (voff)[_i]), (LAS unsigned*)(lds + (bufoff) + ldsw + _i * 8192), 16, 0, 0); } while (0)
; #define PG8_LDA(dst, b, h) do { _Pragma("unroll") for (int m = 0; m < 4; ++m) _Pragma("unroll") for (int k = 0; k < 2; ++k) dst[m][k] = *(const LAS bf16x8*)(lds + PG8_SA(b, h) + aoff + m * 2048 + k * 1024); } while (0)
; #define PG8_LDB(dst, b, h) do { _Pragma("unroll") for (int n = 0; n < 2; ++n) _Pragma("unroll") for (int k = 0; k < 2; ++k) dst[n][k] = *(const LAS bf16x8*)(lds + PG8_SB(b, h) + boff + n * 2048 + k * 1024); } while (0)
; #define PG8_MMA(ai, bj, At, Bt) do { __builtin_amdgcn_s_setprio(1); _Pragma("unroll") for (int m = 0; m < 4; ++m) _Pragma("unroll") for (int n = 0; n < 2; ++n) _Pragma("unroll") for (int k = 0; k < 2; ++k) \
;         acc[ai][bj][m][n] = __builtin_amdgcn_mfma_f32_16x16x32_bf16(Bt[n][k], At[m][k], acc[ai][bj][m][n], 0, 0, 0); __builtin_amdgcn_s_setprio(0); } while (0)
; #define PG8_WAIT_V(n) asm volatile("s_waitcnt vmcnt(" #n ")" ::: "memory")
; #define PG8_WAIT_L(n) asm volatile("s_waitcnt lgkmcnt(" #n ")" ::: "memory")
; #define PG8_BAR __builtin_amdgcn_s_barrier()
; #define PG8_SCHED __builtin_amdgcn_sched_barrier(0)
; template <class Epi>
; DEVI void gemm_phase(LAS unsigned char* lds, const bf16_t* gA, const bf16_t* gBt, const int lda, const int ldb, const int K, const StaticOrder S_, const Epi E) {
;     ...
;             PG8_STAGE(PG8_SB(0, 1), b2 + hstepB, voffB);
;             PG8_WAIT_V(6); PG8_BAR; PG8_MMA(1, 1, At, B1); PG8_BAR;
;             PG8_LDB(B0, 1, 0); PG8_SCHED; PG8_LDA(At, 1, 0); PG8_STAGE(PG8_SA(0, 1), a2 + hstepA, voffA);
;             PG8_WAIT_L(8); PG8_BAR; PG8_WAIT_L(0); PG8_MMA(0, 0, At, B0); PG8_BAR; PG8_SCHED;
;             PG8_LDB(B1, 1, 1); PG8_STAGE(PG8_SB(1, 0), b3, voffB);
;             PG8_BAR; PG8_WAIT_L(0); PG8_MMA(0, 1, At, B1); PG8_BAR;
	s_add_u32 s38, s38, s2
	s_addc_u32 s39, s39, s3
	s_add_i32 s71, s48, s18
	v_lshl_add_u64 v[232:233], s[38:39], 0, v[130:131]
	s_mov_b32 m0, s71
	v_lshl_add_u64 v[234:235], s[38:39], 0, v[134:135]
	global_load_lds_dwordx4 v[232:233], off
	s_add_i32 m0, s71, 0x2000
	s_nop 0
	global_load_lds_dwordx4 v[234:235], off
	s_waitcnt vmcnt(6)
	s_barrier
	v_mfma_f32_16x16x32_bf16 v[52:55], v[210:213], v[176:179], v[52:55]
	v_mfma_f32_16x16x32_bf16 v[48:51], v[218:221], v[176:179], v[48:51]
	v_mfma_f32_16x16x32_bf16 v[36:39], v[210:213], v[184:187], v[36:39]
	v_mfma_f32_16x16x32_bf16 v[32:35], v[218:221], v[184:187], v[32:35]
	v_mfma_f32_16x16x32_bf16 v[20:23], v[210:213], v[192:195], v[20:23]
	v_mfma_f32_16x16x32_bf16 v[16:19], v[218:221], v[192:195], v[16:19]
	v_mfma_f32_16x16x32_bf16 v[4:7], v[210:213], v[202:205], v[4:7]
	v_mfma_f32_16x16x32_bf16 v[0:3], v[218:221], v[202:205], v[0:3]
	v_mfma_f32_16x16x32_bf16 v[52:55], v[214:217], v[180:183], v[52:55]
	v_mfma_f32_16x16x32_bf16 v[48:51], v[222:225], v[180:183], v[48:51]
	v_mfma_f32_16x16x32_bf16 v[36:39], v[214:217], v[188:191], v[36:39]
	v_mfma_f32_16x16x32_bf16 v[32:35], v[222:225], v[188:191], v[32:35]
	v_mfma_f32_16x16x32_bf16 v[20:23], v[214:217], v[198:201], v[20:23]
	v_mfma_f32_16x16x32_bf16 v[16:19], v[222:225], v[198:201], v[16:19]
	v_mfma_f32_16x16x32_bf16 v[4:7], v[214:217], v[206:209], v[4:7]
	v_mfma_f32_16x16x32_bf16 v[0:3], v[222:225], v[206:209], v[0:3]
	s_barrier
	ds_read_b128 v[160:163], v156
	ds_read_b128 v[164:167], v156 offset:1024
	ds_read_b128 v[168:171], v156 offset:2048
	ds_read_b128 v[172:175], v156 offset:3072
	s_add_u32 s16, s16, s0
	s_addc_u32 s17, s17, s1
	s_mov_b32 m0, s21
	v_lshl_add_u64 v[210:211], s[16:17], 0, v[128:129]
	ds_read_b128 v[176:179], v154 offset:32768
	ds_read_b128 v[180:183], v154 offset:33792
	ds_read_b128 v[184:187], v154 offset:34816
	ds_read_b128 v[188:191], v154 offset:35840
	ds_read_b128 v[192:195], v154 offset:36864
	ds_read_b128 v[198:201], v154 offset:37888
	ds_read_b128 v[202:205], v154 offset:38912
	ds_read_b128 v[206:209], v154 offset:39936
	global_load_lds_dwordx4 v[210:211], off
	v_lshl_add_u64 v[210:211], s[16:17], 0, v[132:133]
	s_mov_b32 m0, s22
	s_nop 0
	global_load_lds_dwordx4 v[210:211], off
	s_waitcnt lgkmcnt(8)
	s_barrier
	s_waitcnt lgkmcnt(0)
	v_mfma_f32_16x16x32_bf16 v[124:127], v[160:163], v[176:179], v[124:127]
	v_mfma_f32_16x16x32_bf16 v[120:123], v[168:171], v[176:179], v[120:123]
	v_mfma_f32_16x16x32_bf16 v[108:111], v[160:163], v[184:187], v[108:111]
	v_mfma_f32_16x16x32_bf16 v[104:107], v[168:171], v[184:187], v[104:107]
	v_mfma_f32_16x16x32_bf16 v[92:95], v[160:163], v[192:195], v[92:95]
	v_mfma_f32_16x16x32_bf16 v[88:91], v[168:171], v[192:195], v[88:91]
	v_mfma_f32_16x16x32_bf16 v[76:79], v[160:163], v[202:205], v[76:79]
	v_mfma_f32_16x16x32_bf16 v[72:75], v[168:171], v[202:205], v[72:75]
	v_mfma_f32_16x16x32_bf16 v[124:127], v[164:167], v[180:183], v[124:127]
	v_mfma_f32_16x16x32_bf16 v[120:123], v[172:175], v[180:183], v[120:123]
	v_mfma_f32_16x16x32_bf16 v[108:111], v[164:167], v[188:191], v[108:111]
	v_mfma_f32_16x16x32_bf16 v[104:107], v[172:175], v[188:191], v[104:107]
	v_mfma_f32_16x16x32_bf16 v[92:95], v[164:167], v[198:201], v[92:95]
	v_mfma_f32_16x16x32_bf16 v[88:91], v[172:175], v[198:201], v[88:91]
	v_mfma_f32_16x16x32_bf16 v[76:79], v[164:167], v[206:209], v[76:79]
	v_mfma_f32_16x16x32_bf16 v[72:75], v[172:175], v[206:209], v[72:75]
	s_barrier
	s_add_i32 s16, s49, s18
	v_lshl_add_u64 v[144:145], v[144:145], 0, s[52:53]
	s_mov_b32 m0, s16
	ds_read_b128 v[210:213], v157
	ds_read_b128 v[214:217], v157 offset:1024
	ds_read_b128 v[218:221], v157 offset:2048
	ds_read_b128 v[222:225], v157 offset:3072
	global_load_lds_dwordx4 v[144:145], off
	v_lshl_add_u64 v[144:145], v[226:227], 0, s[52:53]
	s_add_i32 m0, s16, 0x2000
	s_nop 0
	global_load_lds_dwordx4 v[144:145], off
	s_barrier
; #define PG8_STAGE(bufoff, gbase, voff) do { _Pragma("unroll") for (int _i = 0; _i < 2; ++_i) \
;         __builtin_amdgcn_global_load_lds((const unsigned*)((const char*)(gbase) + (voff)[_i]), (LAS unsigned*)(lds + (bufoff) + ldsw + _i * 8192), 16, 0, 0); } while (0)
; #define PG8_LDA(dst, b, h) do { _Pragma("unroll") for (int m = 0; m < 4; ++m) _Pragma("unroll") for (int k = 0; k < 2; ++k) dst[m][k] = *(const LAS bf16x8*)(lds + PG8_SA(b, h) + aoff + m * 2048 + k * 1024); } while (0)
; #define PG8_MMA(ai, bj, At, Bt) do { __builtin_amdgcn_s_setprio(1); _Pragma("unroll") for (int m = 0; m < 4; ++m) _Pragma("unroll") for (int n = 0; n < 2; ++n) _Pragma("unroll") for (int k = 0; k < 2; ++k) \
;         acc[ai][bj][m][n] = __builtin_amdgcn_mfma_f32_16x16x32_bf16(Bt[n][k], At[m][k], acc[ai][bj][m][n], 0, 0, 0); __builtin_amdgcn_s_setprio(0); } while (0)
; #define PG8_WAIT_V(n) asm volatile("s_waitcnt vmcnt(" #n ")" ::: "memory")
; #define PG8_WAIT_L(n) asm volatile("s_waitcnt lgkmcnt(" #n ")" ::: "memory")
; #define PG8_BAR __builtin_amdgcn_s_barrier()
; #define PG8_SCHED __builtin_amdgcn_sched_barrier(0)
; template <class Epi>
; DEVI void gemm_phase(LAS unsigned char* lds, const bf16_t* gA, const bf16_t* gBt, const int lda, const int ldb, const int K, const StaticOrder S_, const Epi E) {
;     ...
;             PG8_BAR; PG8_WAIT_L(0); PG8_MMA(0, 1, At, B1); PG8_BAR;
;             PG8_LDA(At, 1, 1); PG8_STAGE(PG8_SA(1, 0), a3, voffA);
;             PG8_BAR; PG8_WAIT_L(0); PG8_MMA(1, 0, At, B0); PG8_BAR; PG8_SCHED;
;             PG8_STAGE(PG8_SB(1, 1), b3 + hstepB, voffB);
;             PG8_WAIT_V(6); PG8_BAR; PG8_MMA(1, 1, At, B1); PG8_BAR;
;         }
	s_waitcnt lgkmcnt(0)
	v_mfma_f32_16x16x32_bf16 v[116:119], v[210:213], v[176:179], v[116:119]
	v_mfma_f32_16x16x32_bf16 v[112:115], v[218:221], v[176:179], v[112:115]
	v_mfma_f32_16x16x32_bf16 v[100:103], v[210:213], v[184:187], v[100:103]
	v_mfma_f32_16x16x32_bf16 v[96:99], v[218:221], v[184:187], v[96:99]
	v_mfma_f32_16x16x32_bf16 v[84:87], v[210:213], v[192:195], v[84:87]
	v_mfma_f32_16x16x32_bf16 v[80:83], v[218:221], v[192:195], v[80:83]
	v_mfma_f32_16x16x32_bf16 v[68:71], v[210:213], v[202:205], v[68:71]
	v_mfma_f32_16x16x32_bf16 v[64:67], v[218:221], v[202:205], v[64:67]
	v_mfma_f32_16x16x32_bf16 v[116:119], v[214:217], v[180:183], v[116:119]
	v_mfma_f32_16x16x32_bf16 v[112:115], v[222:225], v[180:183], v[112:115]
	v_mfma_f32_16x16x32_bf16 v[100:103], v[214:217], v[188:191], v[100:103]
	v_mfma_f32_16x16x32_bf16 v[96:99], v[222:225], v[188:191], v[96:99]
	v_mfma_f32_16x16x32_bf16 v[84:87], v[214:217], v[198:201], v[84:87]
	v_mfma_f32_16x16x32_bf16 v[80:83], v[222:225], v[198:201], v[80:83]
	v_mfma_f32_16x16x32_bf16 v[68:71], v[214:217], v[206:209], v[68:71]
	v_mfma_f32_16x16x32_bf16 v[64:67], v[222:225], v[206:209], v[64:67]
	s_mov_b32 m0, s23
	v_lshl_add_u64 v[144:145], v[228:229], 0, s[52:53]
	s_barrier
	ds_read_b128 v[176:179], v154 offset:49152
	ds_read_b128 v[180:183], v154 offset:50176
	ds_read_b128 v[184:187], v154 offset:51200
	ds_read_b128 v[188:191], v154 offset:52224
	ds_read_b128 v[192:195], v154 offset:53248
	ds_read_b128 v[198:201], v154 offset:54272
	ds_read_b128 v[202:205], v154 offset:55296
	ds_read_b128 v[206:209], v154 offset:56320
	global_load_lds_dwordx4 v[144:145], off
	v_lshl_add_u64 v[144:145], v[230:231], 0, s[52:53]
	s_mov_b32 m0, s24
	s_nop 0
	global_load_lds_dwordx4 v[144:145], off
	s_barrier
	s_waitcnt lgkmcnt(0)
	v_mfma_f32_16x16x32_bf16 v[60:63], v[160:163], v[176:179], v[60:63]
	v_mfma_f32_16x16x32_bf16 v[56:59], v[168:171], v[176:179], v[56:59]
	v_mfma_f32_16x16x32_bf16 v[44:47], v[160:163], v[184:187], v[44:47]
	v_mfma_f32_16x16x32_bf16 v[40:43], v[168:171], v[184:187], v[40:43]
	v_mfma_f32_16x16x32_bf16 v[28:31], v[160:163], v[192:195], v[28:31]
	v_mfma_f32_16x16x32_bf16 v[24:27], v[168:171], v[192:195], v[24:27]
	v_mfma_f32_16x16x32_bf16 v[12:15], v[160:163], v[202:205], v[12:15]
	v_mfma_f32_16x16x32_bf16 v[8:11], v[168:171], v[202:205], v[8:11]
	v_mfma_f32_16x16x32_bf16 v[60:63], v[164:167], v[180:183], v[60:63]
	v_mfma_f32_16x16x32_bf16 v[56:59], v[172:175], v[180:183], v[56:59]
	v_mfma_f32_16x16x32_bf16 v[44:47], v[164:167], v[188:191], v[44:47]
	v_mfma_f32_16x16x32_bf16 v[40:43], v[172:175], v[188:191], v[40:43]
	v_mfma_f32_16x16x32_bf16 v[28:31], v[164:167], v[198:201], v[28:31]
	v_mfma_f32_16x16x32_bf16 v[24:27], v[172:175], v[198:201], v[24:27]
	v_mfma_f32_16x16x32_bf16 v[12:15], v[164:167], v[206:209], v[12:15]
	v_mfma_f32_16x16x32_bf16 v[8:11], v[172:175], v[206:209], v[8:11]
	s_barrier
	s_add_i32 s16, s50, s18
	v_lshl_add_u64 v[144:145], v[232:233], 0, s[52:53]
	s_mov_b32 m0, s16
	s_nop 0
	global_load_lds_dwordx4 v[144:145], off
	v_lshl_add_u64 v[144:145], v[234:235], 0, s[52:53]
	s_add_i32 m0, s16, 0x2000
	s_nop 0
	global_load_lds_dwordx4 v[144:145], off
	s_waitcnt vmcnt(6)
	s_barrier
	v_mfma_f32_16x16x32_bf16 v[52:55], v[210:213], v[176:179], v[52:55]
	v_mfma_f32_16x16x32_bf16 v[48:51], v[218:221], v[176:179], v[48:51]
	v_mfma_f32_16x16x32_bf16 v[36:39], v[210:213], v[184:187], v[36:39]
	v_mfma_f32_16x16x32_bf16 v[32:35], v[218:221], v[184:187], v[32:35]
	v_mfma_f32_16x16x32_bf16 v[20:23], v[210:213], v[192:195], v[20:23]
	v_mfma_f32_16x16x32_bf16 v[16:19], v[218:221], v[192:195], v[16:19]
	v_mfma_f32_16x16x32_bf16 v[4:7], v[210:213], v[202:205], v[4:7]
	v_mfma_f32_16x16x32_bf16 v[0:3], v[218:221], v[202:205], v[0:3]
	v_mfma_f32_16x16x32_bf16 v[52:55], v[214:217], v[180:183], v[52:55]
	v_mfma_f32_16x16x32_bf16 v[48:51], v[222:225], v[180:183], v[48:51]
	v_mfma_f32_16x16x32_bf16 v[36:39], v[214:217], v[188:191], v[36:39]
	v_mfma_f32_16x16x32_bf16 v[32:35], v[222:225], v[188:191], v[32:35]
	v_mfma_f32_16x16x32_bf16 v[20:23], v[214:217], v[198:201], v[20:23]
	v_mfma_f32_16x16x32_bf16 v[16:19], v[222:225], v[198:201], v[16:19]
	v_mfma_f32_16x16x32_bf16 v[4:7], v[214:217], v[206:209], v[4:7]
	v_mfma_f32_16x16x32_bf16 v[0:3], v[222:225], v[206:209], v[0:3]
	s_add_u32 s14, s14, 0x100
	s_addc_u32 s15, s15, 0
	s_add_u32 s60, s60, 0x100
	s_addc_u32 s61, s61, 0
	s_cmp_ge_i32 s70, s25
	s_mov_b32 s16, s70
	s_barrier
	s_cbranch_scc0 .LBB0_1980

; #define PG8_STAGE(bufoff, gbase, voff) do { _Pragma("unroll") for (int _i = 0; _i < 2; ++_i) \
;         __builtin_amdgcn_global_load_lds((const unsigned*)((const char*)(gbase) + (voff)[_i]), (LAS unsigned*)(lds + (bufoff) + ldsw + _i * 8192), 16, 0, 0); } while (0)
; #define PG8_LDA(dst, b, h) do { _Pragma("unroll") for (int m = 0; m < 4; ++m) _Pragma("unroll") for (int k = 0; k < 2; ++k) dst[m][k] = *(const LAS bf16x8*)(lds + PG8_SA(b, h) + aoff + m * 2048 + k * 1024); } while (0)
; #define PG8_LDB(dst, b, h) do { _Pragma("unroll") for (int n = 0; n < 2; ++n) _Pragma("unroll") for (int k = 0; k < 2; ++k) dst[n][k] = *(const LAS bf16x8*)(lds + PG8_SB(b, h) + boff + n * 2048 + k * 1024); } while (0)
; #define PG8_MMA(ai, bj, At, Bt) do { __builtin_amdgcn_s_setprio(1); _Pragma("unroll") for (int m = 0; m < 4; ++m) _Pragma("unroll") for (int n = 0; n < 2; ++n) _Pragma("unroll") for (int k = 0; k < 2; ++k) \
;         acc[ai][bj][m][n] = __builtin_amdgcn_mfma_f32_16x16x32_bf16(Bt[n][k], At[m][k], acc[ai][bj][m][n], 0, 0, 0); __builtin_amdgcn_s_setprio(0); } while (0)
; #define PG8_WAIT_L(n) asm volatile("s_waitcnt lgkmcnt(" #n ")" ::: "memory")
; #define PG8_BAR __builtin_amdgcn_s_barrier()
; #define PG8_SCHED __builtin_amdgcn_sched_barrier(0)
; template <class Epi>
; DEVI void gemm_phase(LAS unsigned char* lds, const bf16_t* gA, const bf16_t* gBt, const int lda, const int ldb, const int K, const StaticOrder S_, const Epi E) {
;     ...
;             PG8_LDB(B0, 0, 0); PG8_SCHED; PG8_LDA(At, 0, 0); PG8_STAGE(PG8_SA(1, 1), a1 + hstepA, voffA);
;             PG8_WAIT_L(8); PG8_BAR; PG8_WAIT_L(0); PG8_MMA(0, 0, At, B0); PG8_BAR; PG8_SCHED;
;             PG8_LDB(B1, 0, 1); PG8_STAGE(PG8_SB(0, 0), b2, voffB);
;             PG8_BAR; PG8_WAIT_L(0); PG8_MMA(0, 1, At, B1); PG8_BAR;
;             PG8_LDA(At, 0, 1); PG8_STAGE(PG8_SA(0, 0), a2, voffA);
;             PG8_BAR; PG8_WAIT_L(0); PG8_MMA(1, 0, At, B0); PG8_BAR; PG8_SCHED;
.LBB0_2366:
	ds_read_b128 v[128:131], v201
	ds_read_b128 v[132:135], v201 offset:1024
	ds_read_b128 v[136:139], v201 offset:2048
	ds_read_b128 v[140:143], v201 offset:3072
	s_add_i32 s60, s16, 2
	s_add_u32 s38, s14, 0x80
	s_addc_u32 s17, s15, 0
	s_cmp_eq_u32 s19, s16
	s_cselect_b32 s16, s12, s38
	s_cselect_b32 s17, s13, s17
	s_cselect_b32 s39, s41, s49
	s_cselect_b32 s38, s40, s48
	v_lshl_add_u64 v[164:165], s[14:15], 0, v[174:175]
	s_add_i32 m0, s55, 0xc000
	ds_read_b128 v[144:147], v202
	ds_read_b128 v[148:151], v202 offset:1024
	ds_read_b128 v[152:155], v202 offset:2048
	ds_read_b128 v[156:159], v202 offset:3072
	ds_read_b128 v[160:163], v202 offset:4096
	ds_read_b128 v[180:183], v202 offset:5120
	ds_read_b128 v[184:187], v202 offset:6144
	ds_read_b128 v[188:191], v202 offset:7168
	global_load_lds_dwordx4 v[164:165], off
	v_lshl_add_u64 v[164:165], s[14:15], 0, v[176:177]
	s_add_i32 m0, s55, 0xe000
	s_nop 0
	global_load_lds_dwordx4 v[164:165], off
	s_waitcnt lgkmcnt(8)
	s_barrier
	s_waitcnt lgkmcnt(0)
	v_mfma_f32_16x16x32_bf16 v[124:127], v[128:131], v[144:147], v[124:127]
	v_mfma_f32_16x16x32_bf16 v[120:123], v[136:139], v[144:147], v[120:123]
	v_mfma_f32_16x16x32_bf16 v[108:111], v[128:131], v[152:155], v[108:111]
	v_mfma_f32_16x16x32_bf16 v[104:107], v[136:139], v[152:155], v[104:107]
	v_mfma_f32_16x16x32_bf16 v[92:95], v[128:131], v[160:163], v[92:95]
	v_mfma_f32_16x16x32_bf16 v[88:91], v[136:139], v[160:163], v[88:91]
	v_mfma_f32_16x16x32_bf16 v[76:79], v[128:131], v[184:187], v[76:79]
	v_mfma_f32_16x16x32_bf16 v[72:75], v[136:139], v[184:187], v[72:75]
	v_mfma_f32_16x16x32_bf16 v[124:127], v[132:135], v[148:151], v[124:127]
	v_mfma_f32_16x16x32_bf16 v[120:123], v[140:143], v[148:151], v[120:123]
	v_mfma_f32_16x16x32_bf16 v[108:111], v[132:135], v[156:159], v[108:111]
	v_mfma_f32_16x16x32_bf16 v[104:107], v[140:143], v[156:159], v[104:107]
	v_mfma_f32_16x16x32_bf16 v[92:95], v[132:135], v[180:183], v[92:95]
	v_mfma_f32_16x16x32_bf16 v[88:91], v[140:143], v[180:183], v[88:91]
	v_mfma_f32_16x16x32_bf16 v[76:79], v[132:135], v[188:191], v[76:79]
	v_mfma_f32_16x16x32_bf16 v[72:75], v[140:143], v[188:191], v[72:75]
	s_barrier
	s_add_i32 s61, s29, s20
	v_lshl_add_u64 v[164:165], s[38:39], 0, v[168:169]
	s_mov_b32 m0, s61
	ds_read_b128 v[192:195], v203
	ds_read_b128 v[206:209], v203 offset:1024
	ds_read_b128 v[210:213], v203 offset:2048
	ds_read_b128 v[214:217], v203 offset:3072
	global_load_lds_dwordx4 v[164:165], off
	v_lshl_add_u64 v[218:219], s[38:39], 0, v[172:173]
	s_add_i32 m0, s61, 0x2000
	s_nop 0
	global_load_lds_dwordx4 v[218:219], off
	s_barrier
	s_waitcnt lgkmcnt(0)
	v_mfma_f32_16x16x32_bf16 v[116:119], v[192:195], v[144:147], v[116:119]
	v_mfma_f32_16x16x32_bf16 v[112:115], v[210:213], v[144:147], v[112:115]
	v_mfma_f32_16x16x32_bf16 v[100:103], v[192:195], v[152:155], v[100:103]
	v_mfma_f32_16x16x32_bf16 v[96:99], v[210:213], v[152:155], v[96:99]
	v_mfma_f32_16x16x32_bf16 v[84:87], v[192:195], v[160:163], v[84:87]
	v_mfma_f32_16x16x32_bf16 v[80:83], v[210:213], v[160:163], v[80:83]
	v_mfma_f32_16x16x32_bf16 v[68:71], v[192:195], v[184:187], v[68:71]
	v_mfma_f32_16x16x32_bf16 v[64:67], v[210:213], v[184:187], v[64:67]
	v_mfma_f32_16x16x32_bf16 v[116:119], v[206:209], v[148:151], v[116:119]
	v_mfma_f32_16x16x32_bf16 v[112:115], v[214:217], v[148:151], v[112:115]
	v_mfma_f32_16x16x32_bf16 v[100:103], v[206:209], v[156:159], v[100:103]
	v_mfma_f32_16x16x32_bf16 v[96:99], v[214:217], v[156:159], v[96:99]
	v_mfma_f32_16x16x32_bf16 v[84:87], v[206:209], v[180:183], v[84:87]
	v_mfma_f32_16x16x32_bf16 v[80:83], v[214:217], v[180:183], v[80:83]
	v_mfma_f32_16x16x32_bf16 v[68:71], v[206:209], v[188:191], v[68:71]
	v_mfma_f32_16x16x32_bf16 v[64:67], v[214:217], v[188:191], v[64:67]
	s_mov_b32 m0, s55
	v_lshl_add_u64 v[220:221], s[16:17], 0, v[166:167]
	s_barrier
	ds_read_b128 v[144:147], v202 offset:16384
	ds_read_b128 v[148:151], v202 offset:17408
	ds_read_b128 v[152:155], v202 offset:18432
	ds_read_b128 v[156:159], v202 offset:19456
	ds_read_b128 v[160:163], v202 offset:20480
	ds_read_b128 v[180:183], v202 offset:21504
	ds_read_b128 v[184:187], v202 offset:22528
	ds_read_b128 v[188:191], v202 offset:23552
	global_load_lds_dwordx4 v[220:221], off
	v_lshl_add_u64 v[222:223], s[16:17], 0, v[170:171]
	s_mov_b32 m0, s22
	s_nop 0
	global_load_lds_dwordx4 v[222:223], off
	s_barrier
	s_waitcnt lgkmcnt(0)
	v_mfma_f32_16x16x32_bf16 v[60:63], v[128:131], v[144:147], v[60:63]
	v_mfma_f32_16x16x32_bf16 v[56:59], v[136:139], v[144:147], v[56:59]
	v_mfma_f32_16x16x32_bf16 v[44:47], v[128:131], v[152:155], v[44:47]
	v_mfma_f32_16x16x32_bf16 v[40:43], v[136:139], v[152:155], v[40:43]
	v_mfma_f32_16x16x32_bf16 v[28:31], v[128:131], v[160:163], v[28:31]
	v_mfma_f32_16x16x32_bf16 v[24:27], v[136:139], v[160:163], v[24:27]
	v_mfma_f32_16x16x32_bf16 v[12:15], v[128:131], v[184:187], v[12:15]
	v_mfma_f32_16x16x32_bf16 v[8:11], v[136:139], v[184:187], v[8:11]
	v_mfma_f32_16x16x32_bf16 v[60:63], v[132:135], v[148:151], v[60:63]
	v_mfma_f32_16x16x32_bf16 v[56:59], v[140:143], v[148:151], v[56:59]
	v_mfma_f32_16x16x32_bf16 v[44:47], v[132:135], v[156:159], v[44:47]
	v_mfma_f32_16x16x32_bf16 v[40:43], v[140:143], v[156:159], v[40:43]
	v_mfma_f32_16x16x32_bf16 v[28:31], v[132:135], v[180:183], v[28:31]
	v_mfma_f32_16x16x32_bf16 v[24:27], v[140:143], v[180:183], v[24:27]
	v_mfma_f32_16x16x32_bf16 v[12:15], v[132:135], v[188:191], v[12:15]
	v_mfma_f32_16x16x32_bf16 v[8:11], v[140:143], v[188:191], v[8:11]
	s_barrier
; #define PG8_STAGE(bufoff, gbase, voff) do { _Pragma("unroll") for (int _i = 0; _i < 2; ++_i) \
;         __builtin_amdgcn_global_load_lds((const unsigned*)((const char*)(gbase) + (voff)[_i]), (LAS unsigned*)(lds + (bufoff) + ldsw + _i * 8192), 16, 0, 0); } while (0)
; #define PG8_LDA(dst, b, h) do { _Pragma("unroll") for (int m = 0; m < 4; ++m) _Pragma("unroll") for (int k = 0; k < 2; ++k) dst[m][k] = *(const LAS bf16x8*)(lds + PG8_SA(b, h) + aoff + m * 2048 + k * 1024); } while (0)
; #define PG8_LDB(dst, b, h) do { _Pragma("unroll") for (int n = 0; n < 2; ++n) _Pragma("unroll") for (int k = 0; k < 2; ++k) dst[n][k] = *(const LAS bf16x8*)(lds + PG8_SB(b, h) + boff + n * 2048 + k * 1024); } while (0)
; #define PG8_MMA(ai, bj, At, Bt) do { __builtin_amdgcn_s_setprio(1); _Pragma("unroll") for (int m = 0; m < 4; ++m) _Pragma("unroll") for (int n = 0; n < 2; ++n) _Pragma("unroll") for (int k = 0; k < 2; ++k) \
;         acc[ai][bj][m][n] = __builtin_amdgcn_mfma_f32_16x16x32_bf16(Bt[n][k], At[m][k], acc[ai][bj][m][n], 0, 0, 0); __builtin_amdgcn_s_setprio(0); } while (0)
; #define PG8_WAIT_V(n) asm volatile("s_waitcnt vmcnt(" #n ")" ::: "memory")
; #define PG8_WAIT_L(n) asm volatile("s_waitcnt lgkmcnt(" #n ")" ::: "memory")
; #define PG8_BAR __builtin_amdgcn_s_barrier()
; #define PG8_SCHED __builtin_amdgcn_sched_barrier(0)
; template <class Epi>
; DEVI void gemm_phase(LAS unsigned char* lds, const bf16_t* gA, const bf16_t* gBt, const int lda, const int ldb, const int K, const StaticOrder S_, const Epi E) {
;     ...
;             PG8_STAGE(PG8_SB(0, 1), b2 + hstepB, voffB);
;             PG8_WAIT_V(6); PG8_BAR; PG8_MMA(1, 1, At, B1); PG8_BAR;
;             PG8_LDB(B0, 1, 0); PG8_SCHED; PG8_LDA(At, 1, 0); PG8_STAGE(PG8_SA(0, 1), a2 + hstepA, voffA);
;             PG8_WAIT_L(8); PG8_BAR; PG8_WAIT_L(0); PG8_MMA(0, 0, At, B0); PG8_BAR; PG8_SCHED;
;             PG8_LDB(B1, 1, 1); PG8_STAGE(PG8_SB(1, 0), b3, voffB);
;             PG8_BAR; PG8_WAIT_L(0); PG8_MMA(0, 1, At, B1); PG8_BAR;
	s_add_u32 s38, s38, s2
	s_addc_u32 s39, s39, s3
	s_add_i32 s61, s50, s20
	v_lshl_add_u64 v[224:225], s[38:39], 0, v[168:169]
	s_mov_b32 m0, s61
	v_lshl_add_u64 v[226:227], s[38:39], 0, v[172:173]
	global_load_lds_dwordx4 v[224:225], off
	s_add_i32 m0, s61, 0x2000
	s_nop 0
	global_load_lds_dwordx4 v[226:227], off
	s_waitcnt vmcnt(6)
	s_barrier
	v_mfma_f32_16x16x32_bf16 v[52:55], v[192:195], v[144:147], v[52:55]
	v_mfma_f32_16x16x32_bf16 v[48:51], v[210:213], v[144:147], v[48:51]
	v_mfma_f32_16x16x32_bf16 v[36:39], v[192:195], v[152:155], v[36:39]
	v_mfma_f32_16x16x32_bf16 v[32:35], v[210:213], v[152:155], v[32:35]
	v_mfma_f32_16x16x32_bf16 v[20:23], v[192:195], v[160:163], v[20:23]
	v_mfma_f32_16x16x32_bf16 v[16:19], v[210:213], v[160:163], v[16:19]
	v_mfma_f32_16x16x32_bf16 v[4:7], v[192:195], v[184:187], v[4:7]
	v_mfma_f32_16x16x32_bf16 v[0:3], v[210:213], v[184:187], v[0:3]
	v_mfma_f32_16x16x32_bf16 v[52:55], v[206:209], v[148:151], v[52:55]
	v_mfma_f32_16x16x32_bf16 v[48:51], v[214:217], v[148:151], v[48:51]
	v_mfma_f32_16x16x32_bf16 v[36:39], v[206:209], v[156:159], v[36:39]
	v_mfma_f32_16x16x32_bf16 v[32:35], v[214:217], v[156:159], v[32:35]
	v_mfma_f32_16x16x32_bf16 v[20:23], v[206:209], v[180:183], v[20:23]
	v_mfma_f32_16x16x32_bf16 v[16:19], v[214:217], v[180:183], v[16:19]
	v_mfma_f32_16x16x32_bf16 v[4:7], v[206:209], v[188:191], v[4:7]
	v_mfma_f32_16x16x32_bf16 v[0:3], v[214:217], v[188:191], v[0:3]
	s_add_i32 s38, 0, 0x18000
	v_add_u32_e32 v140, s38, v199
	s_barrier
	ds_read_b128 v[128:131], v140
	ds_read_b128 v[132:135], v140 offset:1024
	ds_read_b128 v[136:139], v140 offset:2048
	ds_read_b128 v[140:143], v140 offset:3072
	s_add_u32 s16, s16, s0
	s_addc_u32 s17, s17, s1
	s_mov_b32 m0, s23
	v_lshl_add_u64 v[192:193], s[16:17], 0, v[166:167]
	ds_read_b128 v[144:147], v202 offset:32768
	ds_read_b128 v[148:151], v202 offset:33792
	ds_read_b128 v[152:155], v202 offset:34816
	ds_read_b128 v[156:159], v202 offset:35840
	ds_read_b128 v[160:163], v202 offset:36864
	ds_read_b128 v[180:183], v202 offset:37888
	ds_read_b128 v[184:187], v202 offset:38912
	ds_read_b128 v[188:191], v202 offset:39936
	global_load_lds_dwordx4 v[192:193], off
	v_lshl_add_u64 v[192:193], s[16:17], 0, v[170:171]
	s_mov_b32 m0, s24
	s_nop 0
	global_load_lds_dwordx4 v[192:193], off
	s_waitcnt lgkmcnt(8)
	s_barrier
	s_waitcnt lgkmcnt(0)
	v_mfma_f32_16x16x32_bf16 v[124:127], v[128:131], v[144:147], v[124:127]
	v_mfma_f32_16x16x32_bf16 v[120:123], v[136:139], v[144:147], v[120:123]
	v_mfma_f32_16x16x32_bf16 v[108:111], v[128:131], v[152:155], v[108:111]
	v_mfma_f32_16x16x32_bf16 v[104:107], v[136:139], v[152:155], v[104:107]
	v_mfma_f32_16x16x32_bf16 v[92:95], v[128:131], v[160:163], v[92:95]
	v_mfma_f32_16x16x32_bf16 v[88:91], v[136:139], v[160:163], v[88:91]
	v_mfma_f32_16x16x32_bf16 v[76:79], v[128:131], v[184:187], v[76:79]
	v_mfma_f32_16x16x32_bf16 v[72:75], v[136:139], v[184:187], v[72:75]
	v_mfma_f32_16x16x32_bf16 v[124:127], v[132:135], v[148:151], v[124:127]
	v_mfma_f32_16x16x32_bf16 v[120:123], v[140:143], v[148:151], v[120:123]
	v_mfma_f32_16x16x32_bf16 v[108:111], v[132:135], v[156:159], v[108:111]
	v_mfma_f32_16x16x32_bf16 v[104:107], v[140:143], v[156:159], v[104:107]
	v_mfma_f32_16x16x32_bf16 v[92:95], v[132:135], v[180:183], v[92:95]
	v_mfma_f32_16x16x32_bf16 v[88:91], v[140:143], v[180:183], v[88:91]
	v_mfma_f32_16x16x32_bf16 v[76:79], v[132:135], v[188:191], v[76:79]
	v_mfma_f32_16x16x32_bf16 v[72:75], v[140:143], v[188:191], v[72:75]
	s_barrier
	s_add_i32 s16, 0, 0x1c000
	s_add_i32 s17, s38, s20
	v_add_u32_e32 v205, s16, v199
	v_lshl_add_u64 v[164:165], v[164:165], 0, s[8:9]
	s_mov_b32 m0, s17
	ds_read_b128 v[192:195], v205
	ds_read_b128 v[206:209], v205 offset:1024
	ds_read_b128 v[210:213], v205 offset:2048
	ds_read_b128 v[214:217], v205 offset:3072
	global_load_lds_dwordx4 v[164:165], off
	v_lshl_add_u64 v[164:165], v[218:219], 0, s[8:9]
	s_add_i32 m0, s17, 0x2000
	s_nop 0
	global_load_lds_dwordx4 v[164:165], off
	s_barrier
; #define PG8_STAGE(bufoff, gbase, voff) do { _Pragma("unroll") for (int _i = 0; _i < 2; ++_i) \
;         __builtin_amdgcn_global_load_lds((const unsigned*)((const char*)(gbase) + (voff)[_i]), (LAS unsigned*)(lds + (bufoff) + ldsw + _i * 8192), 16, 0, 0); } while (0)
; #define PG8_LDA(dst, b, h) do { _Pragma("unroll") for (int m = 0; m < 4; ++m) _Pragma("unroll") for (int k = 0; k < 2; ++k) dst[m][k] = *(const LAS bf16x8*)(lds + PG8_SA(b, h) + aoff + m * 2048 + k * 1024); } while (0)
; #define PG8_MMA(ai, bj, At, Bt) do { __builtin_amdgcn_s_setprio(1); _Pragma("unroll") for (int m = 0; m < 4; ++m) _Pragma("unroll") for (int n = 0; n < 2; ++n) _Pragma("unroll") for (int k = 0; k < 2; ++k) \
;         acc[ai][bj][m][n] = __builtin_amdgcn_mfma_f32_16x16x32_bf16(Bt[n][k], At[m][k], acc[ai][bj][m][n], 0, 0, 0); __builtin_amdgcn_s_setprio(0); } while (0)
; #define PG8_WAIT_V(n) asm volatile("s_waitcnt vmcnt(" #n ")" ::: "memory")
; #define PG8_WAIT_L(n) asm volatile("s_waitcnt lgkmcnt(" #n ")" ::: "memory")
; #define PG8_BAR __builtin_amdgcn_s_barrier()
; #define PG8_SCHED __builtin_amdgcn_sched_barrier(0)
; template <class Epi>
; DEVI void gemm_phase(LAS unsigned char* lds, const bf16_t* gA, const bf16_t* gBt, const int lda, const int ldb, const int K, const StaticOrder S_, const Epi E) {
;     ...
;             PG8_BAR; PG8_WAIT_L(0); PG8_MMA(0, 1, At, B1); PG8_BAR;
;             PG8_LDA(At, 1, 1); PG8_STAGE(PG8_SA(1, 0), a3, voffA);
;             PG8_BAR; PG8_WAIT_L(0); PG8_MMA(1, 0, At, B0); PG8_BAR; PG8_SCHED;
;             PG8_STAGE(PG8_SB(1, 1), b3 + hstepB, voffB);
;             PG8_WAIT_V(6); PG8_BAR; PG8_MMA(1, 1, At, B1); PG8_BAR;
;         }
	s_waitcnt lgkmcnt(0)
	v_mfma_f32_16x16x32_bf16 v[116:119], v[192:195], v[144:147], v[116:119]
	v_mfma_f32_16x16x32_bf16 v[112:115], v[210:213], v[144:147], v[112:115]
	v_mfma_f32_16x16x32_bf16 v[100:103], v[192:195], v[152:155], v[100:103]
	v_mfma_f32_16x16x32_bf16 v[96:99], v[210:213], v[152:155], v[96:99]
	v_mfma_f32_16x16x32_bf16 v[84:87], v[192:195], v[160:163], v[84:87]
	v_mfma_f32_16x16x32_bf16 v[80:83], v[210:213], v[160:163], v[80:83]
	v_mfma_f32_16x16x32_bf16 v[68:71], v[192:195], v[184:187], v[68:71]
	v_mfma_f32_16x16x32_bf16 v[64:67], v[210:213], v[184:187], v[64:67]
	v_mfma_f32_16x16x32_bf16 v[116:119], v[206:209], v[148:151], v[116:119]
	v_mfma_f32_16x16x32_bf16 v[112:115], v[214:217], v[148:151], v[112:115]
	v_mfma_f32_16x16x32_bf16 v[100:103], v[206:209], v[156:159], v[100:103]
	v_mfma_f32_16x16x32_bf16 v[96:99], v[214:217], v[156:159], v[96:99]
	v_mfma_f32_16x16x32_bf16 v[84:87], v[206:209], v[180:183], v[84:87]
	v_mfma_f32_16x16x32_bf16 v[80:83], v[214:217], v[180:183], v[80:83]
	v_mfma_f32_16x16x32_bf16 v[68:71], v[206:209], v[188:191], v[68:71]
	v_mfma_f32_16x16x32_bf16 v[64:67], v[214:217], v[188:191], v[64:67]
	s_mov_b32 m0, s26
	v_lshl_add_u64 v[164:165], v[220:221], 0, s[8:9]
	s_barrier
	ds_read_b128 v[144:147], v202 offset:49152
	ds_read_b128 v[148:151], v202 offset:50176
	ds_read_b128 v[152:155], v202 offset:51200
	ds_read_b128 v[156:159], v202 offset:52224
	ds_read_b128 v[160:163], v202 offset:53248
	ds_read_b128 v[180:183], v202 offset:54272
	ds_read_b128 v[184:187], v202 offset:55296
	ds_read_b128 v[188:191], v202 offset:56320
	global_load_lds_dwordx4 v[164:165], off
	v_lshl_add_u64 v[164:165], v[222:223], 0, s[8:9]
	s_mov_b32 m0, s27
	s_nop 0
	global_load_lds_dwordx4 v[164:165], off
	s_barrier
	s_waitcnt lgkmcnt(0)
	v_mfma_f32_16x16x32_bf16 v[60:63], v[128:131], v[144:147], v[60:63]
	v_mfma_f32_16x16x32_bf16 v[56:59], v[136:139], v[144:147], v[56:59]
	v_mfma_f32_16x16x32_bf16 v[44:47], v[128:131], v[152:155], v[44:47]
	v_mfma_f32_16x16x32_bf16 v[40:43], v[136:139], v[152:155], v[40:43]
	v_mfma_f32_16x16x32_bf16 v[28:31], v[128:131], v[160:163], v[28:31]
	v_mfma_f32_16x16x32_bf16 v[24:27], v[136:139], v[160:163], v[24:27]
	v_mfma_f32_16x16x32_bf16 v[12:15], v[128:131], v[184:187], v[12:15]
	v_mfma_f32_16x16x32_bf16 v[8:11], v[136:139], v[184:187], v[8:11]
	v_mfma_f32_16x16x32_bf16 v[60:63], v[132:135], v[148:151], v[60:63]
	v_mfma_f32_16x16x32_bf16 v[56:59], v[140:143], v[148:151], v[56:59]
	v_mfma_f32_16x16x32_bf16 v[44:47], v[132:135], v[156:159], v[44:47]
	v_mfma_f32_16x16x32_bf16 v[40:43], v[140:143], v[156:159], v[40:43]
	v_mfma_f32_16x16x32_bf16 v[28:31], v[132:135], v[180:183], v[28:31]
	v_mfma_f32_16x16x32_bf16 v[24:27], v[140:143], v[180:183], v[24:27]
	v_mfma_f32_16x16x32_bf16 v[12:15], v[132:135], v[188:191], v[12:15]
	v_mfma_f32_16x16x32_bf16 v[8:11], v[140:143], v[188:191], v[8:11]
	s_barrier
	s_add_i32 s16, s16, s20
	v_lshl_add_u64 v[128:129], v[224:225], 0, s[8:9]
	s_mov_b32 m0, s16
	s_nop 0
	global_load_lds_dwordx4 v[128:129], off
	v_lshl_add_u64 v[128:129], v[226:227], 0, s[8:9]
	s_add_i32 m0, s16, 0x2000
	s_nop 0
	global_load_lds_dwordx4 v[128:129], off
	s_waitcnt vmcnt(6)
	s_barrier
	v_mfma_f32_16x16x32_bf16 v[52:55], v[192:195], v[144:147], v[52:55]
	v_mfma_f32_16x16x32_bf16 v[48:51], v[210:213], v[144:147], v[48:51]
	v_mfma_f32_16x16x32_bf16 v[36:39], v[192:195], v[152:155], v[36:39]
	v_mfma_f32_16x16x32_bf16 v[32:35], v[210:213], v[152:155], v[32:35]
	v_mfma_f32_16x16x32_bf16 v[20:23], v[192:195], v[160:163], v[20:23]
	v_mfma_f32_16x16x32_bf16 v[16:19], v[210:213], v[160:163], v[16:19]
	v_mfma_f32_16x16x32_bf16 v[4:7], v[192:195], v[184:187], v[4:7]
	v_mfma_f32_16x16x32_bf16 v[0:3], v[210:213], v[184:187], v[0:3]
	v_mfma_f32_16x16x32_bf16 v[52:55], v[206:209], v[148:151], v[52:55]
	v_mfma_f32_16x16x32_bf16 v[48:51], v[214:217], v[148:151], v[48:51]
	v_mfma_f32_16x16x32_bf16 v[36:39], v[206:209], v[156:159], v[36:39]
	v_mfma_f32_16x16x32_bf16 v[32:35], v[214:217], v[156:159], v[32:35]
	v_mfma_f32_16x16x32_bf16 v[20:23], v[206:209], v[180:183], v[20:23]
	v_mfma_f32_16x16x32_bf16 v[16:19], v[214:217], v[180:183], v[16:19]
	v_mfma_f32_16x16x32_bf16 v[4:7], v[206:209], v[188:191], v[4:7]
	v_mfma_f32_16x16x32_bf16 v[0:3], v[214:217], v[188:191], v[0:3]
	s_add_u32 s14, s14, 0x100
	s_addc_u32 s15, s15, 0
	s_add_u32 s48, s48, 0x100
	s_addc_u32 s49, s49, 0
	s_cmp_ge_i32 s60, s25
	s_mov_b32 s16, s60
	s_barrier
	s_cbranch_scc0 .LBB0_2366

; #define PG8_STAGE(bufoff, gbase, voff) do { _Pragma("unroll") for (int _i = 0; _i < 2; ++_i) \
;         __builtin_amdgcn_global_load_lds((const unsigned*)((const char*)(gbase) + (voff)[_i]), (LAS unsigned*)(lds + (bufoff) + ldsw + _i * 8192), 16, 0, 0); } while (0)
; #define PG8_LDA(dst, b, h) do { _Pragma("unroll") for (int m = 0; m < 4; ++m) _Pragma("unroll") for (int k = 0; k < 2; ++k) dst[m][k] = *(const LAS bf16x8*)(lds + PG8_SA(b, h) + aoff + m * 2048 + k * 1024); } while (0)
; #define PG8_LDB(dst, b, h) do { _Pragma("unroll") for (int n = 0; n < 2; ++n) _Pragma("unroll") for (int k = 0; k < 2; ++k) dst[n][k] = *(const LAS bf16x8*)(lds + PG8_SB(b, h) + boff + n * 2048 + k * 1024); } while (0)
; #define PG8_MMA(ai, bj, At, Bt) do { __builtin_amdgcn_s_setprio(1); _Pragma("unroll") for (int m = 0; m < 4; ++m) _Pragma("unroll") for (int n = 0; n < 2; ++n) _Pragma("unroll") for (int k = 0; k < 2; ++k) \
;         acc[ai][bj][m][n] = __builtin_amdgcn_mfma_f32_16x16x32_bf16(Bt[n][k], At[m][k], acc[ai][bj][m][n], 0, 0, 0); __builtin_amdgcn_s_setprio(0); } while (0)
; #define PG8_WAIT_L(n) asm volatile("s_waitcnt lgkmcnt(" #n ")" ::: "memory")
; #define PG8_BAR __builtin_amdgcn_s_barrier()
; #define PG8_SCHED __builtin_amdgcn_sched_barrier(0)
; template <class Epi>
; DEVI void gemm_phase(LAS unsigned char* lds, const bf16_t* gA, const bf16_t* gBt, const int lda, const int ldb, const int K, const StaticOrder S_, const Epi E) {
;     ...
;             PG8_LDB(B0, 0, 0); PG8_SCHED; PG8_LDA(At, 0, 0); PG8_STAGE(PG8_SA(1, 1), a1 + hstepA, voffA);
;             PG8_WAIT_L(8); PG8_BAR; PG8_WAIT_L(0); PG8_MMA(0, 0, At, B0); PG8_BAR; PG8_SCHED;
;             PG8_LDB(B1, 0, 1); PG8_STAGE(PG8_SB(0, 0), b2, voffB);
;             PG8_BAR; PG8_WAIT_L(0); PG8_MMA(0, 1, At, B1); PG8_BAR;
;             PG8_LDA(At, 0, 1); PG8_STAGE(PG8_SA(0, 0), a2, voffA);
;             PG8_BAR; PG8_WAIT_L(0); PG8_MMA(1, 0, At, B0); PG8_BAR; PG8_SCHED;
.LBB0_2510:
	ds_read_b128 v[158:161], v151
	ds_read_b128 v[162:165], v151 offset:1024
	ds_read_b128 v[166:169], v151 offset:2048
	ds_read_b128 v[170:173], v151 offset:3072
	s_add_i32 s61, s16, 2
	s_add_u32 s48, s14, 0x80
	s_addc_u32 s17, s15, 0
	s_cmp_eq_u32 s26, s16
	s_cselect_b32 s16, s38, s48
	s_cselect_b32 s17, s39, s17
	s_cselect_b32 s49, s47, s60
	s_cselect_b32 s48, s46, s59
	v_lshl_add_u64 v[144:145], s[14:15], 0, v[138:139]
	s_add_i32 m0, s19, 0xc000
	ds_read_b128 v[174:177], v152
	ds_read_b128 v[178:181], v152 offset:1024
	ds_read_b128 v[182:185], v152 offset:2048
	ds_read_b128 v[186:189], v152 offset:3072
	ds_read_b128 v[190:193], v152 offset:4096
	ds_read_b128 v[198:201], v152 offset:5120
	ds_read_b128 v[202:205], v152 offset:6144
	ds_read_b128 v[206:209], v152 offset:7168
	global_load_lds_dwordx4 v[144:145], off
	v_lshl_add_u64 v[144:145], s[14:15], 0, v[140:141]
	s_add_i32 m0, s19, 0xe000
	s_nop 0
	global_load_lds_dwordx4 v[144:145], off
	s_waitcnt lgkmcnt(8)
	s_barrier
	s_waitcnt lgkmcnt(0)
	v_mfma_f32_16x16x32_bf16 v[120:123], v[158:161], v[174:177], v[120:123]
	v_mfma_f32_16x16x32_bf16 v[116:119], v[166:169], v[174:177], v[116:119]
	v_mfma_f32_16x16x32_bf16 v[108:111], v[158:161], v[182:185], v[108:111]
	v_mfma_f32_16x16x32_bf16 v[100:103], v[166:169], v[182:185], v[100:103]
	v_mfma_f32_16x16x32_bf16 v[92:95], v[158:161], v[190:193], v[92:95]
	v_mfma_f32_16x16x32_bf16 v[84:87], v[166:169], v[190:193], v[84:87]
	v_mfma_f32_16x16x32_bf16 v[76:79], v[158:161], v[202:205], v[76:79]
	v_mfma_f32_16x16x32_bf16 v[68:71], v[166:169], v[202:205], v[68:71]
	v_mfma_f32_16x16x32_bf16 v[120:123], v[162:165], v[178:181], v[120:123]
	v_mfma_f32_16x16x32_bf16 v[116:119], v[170:173], v[178:181], v[116:119]
	v_mfma_f32_16x16x32_bf16 v[108:111], v[162:165], v[186:189], v[108:111]
	v_mfma_f32_16x16x32_bf16 v[100:103], v[170:173], v[186:189], v[100:103]
	v_mfma_f32_16x16x32_bf16 v[92:95], v[162:165], v[198:201], v[92:95]
	v_mfma_f32_16x16x32_bf16 v[84:87], v[170:173], v[198:201], v[84:87]
	v_mfma_f32_16x16x32_bf16 v[76:79], v[162:165], v[206:209], v[76:79]
	v_mfma_f32_16x16x32_bf16 v[68:71], v[170:173], v[206:209], v[68:71]
	s_barrier
	s_add_i32 s62, s30, s18
	v_lshl_add_u64 v[144:145], s[48:49], 0, v[130:131]
	s_mov_b32 m0, s62
	ds_read_b128 v[210:213], v153
	ds_read_b128 v[214:217], v153 offset:1024
	ds_read_b128 v[218:221], v153 offset:2048
	ds_read_b128 v[222:225], v153 offset:3072
	global_load_lds_dwordx4 v[144:145], off
	v_lshl_add_u64 v[194:195], s[48:49], 0, v[134:135]
	s_add_i32 m0, s62, 0x2000
	s_nop 0
	global_load_lds_dwordx4 v[194:195], off
	s_barrier
	s_waitcnt lgkmcnt(0)
	v_mfma_f32_16x16x32_bf16 v[124:127], v[210:213], v[174:177], v[124:127]
	v_mfma_f32_16x16x32_bf16 v[112:115], v[218:221], v[174:177], v[112:115]
	v_mfma_f32_16x16x32_bf16 v[104:107], v[210:213], v[182:185], v[104:107]
	v_mfma_f32_16x16x32_bf16 v[96:99], v[218:221], v[182:185], v[96:99]
	v_mfma_f32_16x16x32_bf16 v[88:91], v[210:213], v[190:193], v[88:91]
	v_mfma_f32_16x16x32_bf16 v[80:83], v[218:221], v[190:193], v[80:83]
	v_mfma_f32_16x16x32_bf16 v[72:75], v[210:213], v[202:205], v[72:75]
	v_mfma_f32_16x16x32_bf16 v[64:67], v[218:221], v[202:205], v[64:67]
	v_mfma_f32_16x16x32_bf16 v[124:127], v[214:217], v[178:181], v[124:127]
	v_mfma_f32_16x16x32_bf16 v[112:115], v[222:225], v[178:181], v[112:115]
	v_mfma_f32_16x16x32_bf16 v[104:107], v[214:217], v[186:189], v[104:107]
	v_mfma_f32_16x16x32_bf16 v[96:99], v[222:225], v[186:189], v[96:99]
	v_mfma_f32_16x16x32_bf16 v[88:91], v[214:217], v[198:201], v[88:91]
	v_mfma_f32_16x16x32_bf16 v[80:83], v[222:225], v[198:201], v[80:83]
	v_mfma_f32_16x16x32_bf16 v[72:75], v[214:217], v[206:209], v[72:75]
	v_mfma_f32_16x16x32_bf16 v[64:67], v[222:225], v[206:209], v[64:67]
	s_mov_b32 m0, s19
	v_lshl_add_u64 v[226:227], s[16:17], 0, v[128:129]
	s_barrier
	ds_read_b128 v[174:177], v152 offset:16384
	ds_read_b128 v[178:181], v152 offset:17408
	ds_read_b128 v[182:185], v152 offset:18432
	ds_read_b128 v[186:189], v152 offset:19456
	ds_read_b128 v[190:193], v152 offset:20480
	ds_read_b128 v[198:201], v152 offset:21504
	ds_read_b128 v[202:205], v152 offset:22528
	ds_read_b128 v[206:209], v152 offset:23552
	global_load_lds_dwordx4 v[226:227], off
	v_lshl_add_u64 v[228:229], s[16:17], 0, v[132:133]
	s_mov_b32 m0, s20
	s_nop 0
	global_load_lds_dwordx4 v[228:229], off
	s_barrier
	s_waitcnt lgkmcnt(0)
	v_mfma_f32_16x16x32_bf16 v[60:63], v[158:161], v[174:177], v[60:63]
	v_mfma_f32_16x16x32_bf16 v[56:59], v[166:169], v[174:177], v[56:59]
	v_mfma_f32_16x16x32_bf16 v[44:47], v[158:161], v[182:185], v[44:47]
	v_mfma_f32_16x16x32_bf16 v[40:43], v[166:169], v[182:185], v[40:43]
	v_mfma_f32_16x16x32_bf16 v[28:31], v[158:161], v[190:193], v[28:31]
	v_mfma_f32_16x16x32_bf16 v[24:27], v[166:169], v[190:193], v[24:27]
	v_mfma_f32_16x16x32_bf16 v[12:15], v[158:161], v[202:205], v[12:15]
	v_mfma_f32_16x16x32_bf16 v[8:11], v[166:169], v[202:205], v[8:11]
	v_mfma_f32_16x16x32_bf16 v[60:63], v[162:165], v[178:181], v[60:63]
	v_mfma_f32_16x16x32_bf16 v[56:59], v[170:173], v[178:181], v[56:59]
	v_mfma_f32_16x16x32_bf16 v[44:47], v[162:165], v[186:189], v[44:47]
	v_mfma_f32_16x16x32_bf16 v[40:43], v[170:173], v[186:189], v[40:43]
	v_mfma_f32_16x16x32_bf16 v[28:31], v[162:165], v[198:201], v[28:31]
	v_mfma_f32_16x16x32_bf16 v[24:27], v[170:173], v[198:201], v[24:27]
	v_mfma_f32_16x16x32_bf16 v[12:15], v[162:165], v[206:209], v[12:15]
	v_mfma_f32_16x16x32_bf16 v[8:11], v[170:173], v[206:209], v[8:11]
	s_barrier
; #define PG8_STAGE(bufoff, gbase, voff) do { _Pragma("unroll") for (int _i = 0; _i < 2; ++_i) \
;         __builtin_amdgcn_global_load_lds((const unsigned*)((const char*)(gbase) + (voff)[_i]), (LAS unsigned*)(lds + (bufoff) + ldsw + _i * 8192), 16, 0, 0); } while (0)
; #define PG8_LDA(dst, b, h) do { _Pragma("unroll") for (int m = 0; m < 4; ++m) _Pragma("unroll") for (int k = 0; k < 2; ++k) dst[m][k] = *(const LAS bf16x8*)(lds + PG8_SA(b, h) + aoff + m * 2048 + k * 1024); } while (0)
; #define PG8_LDB(dst, b, h) do { _Pragma("unroll") for (int n = 0; n < 2; ++n) _Pragma("unroll") for (int k = 0; k < 2; ++k) dst[n][k] = *(const LAS bf16x8*)(lds + PG8_SB(b, h) + boff + n * 2048 + k * 1024); } while (0)
; #define PG8_MMA(ai, bj, At, Bt) do { __builtin_amdgcn_s_setprio(1); _Pragma("unroll") for (int m = 0; m < 4; ++m) _Pragma("unroll") for (int n = 0; n < 2; ++n) _Pragma("unroll") for (int k = 0; k < 2; ++k) \
;         acc[ai][bj][m][n] = __builtin_amdgcn_mfma_f32_16x16x32_bf16(Bt[n][k], At[m][k], acc[ai][bj][m][n], 0, 0, 0); __builtin_amdgcn_s_setprio(0); } while (0)
; #define PG8_WAIT_V(n) asm volatile("s_waitcnt vmcnt(" #n ")" ::: "memory")
; #define PG8_WAIT_L(n) asm volatile("s_waitcnt lgkmcnt(" #n ")" ::: "memory")
; #define PG8_BAR __builtin_amdgcn_s_barrier()
; #define PG8_SCHED __builtin_amdgcn_sched_barrier(0)
; template <class Epi>
; DEVI void gemm_phase(LAS unsigned char* lds, const bf16_t* gA, const bf16_t* gBt, const int lda, const int ldb, const int K, const StaticOrder S_, const Epi E) {
;     ...
;             PG8_STAGE(PG8_SB(0, 1), b2 + hstepB, voffB);
;             PG8_WAIT_V(6); PG8_BAR; PG8_MMA(1, 1, At, B1); PG8_BAR;
;             PG8_LDB(B0, 1, 0); PG8_SCHED; PG8_LDA(At, 1, 0); PG8_STAGE(PG8_SA(0, 1), a2 + hstepA, voffA);
;             PG8_WAIT_L(8); PG8_BAR; PG8_WAIT_L(0); PG8_MMA(0, 0, At, B0); PG8_BAR; PG8_SCHED;
;             PG8_LDB(B1, 1, 1); PG8_STAGE(PG8_SB(1, 0), b3, voffB);
;             PG8_BAR; PG8_WAIT_L(0); PG8_MMA(0, 1, At, B1); PG8_BAR;
;             PG8_LDA(At, 1, 1); PG8_STAGE(PG8_SA(1, 0), a3, voffA);
	s_add_u32 s48, s48, s2
	s_addc_u32 s49, s49, s3
	s_add_i32 s62, s50, s18
	v_lshl_add_u64 v[230:231], s[48:49], 0, v[130:131]
	s_mov_b32 m0, s62
	v_lshl_add_u64 v[232:233], s[48:49], 0, v[134:135]
	global_load_lds_dwordx4 v[230:231], off
	s_add_i32 m0, s62, 0x2000
	s_nop 0
	global_load_lds_dwordx4 v[232:233], off
	s_waitcnt vmcnt(6)
	s_barrier
	v_mfma_f32_16x16x32_bf16 v[52:55], v[210:213], v[174:177], v[52:55]
	v_mfma_f32_16x16x32_bf16 v[48:51], v[218:221], v[174:177], v[48:51]
	v_mfma_f32_16x16x32_bf16 v[36:39], v[210:213], v[182:185], v[36:39]
	v_mfma_f32_16x16x32_bf16 v[32:35], v[218:221], v[182:185], v[32:35]
	v_mfma_f32_16x16x32_bf16 v[20:23], v[210:213], v[190:193], v[20:23]
	v_mfma_f32_16x16x32_bf16 v[16:19], v[218:221], v[190:193], v[16:19]
	v_mfma_f32_16x16x32_bf16 v[4:7], v[210:213], v[202:205], v[4:7]
	v_mfma_f32_16x16x32_bf16 v[0:3], v[218:221], v[202:205], v[0:3]
	v_mfma_f32_16x16x32_bf16 v[52:55], v[214:217], v[178:181], v[52:55]
	v_mfma_f32_16x16x32_bf16 v[48:51], v[222:225], v[178:181], v[48:51]
	v_mfma_f32_16x16x32_bf16 v[36:39], v[214:217], v[186:189], v[36:39]
	v_mfma_f32_16x16x32_bf16 v[32:35], v[222:225], v[186:189], v[32:35]
	v_mfma_f32_16x16x32_bf16 v[20:23], v[214:217], v[198:201], v[20:23]
	v_mfma_f32_16x16x32_bf16 v[16:19], v[222:225], v[198:201], v[16:19]
	v_mfma_f32_16x16x32_bf16 v[4:7], v[214:217], v[206:209], v[4:7]
	v_mfma_f32_16x16x32_bf16 v[0:3], v[222:225], v[206:209], v[0:3]
	s_barrier
	ds_read_b128 v[158:161], v154
	ds_read_b128 v[162:165], v154 offset:1024
	ds_read_b128 v[166:169], v154 offset:2048
	ds_read_b128 v[170:173], v154 offset:3072
	s_add_u32 s16, s16, s0
	s_addc_u32 s17, s17, s1
	s_mov_b32 m0, s21
	v_lshl_add_u64 v[210:211], s[16:17], 0, v[128:129]
	ds_read_b128 v[174:177], v152 offset:32768
	ds_read_b128 v[178:181], v152 offset:33792
	ds_read_b128 v[182:185], v152 offset:34816
	ds_read_b128 v[186:189], v152 offset:35840
	ds_read_b128 v[190:193], v152 offset:36864
	ds_read_b128 v[198:201], v152 offset:37888
	ds_read_b128 v[202:205], v152 offset:38912
	ds_read_b128 v[206:209], v152 offset:39936
	global_load_lds_dwordx4 v[210:211], off
	v_lshl_add_u64 v[210:211], s[16:17], 0, v[132:133]
	s_mov_b32 m0, s22
	s_nop 0
	global_load_lds_dwordx4 v[210:211], off
	s_waitcnt lgkmcnt(8)
	s_barrier
	s_waitcnt lgkmcnt(0)
	v_mfma_f32_16x16x32_bf16 v[120:123], v[158:161], v[174:177], v[120:123]
	v_mfma_f32_16x16x32_bf16 v[116:119], v[166:169], v[174:177], v[116:119]
	v_mfma_f32_16x16x32_bf16 v[108:111], v[158:161], v[182:185], v[108:111]
	v_mfma_f32_16x16x32_bf16 v[100:103], v[166:169], v[182:185], v[100:103]
	v_mfma_f32_16x16x32_bf16 v[92:95], v[158:161], v[190:193], v[92:95]
	v_mfma_f32_16x16x32_bf16 v[84:87], v[166:169], v[190:193], v[84:87]
	v_mfma_f32_16x16x32_bf16 v[76:79], v[158:161], v[202:205], v[76:79]
	v_mfma_f32_16x16x32_bf16 v[68:71], v[166:169], v[202:205], v[68:71]
	v_mfma_f32_16x16x32_bf16 v[120:123], v[162:165], v[178:181], v[120:123]
	v_mfma_f32_16x16x32_bf16 v[116:119], v[170:173], v[178:181], v[116:119]
	v_mfma_f32_16x16x32_bf16 v[108:111], v[162:165], v[186:189], v[108:111]
	v_mfma_f32_16x16x32_bf16 v[100:103], v[170:173], v[186:189], v[100:103]
	v_mfma_f32_16x16x32_bf16 v[92:95], v[162:165], v[198:201], v[92:95]
	v_mfma_f32_16x16x32_bf16 v[84:87], v[170:173], v[198:201], v[84:87]
	v_mfma_f32_16x16x32_bf16 v[76:79], v[162:165], v[206:209], v[76:79]
	v_mfma_f32_16x16x32_bf16 v[68:71], v[170:173], v[206:209], v[68:71]
	s_barrier
	s_add_i32 s16, s51, s18
	v_lshl_add_u64 v[144:145], v[144:145], 0, s[44:45]
	s_mov_b32 m0, s16
	ds_read_b128 v[210:213], v155
	ds_read_b128 v[214:217], v155 offset:1024
	ds_read_b128 v[218:221], v155 offset:2048
	ds_read_b128 v[222:225], v155 offset:3072
	global_load_lds_dwordx4 v[144:145], off
	v_lshl_add_u64 v[144:145], v[194:195], 0, s[44:45]
	s_add_i32 m0, s16, 0x2000
	s_nop 0
	global_load_lds_dwordx4 v[144:145], off
	s_barrier
; #define PG8_STAGE(bufoff, gbase, voff) do { _Pragma("unroll") for (int _i = 0; _i < 2; ++_i) \
;         __builtin_amdgcn_global_load_lds((const unsigned*)((const char*)(gbase) + (voff)[_i]), (LAS unsigned*)(lds + (bufoff) + ldsw + _i * 8192), 16, 0, 0); } while (0)
; #define PG8_LDA(dst, b, h) do { _Pragma("unroll") for (int m = 0; m < 4; ++m) _Pragma("unroll") for (int k = 0; k < 2; ++k) dst[m][k] = *(const LAS bf16x8*)(lds + PG8_SA(b, h) + aoff + m * 2048 + k * 1024); } while (0)
; #define PG8_MMA(ai, bj, At, Bt) do { __builtin_amdgcn_s_setprio(1); _Pragma("unroll") for (int m = 0; m < 4; ++m) _Pragma("unroll") for (int n = 0; n < 2; ++n) _Pragma("unroll") for (int k = 0; k < 2; ++k) \
;         acc[ai][bj][m][n] = __builtin_amdgcn_mfma_f32_16x16x32_bf16(Bt[n][k], At[m][k], acc[ai][bj][m][n], 0, 0, 0); __builtin_amdgcn_s_setprio(0); } while (0)
; #define PG8_WAIT_V(n) asm volatile("s_waitcnt vmcnt(" #n ")" ::: "memory")
; #define PG8_WAIT_L(n) asm volatile("s_waitcnt lgkmcnt(" #n ")" ::: "memory")
; #define PG8_BAR __builtin_amdgcn_s_barrier()
; #define PG8_SCHED __builtin_amdgcn_sched_barrier(0)
; template <class Epi>
; DEVI void gemm_phase(LAS unsigned char* lds, const bf16_t* gA, const bf16_t* gBt, const int lda, const int ldb, const int K, const StaticOrder S_, const Epi E) {
;     ...
;             PG8_BAR; PG8_WAIT_L(0); PG8_MMA(0, 1, At, B1); PG8_BAR;
;             PG8_LDA(At, 1, 1); PG8_STAGE(PG8_SA(1, 0), a3, voffA);
;             PG8_BAR; PG8_WAIT_L(0); PG8_MMA(1, 0, At, B0); PG8_BAR; PG8_SCHED;
;             PG8_STAGE(PG8_SB(1, 1), b3 + hstepB, voffB);
;             PG8_WAIT_V(6); PG8_BAR; PG8_MMA(1, 1, At, B1); PG8_BAR;
	s_waitcnt lgkmcnt(0)
	v_mfma_f32_16x16x32_bf16 v[124:127], v[210:213], v[174:177], v[124:127]
	v_mfma_f32_16x16x32_bf16 v[112:115], v[218:221], v[174:177], v[112:115]
	v_mfma_f32_16x16x32_bf16 v[104:107], v[210:213], v[182:185], v[104:107]
	v_mfma_f32_16x16x32_bf16 v[96:99], v[218:221], v[182:185], v[96:99]
	v_mfma_f32_16x16x32_bf16 v[88:91], v[210:213], v[190:193], v[88:91]
	v_mfma_f32_16x16x32_bf16 v[80:83], v[218:221], v[190:193], v[80:83]
	v_mfma_f32_16x16x32_bf16 v[72:75], v[210:213], v[202:205], v[72:75]
	v_mfma_f32_16x16x32_bf16 v[64:67], v[218:221], v[202:205], v[64:67]
	v_mfma_f32_16x16x32_bf16 v[124:127], v[214:217], v[178:181], v[124:127]
	v_mfma_f32_16x16x32_bf16 v[112:115], v[222:225], v[178:181], v[112:115]
	v_mfma_f32_16x16x32_bf16 v[104:107], v[214:217], v[186:189], v[104:107]
	v_mfma_f32_16x16x32_bf16 v[96:99], v[222:225], v[186:189], v[96:99]
	v_mfma_f32_16x16x32_bf16 v[88:91], v[214:217], v[198:201], v[88:91]
	v_mfma_f32_16x16x32_bf16 v[80:83], v[222:225], v[198:201], v[80:83]
	v_mfma_f32_16x16x32_bf16 v[72:75], v[214:217], v[206:209], v[72:75]
	v_mfma_f32_16x16x32_bf16 v[64:67], v[222:225], v[206:209], v[64:67]
	s_mov_b32 m0, s23
	v_lshl_add_u64 v[144:145], v[226:227], 0, s[44:45]
	s_barrier
	ds_read_b128 v[174:177], v152 offset:49152
	ds_read_b128 v[178:181], v152 offset:50176
	ds_read_b128 v[182:185], v152 offset:51200
	ds_read_b128 v[186:189], v152 offset:52224
	ds_read_b128 v[190:193], v152 offset:53248
	ds_read_b128 v[198:201], v152 offset:54272
	ds_read_b128 v[202:205], v152 offset:55296
	ds_read_b128 v[206:209], v152 offset:56320
	global_load_lds_dwordx4 v[144:145], off
	v_lshl_add_u64 v[144:145], v[228:229], 0, s[44:45]
	s_mov_b32 m0, s24
	s_nop 0
	global_load_lds_dwordx4 v[144:145], off
	s_barrier
	s_waitcnt lgkmcnt(0)
	v_mfma_f32_16x16x32_bf16 v[60:63], v[158:161], v[174:177], v[60:63]
	v_mfma_f32_16x16x32_bf16 v[56:59], v[166:169], v[174:177], v[56:59]
	v_mfma_f32_16x16x32_bf16 v[44:47], v[158:161], v[182:185], v[44:47]
	v_mfma_f32_16x16x32_bf16 v[40:43], v[166:169], v[182:185], v[40:43]
	v_mfma_f32_16x16x32_bf16 v[28:31], v[158:161], v[190:193], v[28:31]
	v_mfma_f32_16x16x32_bf16 v[24:27], v[166:169], v[190:193], v[24:27]
	v_mfma_f32_16x16x32_bf16 v[12:15], v[158:161], v[202:205], v[12:15]
	v_mfma_f32_16x16x32_bf16 v[8:11], v[166:169], v[202:205], v[8:11]
	v_mfma_f32_16x16x32_bf16 v[60:63], v[162:165], v[178:181], v[60:63]
	v_mfma_f32_16x16x32_bf16 v[56:59], v[170:173], v[178:181], v[56:59]
	v_mfma_f32_16x16x32_bf16 v[44:47], v[162:165], v[186:189], v[44:47]
	v_mfma_f32_16x16x32_bf16 v[40:43], v[170:173], v[186:189], v[40:43]
	v_mfma_f32_16x16x32_bf16 v[28:31], v[162:165], v[198:201], v[28:31]
	v_mfma_f32_16x16x32_bf16 v[24:27], v[170:173], v[198:201], v[24:27]
	v_mfma_f32_16x16x32_bf16 v[12:15], v[162:165], v[206:209], v[12:15]
	v_mfma_f32_16x16x32_bf16 v[8:11], v[170:173], v[206:209], v[8:11]
	s_barrier
	s_add_i32 s16, s31, s18
	v_lshl_add_u64 v[144:145], v[230:231], 0, s[44:45]
	s_mov_b32 m0, s16
	s_nop 0
	global_load_lds_dwordx4 v[144:145], off
	v_lshl_add_u64 v[144:145], v[232:233], 0, s[44:45]
	s_add_i32 m0, s16, 0x2000
	s_nop 0
	global_load_lds_dwordx4 v[144:145], off
	s_waitcnt vmcnt(6)
	s_barrier
	v_mfma_f32_16x16x32_bf16 v[52:55], v[210:213], v[174:177], v[52:55]
	v_mfma_f32_16x16x32_bf16 v[48:51], v[218:221], v[174:177], v[48:51]
	v_mfma_f32_16x16x32_bf16 v[36:39], v[210:213], v[182:185], v[36:39]
	v_mfma_f32_16x16x32_bf16 v[32:35], v[218:221], v[182:185], v[32:35]
	v_mfma_f32_16x16x32_bf16 v[20:23], v[210:213], v[190:193], v[20:23]
	v_mfma_f32_16x16x32_bf16 v[16:19], v[218:221], v[190:193], v[16:19]
	v_mfma_f32_16x16x32_bf16 v[4:7], v[210:213], v[202:205], v[4:7]
	v_mfma_f32_16x16x32_bf16 v[0:3], v[218:221], v[202:205], v[0:3]
	v_mfma_f32_16x16x32_bf16 v[52:55], v[214:217], v[178:181], v[52:55]
	v_mfma_f32_16x16x32_bf16 v[48:51], v[222:225], v[178:181], v[48:51]
	v_mfma_f32_16x16x32_bf16 v[36:39], v[214:217], v[186:189], v[36:39]
	v_mfma_f32_16x16x32_bf16 v[32:35], v[222:225], v[186:189], v[32:35]
	v_mfma_f32_16x16x32_bf16 v[20:23], v[214:217], v[198:201], v[20:23]
	v_mfma_f32_16x16x32_bf16 v[16:19], v[222:225], v[198:201], v[16:19]
	v_mfma_f32_16x16x32_bf16 v[4:7], v[214:217], v[206:209], v[4:7]
	v_mfma_f32_16x16x32_bf16 v[0:3], v[222:225], v[206:209], v[0:3]
	s_add_u32 s14, s14, 0x100
	s_addc_u32 s15, s15, 0
	s_add_u32 s59, s59, 0x100
	s_addc_u32 s60, s60, 0
	s_cmp_ge_i32 s61, s25
	s_mov_b32 s16, s61
	s_barrier
	s_cbranch_scc0 .LBB0_2510

; #define PG8_STAGE(bufoff, gbase, voff) do { _Pragma("unroll") for (int _i = 0; _i < 2; ++_i) \
;         __builtin_amdgcn_global_load_lds((const unsigned*)((const char*)(gbase) + (voff)[_i]), (LAS unsigned*)(lds + (bufoff) + ldsw + _i * 8192), 16, 0, 0); } while (0)
; #define PG8_LDA(dst, b, h) do { _Pragma("unroll") for (int m = 0; m < 4; ++m) _Pragma("unroll") for (int k = 0; k < 2; ++k) dst[m][k] = *(const LAS bf16x8*)(lds + PG8_SA(b, h) + aoff + m * 2048 + k * 1024); } while (0)
; #define PG8_LDB(dst, b, h) do { _Pragma("unroll") for (int n = 0; n < 2; ++n) _Pragma("unroll") for (int k = 0; k < 2; ++k) dst[n][k] = *(const LAS bf16x8*)(lds + PG8_SB(b, h) + boff + n * 2048 + k * 1024); } while (0)
; #define PG8_MMA(ai, bj, At, Bt) do { __builtin_amdgcn_s_setprio(1); _Pragma("unroll") for (int m = 0; m < 4; ++m) _Pragma("unroll") for (int n = 0; n < 2; ++n) _Pragma("unroll") for (int k = 0; k < 2; ++k) \
;         acc[ai][bj][m][n] = __builtin_amdgcn_mfma_f32_16x16x32_bf16(Bt[n][k], At[m][k], acc[ai][bj][m][n], 0, 0, 0); __builtin_amdgcn_s_setprio(0); } while (0)
; #define PG8_WAIT_L(n) asm volatile("s_waitcnt lgkmcnt(" #n ")" ::: "memory")
; #define PG8_BAR __builtin_amdgcn_s_barrier()
; #define PG8_SCHED __builtin_amdgcn_sched_barrier(0)
; template <class Epi>
; DEVI void gemm_phase(LAS unsigned char* lds, const bf16_t* gA, const bf16_t* gBt, const int lda, const int ldb, const int K, const StaticOrder S_, const Epi E) {
;     ...
;             const char* a1 = cA + (size_t)(t + 1) * kstep;
;             const char* a2 = last ? nA : cA + (size_t)(t + 2) * kstep; const char* b2 = last ? nB : cB + (size_t)(t + 2) * kstep;
;             const char* a3 = a2 + kstep; const char* b3 = b2 + kstep;
;             PG8_LDB(B0, 0, 0); PG8_SCHED; PG8_LDA(At, 0, 0); PG8_STAGE(PG8_SA(1, 1), a1 + hstepA, voffA);
;             PG8_WAIT_L(8); PG8_BAR; PG8_WAIT_L(0); PG8_MMA(0, 0, At, B0); PG8_BAR; PG8_SCHED;
;             PG8_LDB(B1, 0, 1); PG8_STAGE(PG8_SB(0, 0), b2, voffB);
;             PG8_BAR; PG8_WAIT_L(0); PG8_MMA(0, 1, At, B1); PG8_BAR;
;             PG8_LDA(At, 0, 1); PG8_STAGE(PG8_SA(0, 0), a2, voffA);
;             PG8_BAR; PG8_WAIT_L(0); PG8_MMA(1, 0, At, B0); PG8_BAR; PG8_SCHED;
.LBB0_2589:
	ds_read_b128 v[128:131], v200
	ds_read_b128 v[132:135], v200 offset:1024
	ds_read_b128 v[136:139], v200 offset:2048
	ds_read_b128 v[140:143], v200 offset:3072
	s_add_i32 s56, s24, 2
	s_add_u32 s26, s4, 0x80
	s_addc_u32 s25, s5, 0
	s_cmp_eq_u32 s43, s24
	s_cselect_b32 s24, s22, s26
	s_cselect_b32 s25, s23, s25
	s_cselect_b32 s27, s7, s55
	s_cselect_b32 s26, s6, s54
	v_lshl_add_u64 v[164:165], s[4:5], 0, v[174:175]
	s_add_i32 m0, s34, 0xc000
	ds_read_b128 v[144:147], v201
	ds_read_b128 v[148:151], v201 offset:1024
	ds_read_b128 v[152:155], v201 offset:2048
	ds_read_b128 v[156:159], v201 offset:3072
	ds_read_b128 v[160:163], v201 offset:4096
	ds_read_b128 v[180:183], v201 offset:5120
	ds_read_b128 v[184:187], v201 offset:6144
	ds_read_b128 v[188:191], v201 offset:7168
	global_load_lds_dwordx4 v[164:165], off
	v_lshl_add_u64 v[164:165], s[4:5], 0, v[176:177]
	s_add_i32 m0, s34, 0xe000
	s_nop 0
	global_load_lds_dwordx4 v[164:165], off
	s_waitcnt lgkmcnt(8)
	s_barrier
	s_waitcnt lgkmcnt(0)
	v_mfma_f32_16x16x32_bf16 v[124:127], v[128:131], v[144:147], v[124:127]
	v_mfma_f32_16x16x32_bf16 v[120:123], v[136:139], v[144:147], v[120:123]
	v_mfma_f32_16x16x32_bf16 v[108:111], v[128:131], v[152:155], v[108:111]
	v_mfma_f32_16x16x32_bf16 v[104:107], v[136:139], v[152:155], v[104:107]
	v_mfma_f32_16x16x32_bf16 v[92:95], v[128:131], v[160:163], v[92:95]
	v_mfma_f32_16x16x32_bf16 v[88:91], v[136:139], v[160:163], v[88:91]
	v_mfma_f32_16x16x32_bf16 v[76:79], v[128:131], v[184:187], v[76:79]
	v_mfma_f32_16x16x32_bf16 v[72:75], v[136:139], v[184:187], v[72:75]
	v_mfma_f32_16x16x32_bf16 v[124:127], v[132:135], v[148:151], v[124:127]
	v_mfma_f32_16x16x32_bf16 v[120:123], v[140:143], v[148:151], v[120:123]
	v_mfma_f32_16x16x32_bf16 v[108:111], v[132:135], v[156:159], v[108:111]
	v_mfma_f32_16x16x32_bf16 v[104:107], v[140:143], v[156:159], v[104:107]
	v_mfma_f32_16x16x32_bf16 v[92:95], v[132:135], v[180:183], v[92:95]
	v_mfma_f32_16x16x32_bf16 v[88:91], v[140:143], v[180:183], v[88:91]
	v_mfma_f32_16x16x32_bf16 v[76:79], v[132:135], v[188:191], v[76:79]
	v_mfma_f32_16x16x32_bf16 v[72:75], v[140:143], v[188:191], v[72:75]
	s_barrier
	s_add_i32 s57, s49, s30
	v_lshl_add_u64 v[164:165], s[26:27], 0, v[168:169]
	s_mov_b32 m0, s57
	ds_read_b128 v[192:195], v202
	ds_read_b128 v[204:207], v202 offset:1024
	ds_read_b128 v[208:211], v202 offset:2048
	ds_read_b128 v[212:215], v202 offset:3072
	global_load_lds_dwordx4 v[164:165], off
	v_lshl_add_u64 v[216:217], s[26:27], 0, v[172:173]
	s_add_i32 m0, s57, 0x2000
	s_nop 0
	global_load_lds_dwordx4 v[216:217], off
	s_barrier
	s_waitcnt lgkmcnt(0)
	v_mfma_f32_16x16x32_bf16 v[116:119], v[192:195], v[144:147], v[116:119]
	v_mfma_f32_16x16x32_bf16 v[112:115], v[208:211], v[144:147], v[112:115]
	v_mfma_f32_16x16x32_bf16 v[100:103], v[192:195], v[152:155], v[100:103]
	v_mfma_f32_16x16x32_bf16 v[96:99], v[208:211], v[152:155], v[96:99]
	v_mfma_f32_16x16x32_bf16 v[84:87], v[192:195], v[160:163], v[84:87]
	v_mfma_f32_16x16x32_bf16 v[80:83], v[208:211], v[160:163], v[80:83]
	v_mfma_f32_16x16x32_bf16 v[68:71], v[192:195], v[184:187], v[68:71]
	v_mfma_f32_16x16x32_bf16 v[64:67], v[208:211], v[184:187], v[64:67]
	v_mfma_f32_16x16x32_bf16 v[116:119], v[204:207], v[148:151], v[116:119]
	v_mfma_f32_16x16x32_bf16 v[112:115], v[212:215], v[148:151], v[112:115]
	v_mfma_f32_16x16x32_bf16 v[100:103], v[204:207], v[156:159], v[100:103]
	v_mfma_f32_16x16x32_bf16 v[96:99], v[212:215], v[156:159], v[96:99]
	v_mfma_f32_16x16x32_bf16 v[84:87], v[204:207], v[180:183], v[84:87]
	v_mfma_f32_16x16x32_bf16 v[80:83], v[212:215], v[180:183], v[80:83]
	v_mfma_f32_16x16x32_bf16 v[68:71], v[204:207], v[188:191], v[68:71]
	v_mfma_f32_16x16x32_bf16 v[64:67], v[212:215], v[188:191], v[64:67]
	s_mov_b32 m0, s34
	v_lshl_add_u64 v[218:219], s[24:25], 0, v[166:167]
	s_barrier
	ds_read_b128 v[144:147], v201 offset:16384
	ds_read_b128 v[148:151], v201 offset:17408
	ds_read_b128 v[152:155], v201 offset:18432
	ds_read_b128 v[156:159], v201 offset:19456
	ds_read_b128 v[160:163], v201 offset:20480
	ds_read_b128 v[180:183], v201 offset:21504
	ds_read_b128 v[184:187], v201 offset:22528
	ds_read_b128 v[188:191], v201 offset:23552
	global_load_lds_dwordx4 v[218:219], off
	v_lshl_add_u64 v[220:221], s[24:25], 0, v[170:171]
	s_mov_b32 m0, s35
	s_nop 0
	global_load_lds_dwordx4 v[220:221], off
	s_barrier
	s_waitcnt lgkmcnt(0)
	v_mfma_f32_16x16x32_bf16 v[60:63], v[128:131], v[144:147], v[60:63]
	v_mfma_f32_16x16x32_bf16 v[56:59], v[136:139], v[144:147], v[56:59]
	v_mfma_f32_16x16x32_bf16 v[44:47], v[128:131], v[152:155], v[44:47]
	v_mfma_f32_16x16x32_bf16 v[40:43], v[136:139], v[152:155], v[40:43]
	v_mfma_f32_16x16x32_bf16 v[28:31], v[128:131], v[160:163], v[28:31]
	v_mfma_f32_16x16x32_bf16 v[24:27], v[136:139], v[160:163], v[24:27]
	v_mfma_f32_16x16x32_bf16 v[12:15], v[128:131], v[184:187], v[12:15]
	v_mfma_f32_16x16x32_bf16 v[8:11], v[136:139], v[184:187], v[8:11]
	v_mfma_f32_16x16x32_bf16 v[60:63], v[132:135], v[148:151], v[60:63]
	v_mfma_f32_16x16x32_bf16 v[56:59], v[140:143], v[148:151], v[56:59]
	v_mfma_f32_16x16x32_bf16 v[44:47], v[132:135], v[156:159], v[44:47]
	v_mfma_f32_16x16x32_bf16 v[40:43], v[140:143], v[156:159], v[40:43]
	v_mfma_f32_16x16x32_bf16 v[28:31], v[132:135], v[180:183], v[28:31]
	v_mfma_f32_16x16x32_bf16 v[24:27], v[140:143], v[180:183], v[24:27]
	v_mfma_f32_16x16x32_bf16 v[12:15], v[132:135], v[188:191], v[12:15]
	v_mfma_f32_16x16x32_bf16 v[8:11], v[140:143], v[188:191], v[8:11]
	s_barrier
; #define PG8_STAGE(bufoff, gbase, voff) do { _Pragma("unroll") for (int _i = 0; _i < 2; ++_i) \
;         __builtin_amdgcn_global_load_lds((const unsigned*)((const char*)(gbase) + (voff)[_i]), (LAS unsigned*)(lds + (bufoff) + ldsw + _i * 8192), 16, 0, 0); } while (0)
; #define PG8_LDA(dst, b, h) do { _Pragma("unroll") for (int m = 0; m < 4; ++m) _Pragma("unroll") for (int k = 0; k < 2; ++k) dst[m][k] = *(const LAS bf16x8*)(lds + PG8_SA(b, h) + aoff + m * 2048 + k * 1024); } while (0)
; #define PG8_LDB(dst, b, h) do { _Pragma("unroll") for (int n = 0; n < 2; ++n) _Pragma("unroll") for (int k = 0; k < 2; ++k) dst[n][k] = *(const LAS bf16x8*)(lds + PG8_SB(b, h) + boff + n * 2048 + k * 1024); } while (0)
; #define PG8_MMA(ai, bj, At, Bt) do { __builtin_amdgcn_s_setprio(1); _Pragma("unroll") for (int m = 0; m < 4; ++m) _Pragma("unroll") for (int n = 0; n < 2; ++n) _Pragma("unroll") for (int k = 0; k < 2; ++k) \
;         acc[ai][bj][m][n] = __builtin_amdgcn_mfma_f32_16x16x32_bf16(Bt[n][k], At[m][k], acc[ai][bj][m][n], 0, 0, 0); __builtin_amdgcn_s_setprio(0); } while (0)
; #define PG8_WAIT_V(n) asm volatile("s_waitcnt vmcnt(" #n ")" ::: "memory")
; #define PG8_WAIT_L(n) asm volatile("s_waitcnt lgkmcnt(" #n ")" ::: "memory")
; #define PG8_BAR __builtin_amdgcn_s_barrier()
; #define PG8_SCHED __builtin_amdgcn_sched_barrier(0)
; template <class Epi>
; DEVI void gemm_phase(LAS unsigned char* lds, const bf16_t* gA, const bf16_t* gBt, const int lda, const int ldb, const int K, const StaticOrder S_, const Epi E) {
;     ...
;             PG8_STAGE(PG8_SB(0, 1), b2 + hstepB, voffB);
;             PG8_WAIT_V(6); PG8_BAR; PG8_MMA(1, 1, At, B1); PG8_BAR;
;             PG8_LDB(B0, 1, 0); PG8_SCHED; PG8_LDA(At, 1, 0); PG8_STAGE(PG8_SA(0, 1), a2 + hstepA, voffA);
;             PG8_WAIT_L(8); PG8_BAR; PG8_WAIT_L(0); PG8_MMA(0, 0, At, B0); PG8_BAR; PG8_SCHED;
;             PG8_LDB(B1, 1, 1); PG8_STAGE(PG8_SB(1, 0), b3, voffB);
	s_add_u32 s26, s26, s10
	s_addc_u32 s27, s27, s11
	s_add_i32 s57, s50, s30
	v_lshl_add_u64 v[222:223], s[26:27], 0, v[168:169]
	s_mov_b32 m0, s57
	v_lshl_add_u64 v[224:225], s[26:27], 0, v[172:173]
	global_load_lds_dwordx4 v[222:223], off
	s_add_i32 m0, s57, 0x2000
	s_nop 0
	global_load_lds_dwordx4 v[224:225], off
	s_waitcnt vmcnt(6)
	s_barrier
	v_mfma_f32_16x16x32_bf16 v[52:55], v[192:195], v[144:147], v[52:55]
	v_mfma_f32_16x16x32_bf16 v[48:51], v[208:211], v[144:147], v[48:51]
	v_mfma_f32_16x16x32_bf16 v[36:39], v[192:195], v[152:155], v[36:39]
	v_mfma_f32_16x16x32_bf16 v[32:35], v[208:211], v[152:155], v[32:35]
	v_mfma_f32_16x16x32_bf16 v[20:23], v[192:195], v[160:163], v[20:23]
	v_mfma_f32_16x16x32_bf16 v[16:19], v[208:211], v[160:163], v[16:19]
	v_mfma_f32_16x16x32_bf16 v[4:7], v[192:195], v[184:187], v[4:7]
	v_mfma_f32_16x16x32_bf16 v[0:3], v[208:211], v[184:187], v[0:3]
	v_mfma_f32_16x16x32_bf16 v[52:55], v[204:207], v[148:151], v[52:55]
	v_mfma_f32_16x16x32_bf16 v[48:51], v[212:215], v[148:151], v[48:51]
	v_mfma_f32_16x16x32_bf16 v[36:39], v[204:207], v[156:159], v[36:39]
	v_mfma_f32_16x16x32_bf16 v[32:35], v[212:215], v[156:159], v[32:35]
	v_mfma_f32_16x16x32_bf16 v[20:23], v[204:207], v[180:183], v[20:23]
	v_mfma_f32_16x16x32_bf16 v[16:19], v[212:215], v[180:183], v[16:19]
	v_mfma_f32_16x16x32_bf16 v[4:7], v[204:207], v[188:191], v[4:7]
	v_mfma_f32_16x16x32_bf16 v[0:3], v[212:215], v[188:191], v[0:3]
	s_add_i32 s26, 0, 0x18000
	v_add_u32_e32 v140, s26, v196
	s_barrier
	ds_read_b128 v[128:131], v140
	ds_read_b128 v[132:135], v140 offset:1024
	ds_read_b128 v[136:139], v140 offset:2048
	ds_read_b128 v[140:143], v140 offset:3072
	s_add_u32 s24, s24, s2
	s_addc_u32 s25, s25, s3
	s_mov_b32 m0, s36
	v_lshl_add_u64 v[192:193], s[24:25], 0, v[166:167]
	ds_read_b128 v[144:147], v201 offset:32768
	ds_read_b128 v[148:151], v201 offset:33792
	ds_read_b128 v[152:155], v201 offset:34816
	ds_read_b128 v[156:159], v201 offset:35840
	ds_read_b128 v[160:163], v201 offset:36864
	ds_read_b128 v[180:183], v201 offset:37888
	ds_read_b128 v[184:187], v201 offset:38912
	ds_read_b128 v[188:191], v201 offset:39936
	global_load_lds_dwordx4 v[192:193], off
	v_lshl_add_u64 v[192:193], s[24:25], 0, v[170:171]
	s_mov_b32 m0, s37
	s_nop 0
	global_load_lds_dwordx4 v[192:193], off
	s_waitcnt lgkmcnt(8)
	s_barrier
	s_waitcnt lgkmcnt(0)
	v_mfma_f32_16x16x32_bf16 v[124:127], v[128:131], v[144:147], v[124:127]
	v_mfma_f32_16x16x32_bf16 v[120:123], v[136:139], v[144:147], v[120:123]
	v_mfma_f32_16x16x32_bf16 v[108:111], v[128:131], v[152:155], v[108:111]
	v_mfma_f32_16x16x32_bf16 v[104:107], v[136:139], v[152:155], v[104:107]
	v_mfma_f32_16x16x32_bf16 v[92:95], v[128:131], v[160:163], v[92:95]
	v_mfma_f32_16x16x32_bf16 v[88:91], v[136:139], v[160:163], v[88:91]
	v_mfma_f32_16x16x32_bf16 v[76:79], v[128:131], v[184:187], v[76:79]
	v_mfma_f32_16x16x32_bf16 v[72:75], v[136:139], v[184:187], v[72:75]
	v_mfma_f32_16x16x32_bf16 v[124:127], v[132:135], v[148:151], v[124:127]
	v_mfma_f32_16x16x32_bf16 v[120:123], v[140:143], v[148:151], v[120:123]
	v_mfma_f32_16x16x32_bf16 v[108:111], v[132:135], v[156:159], v[108:111]
	v_mfma_f32_16x16x32_bf16 v[104:107], v[140:143], v[156:159], v[104:107]
	v_mfma_f32_16x16x32_bf16 v[92:95], v[132:135], v[180:183], v[92:95]
	v_mfma_f32_16x16x32_bf16 v[88:91], v[140:143], v[180:183], v[88:91]
	v_mfma_f32_16x16x32_bf16 v[76:79], v[132:135], v[188:191], v[76:79]
	v_mfma_f32_16x16x32_bf16 v[72:75], v[140:143], v[188:191], v[72:75]
	s_barrier
	s_add_i32 s24, 0, 0x1c000
	s_add_i32 s25, s26, s30
	v_add_u32_e32 v212, s24, v196
	v_lshl_add_u64 v[164:165], v[164:165], 0, s[16:17]
	s_mov_b32 m0, s25
	ds_read_b128 v[192:195], v212
	ds_read_b128 v[204:207], v212 offset:1024
	ds_read_b128 v[208:211], v212 offset:2048
	ds_read_b128 v[212:215], v212 offset:3072
	global_load_lds_dwordx4 v[164:165], off
	v_lshl_add_u64 v[164:165], v[216:217], 0, s[16:17]
	s_add_i32 m0, s25, 0x2000
	s_nop 0
	global_load_lds_dwordx4 v[164:165], off
	s_barrier
; #define PG8_STAGE(bufoff, gbase, voff) do { _Pragma("unroll") for (int _i = 0; _i < 2; ++_i) \
;         __builtin_amdgcn_global_load_lds((const unsigned*)((const char*)(gbase) + (voff)[_i]), (LAS unsigned*)(lds + (bufoff) + ldsw + _i * 8192), 16, 0, 0); } while (0)
; #define PG8_LDA(dst, b, h) do { _Pragma("unroll") for (int m = 0; m < 4; ++m) _Pragma("unroll") for (int k = 0; k < 2; ++k) dst[m][k] = *(const LAS bf16x8*)(lds + PG8_SA(b, h) + aoff + m * 2048 + k * 1024); } while (0)
; #define PG8_MMA(ai, bj, At, Bt) do { __builtin_amdgcn_s_setprio(1); _Pragma("unroll") for (int m = 0; m < 4; ++m) _Pragma("unroll") for (int n = 0; n < 2; ++n) _Pragma("unroll") for (int k = 0; k < 2; ++k) \
;         acc[ai][bj][m][n] = __builtin_amdgcn_mfma_f32_16x16x32_bf16(Bt[n][k], At[m][k], acc[ai][bj][m][n], 0, 0, 0); __builtin_amdgcn_s_setprio(0); } while (0)
; #define PG8_WAIT_V(n) asm volatile("s_waitcnt vmcnt(" #n ")" ::: "memory")
; #define PG8_WAIT_L(n) asm volatile("s_waitcnt lgkmcnt(" #n ")" ::: "memory")
; #define PG8_BAR __builtin_amdgcn_s_barrier()
; #define PG8_SCHED __builtin_amdgcn_sched_barrier(0)
; template <class Epi>
; DEVI void gemm_phase(LAS unsigned char* lds, const bf16_t* gA, const bf16_t* gBt, const int lda, const int ldb, const int K, const StaticOrder S_, const Epi E) {
;     ...
;             PG8_BAR; PG8_WAIT_L(0); PG8_MMA(0, 1, At, B1); PG8_BAR;
;             PG8_LDA(At, 1, 1); PG8_STAGE(PG8_SA(1, 0), a3, voffA);
;             PG8_BAR; PG8_WAIT_L(0); PG8_MMA(1, 0, At, B0); PG8_BAR; PG8_SCHED;
;             PG8_STAGE(PG8_SB(1, 1), b3 + hstepB, voffB);
;             PG8_WAIT_V(6); PG8_BAR; PG8_MMA(1, 1, At, B1); PG8_BAR;
	s_waitcnt lgkmcnt(0)
	v_mfma_f32_16x16x32_bf16 v[116:119], v[192:195], v[144:147], v[116:119]
	v_mfma_f32_16x16x32_bf16 v[112:115], v[208:211], v[144:147], v[112:115]
	v_mfma_f32_16x16x32_bf16 v[100:103], v[192:195], v[152:155], v[100:103]
	v_mfma_f32_16x16x32_bf16 v[96:99], v[208:211], v[152:155], v[96:99]
	v_mfma_f32_16x16x32_bf16 v[84:87], v[192:195], v[160:163], v[84:87]
	v_mfma_f32_16x16x32_bf16 v[80:83], v[208:211], v[160:163], v[80:83]
	v_mfma_f32_16x16x32_bf16 v[68:71], v[192:195], v[184:187], v[68:71]
	v_mfma_f32_16x16x32_bf16 v[64:67], v[208:211], v[184:187], v[64:67]
	v_mfma_f32_16x16x32_bf16 v[116:119], v[204:207], v[148:151], v[116:119]
	v_mfma_f32_16x16x32_bf16 v[112:115], v[212:215], v[148:151], v[112:115]
	v_mfma_f32_16x16x32_bf16 v[100:103], v[204:207], v[156:159], v[100:103]
	v_mfma_f32_16x16x32_bf16 v[96:99], v[212:215], v[156:159], v[96:99]
	v_mfma_f32_16x16x32_bf16 v[84:87], v[204:207], v[180:183], v[84:87]
	v_mfma_f32_16x16x32_bf16 v[80:83], v[212:215], v[180:183], v[80:83]
	v_mfma_f32_16x16x32_bf16 v[68:71], v[204:207], v[188:191], v[68:71]
	v_mfma_f32_16x16x32_bf16 v[64:67], v[212:215], v[188:191], v[64:67]
	s_mov_b32 m0, s39
	v_lshl_add_u64 v[164:165], v[218:219], 0, s[16:17]
	s_barrier
	ds_read_b128 v[144:147], v201 offset:49152
	ds_read_b128 v[148:151], v201 offset:50176
	ds_read_b128 v[152:155], v201 offset:51200
	ds_read_b128 v[156:159], v201 offset:52224
	ds_read_b128 v[160:163], v201 offset:53248
	ds_read_b128 v[180:183], v201 offset:54272
	ds_read_b128 v[184:187], v201 offset:55296
	ds_read_b128 v[188:191], v201 offset:56320
	global_load_lds_dwordx4 v[164:165], off
	v_lshl_add_u64 v[164:165], v[220:221], 0, s[16:17]
	s_mov_b32 m0, s40
	s_nop 0
	global_load_lds_dwordx4 v[164:165], off
	s_barrier
	s_waitcnt lgkmcnt(0)
	v_mfma_f32_16x16x32_bf16 v[60:63], v[128:131], v[144:147], v[60:63]
	v_mfma_f32_16x16x32_bf16 v[56:59], v[136:139], v[144:147], v[56:59]
	v_mfma_f32_16x16x32_bf16 v[44:47], v[128:131], v[152:155], v[44:47]
	v_mfma_f32_16x16x32_bf16 v[40:43], v[136:139], v[152:155], v[40:43]
	v_mfma_f32_16x16x32_bf16 v[28:31], v[128:131], v[160:163], v[28:31]
	v_mfma_f32_16x16x32_bf16 v[24:27], v[136:139], v[160:163], v[24:27]
	v_mfma_f32_16x16x32_bf16 v[12:15], v[128:131], v[184:187], v[12:15]
	v_mfma_f32_16x16x32_bf16 v[8:11], v[136:139], v[184:187], v[8:11]
	v_mfma_f32_16x16x32_bf16 v[60:63], v[132:135], v[148:151], v[60:63]
	v_mfma_f32_16x16x32_bf16 v[56:59], v[140:143], v[148:151], v[56:59]
	v_mfma_f32_16x16x32_bf16 v[44:47], v[132:135], v[156:159], v[44:47]
	v_mfma_f32_16x16x32_bf16 v[40:43], v[140:143], v[156:159], v[40:43]
	v_mfma_f32_16x16x32_bf16 v[28:31], v[132:135], v[180:183], v[28:31]
	v_mfma_f32_16x16x32_bf16 v[24:27], v[140:143], v[180:183], v[24:27]
	v_mfma_f32_16x16x32_bf16 v[12:15], v[132:135], v[188:191], v[12:15]
	v_mfma_f32_16x16x32_bf16 v[8:11], v[140:143], v[188:191], v[8:11]
	s_barrier
	s_add_i32 s24, s24, s30
	v_lshl_add_u64 v[128:129], v[222:223], 0, s[16:17]
	s_mov_b32 m0, s24
	s_nop 0
	global_load_lds_dwordx4 v[128:129], off
	v_lshl_add_u64 v[128:129], v[224:225], 0, s[16:17]
	s_add_i32 m0, s24, 0x2000
	s_nop 0
	global_load_lds_dwordx4 v[128:129], off
	s_waitcnt vmcnt(6)
	s_barrier
	v_mfma_f32_16x16x32_bf16 v[52:55], v[192:195], v[144:147], v[52:55]
	v_mfma_f32_16x16x32_bf16 v[48:51], v[208:211], v[144:147], v[48:51]
	v_mfma_f32_16x16x32_bf16 v[36:39], v[192:195], v[152:155], v[36:39]
	v_mfma_f32_16x16x32_bf16 v[32:35], v[208:211], v[152:155], v[32:35]
	v_mfma_f32_16x16x32_bf16 v[20:23], v[192:195], v[160:163], v[20:23]
	v_mfma_f32_16x16x32_bf16 v[16:19], v[208:211], v[160:163], v[16:19]
	v_mfma_f32_16x16x32_bf16 v[4:7], v[192:195], v[184:187], v[4:7]
	v_mfma_f32_16x16x32_bf16 v[0:3], v[208:211], v[184:187], v[0:3]
	v_mfma_f32_16x16x32_bf16 v[52:55], v[204:207], v[148:151], v[52:55]
	v_mfma_f32_16x16x32_bf16 v[48:51], v[212:215], v[148:151], v[48:51]
	v_mfma_f32_16x16x32_bf16 v[36:39], v[204:207], v[156:159], v[36:39]
	v_mfma_f32_16x16x32_bf16 v[32:35], v[212:215], v[156:159], v[32:35]
	v_mfma_f32_16x16x32_bf16 v[20:23], v[204:207], v[180:183], v[20:23]
	v_mfma_f32_16x16x32_bf16 v[16:19], v[212:215], v[180:183], v[16:19]
	v_mfma_f32_16x16x32_bf16 v[4:7], v[204:207], v[188:191], v[4:7]
	v_mfma_f32_16x16x32_bf16 v[0:3], v[212:215], v[188:191], v[0:3]
	s_add_u32 s4, s4, 0x100
	s_addc_u32 s5, s5, 0
	s_add_u32 s54, s54, 0x100
	s_addc_u32 s55, s55, 0
	s_cmp_ge_i32 s56, s41
	s_mov_b32 s24, s56
	s_barrier
	s_cbranch_scc0 .LBB0_2589
	v_readlane_b32 s56, v241, 26
	v_readlane_b32 s58, v241, 28
	v_readlane_b32 s57, v241, 27
	v_readlane_b32 s59, v241, 29
